# GEMM K-loops: loop counter/pointer updates and exit test moved in front of the loop-back barrier (back-edge rotation)
# speedup vs baseline: 1.0016x; 1.0016x over previous
; #define PG8_STAGE(bufoff, gbase, voff) do { _Pragma("unroll") for (int _i = 0; _i < 2; ++_i) \
;         __builtin_amdgcn_global_load_lds((const unsigned*)((const char*)(gbase) + (voff)[_i]), (PG8_LAS unsigned*)(lds + (bufoff) + ldsw + _i * 8192), 16, 0, 0); } while (0)
; #define PG8_LDA(dst, b, h) do { _Pragma("unroll") for (int m = 0; m < 4; ++m) _Pragma("unroll") for (int k = 0; k < 2; ++k) dst[m][k] = *(const PG8_LAS bf16x8*)(lds + PG8_SA(b, h) + aoff + m * 2048 + k * 1024); } while (0)
; #define PG8_LDB(dst, b, h) do { _Pragma("unroll") for (int n = 0; n < 2; ++n) _Pragma("unroll") for (int k = 0; k < 2; ++k) dst[n][k] = *(const PG8_LAS bf16x8*)(lds + PG8_SB(b, h) + boff + n * 2048 + k * 1024); } while (0)
; #define PG8_MMA(ai, bj, At, Bt) do { __builtin_amdgcn_s_setprio(1); _Pragma("unroll") for (int m = 0; m < 4; ++m) _Pragma("unroll") for (int n = 0; n < 2; ++n) _Pragma("unroll") for (int k = 0; k < 2; ++k) \
;         acc[ai][bj][m][n] = __builtin_amdgcn_mfma_f32_16x16x32_bf16(Bt[n][k], At[m][k], acc[ai][bj][m][n], 0, 0, 0); __builtin_amdgcn_s_setprio(0); } while (0)
; #define PG8_WAIT_V(n) asm volatile("s_waitcnt vmcnt(" #n ")" ::: "memory")
; #define PG8_WAIT_L(n) asm volatile("s_waitcnt lgkmcnt(" #n ")" ::: "memory")
; #define PG8_BAR __builtin_amdgcn_s_barrier()
; #define PG8_SCHED __builtin_amdgcn_sched_barrier(0)
; template <class Epi, class Sched, bool ALIGN_EPI = false, bool SP2 = false>
; __device__ __forceinline__ void gemm_phase(PG8_LAS unsigned char* lds, const Gemm g, const Sched& S, const Epi& E) {
;     ...
;             if constexpr (SP2) {
;             PG8_LDB(B0, 0, 0); PG8_LDB(B1, 0, 1); PG8_SCHED; PG8_LDA(At, 0, 0); PG8_STAGE(PG8_SA(1, 1), a1 + hstep, voffA);
;             PG8_WAIT_V(8); PG8_WAIT_L(0); PG8_BAR; PG8_MMA(0, 0, At, B0); PG8_MMA(0, 1, At, B1); PG8_BAR; PG8_SCHED;
;             PG8_LDA(At, 0, 1); PG8_STAGE(PG8_SB(0, 0), b2, voffB); PG8_STAGE(PG8_SB(0, 1), b2 + hstep, voffB); PG8_STAGE(PG8_SA(0, 0), a2, voffA);
;             PG8_WAIT_V(8); PG8_WAIT_L(0); PG8_BAR; PG8_MMA(1, 0, At, B0); PG8_MMA(1, 1, At, B1); PG8_BAR; PG8_SCHED;
.LBB0_188:
	ds_read_b128 v[144:147], v154
	ds_read_b128 v[158:161], v154 offset:1024
	ds_read_b128 v[162:165], v154 offset:2048
	ds_read_b128 v[166:169], v154 offset:3072
	ds_read_b128 v[170:173], v155
	ds_read_b128 v[174:177], v155 offset:1024
	ds_read_b128 v[178:181], v155 offset:2048
	ds_read_b128 v[186:189], v155 offset:3072
	s_add_u32 s44, s36, 0xfffc0080
	s_addc_u32 s45, s37, -1
	s_cmp_eq_u32 s91, 12
	s_cselect_b32 s47, s27, s45
	s_cselect_b32 s46, s87, s44
	s_cselect_b32 s45, s25, s90
	s_cselect_b32 s44, s88, s89
	v_lshl_add_u64 v[182:183], s[36:37], 0, v[136:137]
	s_add_i32 m0, s69, 0xc000
	ds_read_b128 v[190:193], v156
	ds_read_b128 v[194:197], v156 offset:1024
	ds_read_b128 v[198:201], v156 offset:2048
	ds_read_b128 v[202:205], v156 offset:3072
	ds_read_b128 v[206:209], v156 offset:4096
	ds_read_b128 v[210:213], v156 offset:5120
	ds_read_b128 v[214:217], v156 offset:6144
	ds_read_b128 v[218:221], v156 offset:7168
	global_load_lds_dwordx4 v[182:183], off
	v_lshl_add_u64 v[182:183], s[36:37], 0, v[138:139]
	s_add_i32 m0, s69, 0xe000
	s_nop 0
	global_load_lds_dwordx4 v[182:183], off
	s_waitcnt vmcnt(8)
	s_waitcnt lgkmcnt(0)
	s_barrier
	s_setprio 1
	s_waitcnt lgkmcnt(0)
	v_mfma_f32_16x16x32_bf16 v[124:127], v[144:147], v[190:193], v[124:127]
	v_mfma_f32_16x16x32_bf16 v[120:123], v[162:165], v[190:193], v[120:123]
	v_mfma_f32_16x16x32_bf16 v[108:111], v[144:147], v[198:201], v[108:111]
	v_mfma_f32_16x16x32_bf16 v[104:107], v[162:165], v[198:201], v[104:107]
	v_mfma_f32_16x16x32_bf16 v[92:95], v[144:147], v[206:209], v[92:95]
	v_mfma_f32_16x16x32_bf16 v[88:91], v[162:165], v[206:209], v[88:91]
	v_mfma_f32_16x16x32_bf16 v[76:79], v[144:147], v[214:217], v[76:79]
	v_mfma_f32_16x16x32_bf16 v[72:75], v[162:165], v[214:217], v[72:75]
	v_mfma_f32_16x16x32_bf16 v[124:127], v[158:161], v[194:197], v[124:127]
	v_mfma_f32_16x16x32_bf16 v[120:123], v[166:169], v[194:197], v[120:123]
	v_mfma_f32_16x16x32_bf16 v[108:111], v[158:161], v[202:205], v[108:111]
	v_mfma_f32_16x16x32_bf16 v[104:107], v[166:169], v[202:205], v[104:107]
	v_mfma_f32_16x16x32_bf16 v[92:95], v[158:161], v[210:213], v[92:95]
	v_mfma_f32_16x16x32_bf16 v[88:91], v[166:169], v[210:213], v[88:91]
	v_mfma_f32_16x16x32_bf16 v[76:79], v[158:161], v[218:221], v[76:79]
	v_mfma_f32_16x16x32_bf16 v[72:75], v[166:169], v[218:221], v[72:75]
	s_setprio 0
	s_setprio 1
	v_mfma_f32_16x16x32_bf16 v[116:119], v[170:173], v[190:193], v[116:119]
	v_mfma_f32_16x16x32_bf16 v[112:115], v[178:181], v[190:193], v[112:115]
	v_mfma_f32_16x16x32_bf16 v[100:103], v[170:173], v[198:201], v[100:103]
	v_mfma_f32_16x16x32_bf16 v[96:99], v[178:181], v[198:201], v[96:99]
	v_mfma_f32_16x16x32_bf16 v[84:87], v[170:173], v[206:209], v[84:87]
	v_mfma_f32_16x16x32_bf16 v[80:83], v[178:181], v[206:209], v[80:83]
	v_mfma_f32_16x16x32_bf16 v[68:71], v[170:173], v[214:217], v[68:71]
	v_mfma_f32_16x16x32_bf16 v[64:67], v[178:181], v[214:217], v[64:67]
	v_mfma_f32_16x16x32_bf16 v[116:119], v[174:177], v[194:197], v[116:119]
	v_mfma_f32_16x16x32_bf16 v[112:115], v[186:189], v[194:197], v[112:115]
	v_mfma_f32_16x16x32_bf16 v[100:103], v[174:177], v[202:205], v[100:103]
	v_mfma_f32_16x16x32_bf16 v[96:99], v[186:189], v[202:205], v[96:99]
	v_mfma_f32_16x16x32_bf16 v[84:87], v[174:177], v[210:213], v[84:87]
	v_mfma_f32_16x16x32_bf16 v[80:83], v[186:189], v[210:213], v[80:83]
	v_mfma_f32_16x16x32_bf16 v[68:71], v[174:177], v[218:221], v[68:71]
	v_mfma_f32_16x16x32_bf16 v[64:67], v[186:189], v[218:221], v[64:67]
	s_setprio 0
	s_barrier
	s_add_i32 s92, s82, s50
	v_lshl_add_u64 v[182:183], s[44:45], 0, v[132:133]
	s_mov_b32 m0, s92
	ds_read_b128 v[190:193], v156 offset:16384
	ds_read_b128 v[194:197], v156 offset:17408
	ds_read_b128 v[198:201], v156 offset:18432
	ds_read_b128 v[202:205], v156 offset:19456
	ds_read_b128 v[206:209], v156 offset:20480
	ds_read_b128 v[210:213], v156 offset:21504
	ds_read_b128 v[214:217], v156 offset:22528
	ds_read_b128 v[218:221], v156 offset:23552
	global_load_lds_dwordx4 v[182:183], off
	s_add_i32 m0, s92, 0x2000
	s_add_u32 s92, s44, 0x40000
	v_lshl_add_u64 v[222:223], s[44:45], 0, v[128:129]
	s_addc_u32 s93, s45, 0
	s_add_i32 s94, s83, s50
	global_load_lds_dwordx4 v[222:223], off
	v_lshl_add_u64 v[224:225], s[92:93], 0, v[132:133]
	s_mov_b32 m0, s94
	v_lshl_add_u64 v[226:227], s[46:47], 0, v[130:131]
	global_load_lds_dwordx4 v[224:225], off
	v_lshl_add_u64 v[224:225], s[92:93], 0, v[128:129]
	s_add_i32 m0, s94, 0x2000
	s_nop 0
	global_load_lds_dwordx4 v[224:225], off
	v_lshl_add_u64 v[224:225], s[46:47], 0, v[134:135]
	s_mov_b32 m0, s69
	s_nop 0
	global_load_lds_dwordx4 v[224:225], off
	s_mov_b32 m0, s70
	s_nop 0
	global_load_lds_dwordx4 v[226:227], off
	s_waitcnt vmcnt(8)
	s_waitcnt lgkmcnt(0)
	s_barrier
; #define PG8_STAGE(bufoff, gbase, voff) do { _Pragma("unroll") for (int _i = 0; _i < 2; ++_i) \
;         __builtin_amdgcn_global_load_lds((const unsigned*)((const char*)(gbase) + (voff)[_i]), (PG8_LAS unsigned*)(lds + (bufoff) + ldsw + _i * 8192), 16, 0, 0); } while (0)
; #define PG8_LDA(dst, b, h) do { _Pragma("unroll") for (int m = 0; m < 4; ++m) _Pragma("unroll") for (int k = 0; k < 2; ++k) dst[m][k] = *(const PG8_LAS bf16x8*)(lds + PG8_SA(b, h) + aoff + m * 2048 + k * 1024); } while (0)
; #define PG8_LDB(dst, b, h) do { _Pragma("unroll") for (int n = 0; n < 2; ++n) _Pragma("unroll") for (int k = 0; k < 2; ++k) dst[n][k] = *(const PG8_LAS bf16x8*)(lds + PG8_SB(b, h) + boff + n * 2048 + k * 1024); } while (0)
; #define PG8_MMA(ai, bj, At, Bt) do { __builtin_amdgcn_s_setprio(1); _Pragma("unroll") for (int m = 0; m < 4; ++m) _Pragma("unroll") for (int n = 0; n < 2; ++n) _Pragma("unroll") for (int k = 0; k < 2; ++k) \
;         acc[ai][bj][m][n] = __builtin_amdgcn_mfma_f32_16x16x32_bf16(Bt[n][k], At[m][k], acc[ai][bj][m][n], 0, 0, 0); __builtin_amdgcn_s_setprio(0); } while (0)
; #define PG8_WAIT_V(n) asm volatile("s_waitcnt vmcnt(" #n ")" ::: "memory")
; #define PG8_WAIT_L(n) asm volatile("s_waitcnt lgkmcnt(" #n ")" ::: "memory")
; #define PG8_BAR __builtin_amdgcn_s_barrier()
; #define PG8_SCHED __builtin_amdgcn_sched_barrier(0)
; template <class Epi, class Sched, bool ALIGN_EPI = false, bool SP2 = false>
; __device__ __forceinline__ void gemm_phase(PG8_LAS unsigned char* lds, const Gemm g, const Sched& S, const Epi& E) {
;     ...
;             PG8_WAIT_V(8); PG8_WAIT_L(0); PG8_BAR; PG8_MMA(1, 0, At, B0); PG8_MMA(1, 1, At, B1); PG8_BAR; PG8_SCHED;
;             PG8_LDB(B0, 1, 0); PG8_LDB(B1, 1, 1); PG8_SCHED; PG8_LDA(At, 1, 0); PG8_STAGE(PG8_SA(0, 1), a2 + hstep, voffA);
;             PG8_WAIT_V(8); PG8_WAIT_L(0); PG8_BAR; PG8_MMA(0, 0, At, B0); PG8_MMA(0, 1, At, B1); PG8_BAR; PG8_SCHED;
	s_setprio 1
	s_waitcnt lgkmcnt(0)
	v_mfma_f32_16x16x32_bf16 v[60:63], v[144:147], v[190:193], v[60:63]
	v_mfma_f32_16x16x32_bf16 v[56:59], v[162:165], v[190:193], v[56:59]
	v_mfma_f32_16x16x32_bf16 v[44:47], v[144:147], v[198:201], v[44:47]
	v_mfma_f32_16x16x32_bf16 v[40:43], v[162:165], v[198:201], v[40:43]
	v_mfma_f32_16x16x32_bf16 v[28:31], v[144:147], v[206:209], v[28:31]
	v_mfma_f32_16x16x32_bf16 v[24:27], v[162:165], v[206:209], v[24:27]
	v_mfma_f32_16x16x32_bf16 v[12:15], v[144:147], v[214:217], v[12:15]
	v_mfma_f32_16x16x32_bf16 v[8:11], v[162:165], v[214:217], v[8:11]
	v_mfma_f32_16x16x32_bf16 v[60:63], v[158:161], v[194:197], v[60:63]
	v_mfma_f32_16x16x32_bf16 v[56:59], v[166:169], v[194:197], v[56:59]
	v_mfma_f32_16x16x32_bf16 v[44:47], v[158:161], v[202:205], v[44:47]
	v_mfma_f32_16x16x32_bf16 v[40:43], v[166:169], v[202:205], v[40:43]
	v_mfma_f32_16x16x32_bf16 v[28:31], v[158:161], v[210:213], v[28:31]
	v_mfma_f32_16x16x32_bf16 v[24:27], v[166:169], v[210:213], v[24:27]
	v_mfma_f32_16x16x32_bf16 v[12:15], v[158:161], v[218:221], v[12:15]
	v_mfma_f32_16x16x32_bf16 v[8:11], v[166:169], v[218:221], v[8:11]
	s_setprio 0
	s_setprio 1
	v_mfma_f32_16x16x32_bf16 v[52:55], v[170:173], v[190:193], v[52:55]
	v_mfma_f32_16x16x32_bf16 v[48:51], v[178:181], v[190:193], v[48:51]
	v_mfma_f32_16x16x32_bf16 v[36:39], v[170:173], v[198:201], v[36:39]
	v_mfma_f32_16x16x32_bf16 v[32:35], v[178:181], v[198:201], v[32:35]
	v_mfma_f32_16x16x32_bf16 v[20:23], v[170:173], v[206:209], v[20:23]
	v_mfma_f32_16x16x32_bf16 v[16:19], v[178:181], v[206:209], v[16:19]
	v_mfma_f32_16x16x32_bf16 v[4:7], v[170:173], v[214:217], v[4:7]
	v_mfma_f32_16x16x32_bf16 v[0:3], v[178:181], v[214:217], v[0:3]
	v_mfma_f32_16x16x32_bf16 v[52:55], v[174:177], v[194:197], v[52:55]
	v_mfma_f32_16x16x32_bf16 v[48:51], v[186:189], v[194:197], v[48:51]
	v_mfma_f32_16x16x32_bf16 v[36:39], v[174:177], v[202:205], v[36:39]
	v_mfma_f32_16x16x32_bf16 v[32:35], v[186:189], v[202:205], v[32:35]
	v_mfma_f32_16x16x32_bf16 v[20:23], v[174:177], v[210:213], v[20:23]
	v_mfma_f32_16x16x32_bf16 v[16:19], v[186:189], v[210:213], v[16:19]
	v_mfma_f32_16x16x32_bf16 v[4:7], v[174:177], v[218:221], v[4:7]
	v_mfma_f32_16x16x32_bf16 v[0:3], v[186:189], v[218:221], v[0:3]
	s_setprio 0
	s_barrier
	s_add_i32 s92, 0, 0x18000
	v_add_u32_e32 v148, s92, v151
	s_add_i32 s93, 0, 0x1c000
	ds_read_b128 v[144:147], v148
	ds_read_b128 v[158:161], v148 offset:1024
	ds_read_b128 v[162:165], v148 offset:2048
	ds_read_b128 v[166:169], v148 offset:3072
	v_add_u32_e32 v148, s93, v151
	ds_read_b128 v[170:173], v148
	ds_read_b128 v[174:177], v148 offset:1024
	ds_read_b128 v[178:181], v148 offset:2048
	ds_read_b128 v[186:189], v148 offset:3072
	s_add_u32 s46, s46, 0x40000
	s_addc_u32 s47, s47, 0
	s_mov_b32 m0, s71
	v_lshl_add_u64 v[228:229], s[46:47], 0, v[134:135]
	ds_read_b128 v[190:193], v156 offset:32768
	ds_read_b128 v[194:197], v156 offset:33792
	ds_read_b128 v[198:201], v156 offset:34816
	ds_read_b128 v[202:205], v156 offset:35840
	ds_read_b128 v[206:209], v156 offset:36864
	ds_read_b128 v[210:213], v156 offset:37888
	ds_read_b128 v[214:217], v156 offset:38912
	ds_read_b128 v[218:221], v156 offset:39936
	global_load_lds_dwordx4 v[228:229], off
	v_lshl_add_u64 v[228:229], s[46:47], 0, v[130:131]
	s_mov_b32 m0, s72
	s_nop 0
	global_load_lds_dwordx4 v[228:229], off
	s_waitcnt vmcnt(8)
	s_waitcnt lgkmcnt(0)
	s_barrier
	s_setprio 1
	s_waitcnt lgkmcnt(0)
	v_mfma_f32_16x16x32_bf16 v[124:127], v[144:147], v[190:193], v[124:127]
	v_mfma_f32_16x16x32_bf16 v[120:123], v[162:165], v[190:193], v[120:123]
	v_mfma_f32_16x16x32_bf16 v[108:111], v[144:147], v[198:201], v[108:111]
	v_mfma_f32_16x16x32_bf16 v[104:107], v[162:165], v[198:201], v[104:107]
	v_mfma_f32_16x16x32_bf16 v[92:95], v[144:147], v[206:209], v[92:95]
	v_mfma_f32_16x16x32_bf16 v[88:91], v[162:165], v[206:209], v[88:91]
	v_mfma_f32_16x16x32_bf16 v[76:79], v[144:147], v[214:217], v[76:79]
	v_mfma_f32_16x16x32_bf16 v[72:75], v[162:165], v[214:217], v[72:75]
	v_mfma_f32_16x16x32_bf16 v[124:127], v[158:161], v[194:197], v[124:127]
	v_mfma_f32_16x16x32_bf16 v[120:123], v[166:169], v[194:197], v[120:123]
	v_mfma_f32_16x16x32_bf16 v[108:111], v[158:161], v[202:205], v[108:111]
	v_mfma_f32_16x16x32_bf16 v[104:107], v[166:169], v[202:205], v[104:107]
	v_mfma_f32_16x16x32_bf16 v[92:95], v[158:161], v[210:213], v[92:95]
	v_mfma_f32_16x16x32_bf16 v[88:91], v[166:169], v[210:213], v[88:91]
	v_mfma_f32_16x16x32_bf16 v[76:79], v[158:161], v[218:221], v[76:79]
	v_mfma_f32_16x16x32_bf16 v[72:75], v[166:169], v[218:221], v[72:75]
	s_setprio 0
	s_setprio 1
	v_mfma_f32_16x16x32_bf16 v[116:119], v[170:173], v[190:193], v[116:119]
	v_mfma_f32_16x16x32_bf16 v[112:115], v[178:181], v[190:193], v[112:115]
	v_mfma_f32_16x16x32_bf16 v[100:103], v[170:173], v[198:201], v[100:103]
	v_mfma_f32_16x16x32_bf16 v[96:99], v[178:181], v[198:201], v[96:99]
	v_mfma_f32_16x16x32_bf16 v[84:87], v[170:173], v[206:209], v[84:87]
	v_mfma_f32_16x16x32_bf16 v[80:83], v[178:181], v[206:209], v[80:83]
	v_mfma_f32_16x16x32_bf16 v[68:71], v[170:173], v[214:217], v[68:71]
	v_mfma_f32_16x16x32_bf16 v[64:67], v[178:181], v[214:217], v[64:67]
	v_mfma_f32_16x16x32_bf16 v[116:119], v[174:177], v[194:197], v[116:119]
	v_mfma_f32_16x16x32_bf16 v[112:115], v[186:189], v[194:197], v[112:115]
	v_mfma_f32_16x16x32_bf16 v[100:103], v[174:177], v[202:205], v[100:103]
	v_mfma_f32_16x16x32_bf16 v[96:99], v[186:189], v[202:205], v[96:99]
	v_mfma_f32_16x16x32_bf16 v[84:87], v[174:177], v[210:213], v[84:87]
	v_mfma_f32_16x16x32_bf16 v[80:83], v[186:189], v[210:213], v[80:83]
	v_mfma_f32_16x16x32_bf16 v[68:71], v[174:177], v[218:221], v[68:71]
	v_mfma_f32_16x16x32_bf16 v[64:67], v[186:189], v[218:221], v[64:67]
	s_setprio 0
	s_barrier
; #define PG8_STAGE(bufoff, gbase, voff) do { _Pragma("unroll") for (int _i = 0; _i < 2; ++_i) \
;         __builtin_amdgcn_global_load_lds((const unsigned*)((const char*)(gbase) + (voff)[_i]), (PG8_LAS unsigned*)(lds + (bufoff) + ldsw + _i * 8192), 16, 0, 0); } while (0)
; #define PG8_LDA(dst, b, h) do { _Pragma("unroll") for (int m = 0; m < 4; ++m) _Pragma("unroll") for (int k = 0; k < 2; ++k) dst[m][k] = *(const PG8_LAS bf16x8*)(lds + PG8_SA(b, h) + aoff + m * 2048 + k * 1024); } while (0)
; #define PG8_MMA(ai, bj, At, Bt) do { __builtin_amdgcn_s_setprio(1); _Pragma("unroll") for (int m = 0; m < 4; ++m) _Pragma("unroll") for (int n = 0; n < 2; ++n) _Pragma("unroll") for (int k = 0; k < 2; ++k) \
;         acc[ai][bj][m][n] = __builtin_amdgcn_mfma_f32_16x16x32_bf16(Bt[n][k], At[m][k], acc[ai][bj][m][n], 0, 0, 0); __builtin_amdgcn_s_setprio(0); } while (0)
; #define PG8_WAIT_V(n) asm volatile("s_waitcnt vmcnt(" #n ")" ::: "memory")
; #define PG8_WAIT_L(n) asm volatile("s_waitcnt lgkmcnt(" #n ")" ::: "memory")
; #define PG8_BAR __builtin_amdgcn_s_barrier()
; #define PG8_SCHED __builtin_amdgcn_sched_barrier(0)
; template <class Epi, class Sched, bool ALIGN_EPI = false, bool SP2 = false>
; __device__ __forceinline__ void gemm_phase(PG8_LAS unsigned char* lds, const Gemm g, const Sched& S, const Epi& E) {
;     ...
;         for (int t = 0; t < nt; t += 2) {
;     ...
;             PG8_LDA(At, 1, 1); PG8_STAGE(PG8_SB(1, 0), b3, voffB); PG8_STAGE(PG8_SB(1, 1), b3 + hstep, voffB); PG8_STAGE(PG8_SA(1, 0), a3, voffA);
;             PG8_WAIT_V(8); PG8_WAIT_L(0); PG8_BAR; PG8_MMA(1, 0, At, B0); PG8_MMA(1, 1, At, B1); PG8_BAR; PG8_SCHED;
	s_add_i32 s46, s92, s50
	v_lshl_add_u64 v[182:183], v[182:183], 0, s[20:21]
	s_mov_b32 m0, s46
	ds_read_b128 v[190:193], v156 offset:49152
	ds_read_b128 v[194:197], v156 offset:50176
	ds_read_b128 v[198:201], v156 offset:51200
	ds_read_b128 v[202:205], v156 offset:52224
	ds_read_b128 v[206:209], v156 offset:53248
	ds_read_b128 v[210:213], v156 offset:54272
	ds_read_b128 v[214:217], v156 offset:55296
	ds_read_b128 v[218:221], v156 offset:56320
	global_load_lds_dwordx4 v[182:183], off
	s_add_i32 m0, s46, 0x2000
	s_add_u32 s44, s44, 0x40080
	v_lshl_add_u64 v[182:183], v[222:223], 0, s[20:21]
	s_addc_u32 s45, s45, 0
	s_add_i32 s46, s93, s50
	global_load_lds_dwordx4 v[182:183], off
	v_lshl_add_u64 v[182:183], s[44:45], 0, v[132:133]
	s_mov_b32 m0, s46
	s_nop 0
	global_load_lds_dwordx4 v[182:183], off
	v_lshl_add_u64 v[182:183], s[44:45], 0, v[128:129]
	s_add_i32 m0, s46, 0x2000
	s_nop 0
	global_load_lds_dwordx4 v[182:183], off
	v_lshl_add_u64 v[182:183], v[224:225], 0, s[20:21]
	s_mov_b32 m0, s78
	s_nop 0
	global_load_lds_dwordx4 v[182:183], off
	v_lshl_add_u64 v[182:183], v[226:227], 0, s[20:21]
	s_mov_b32 m0, s79
	s_nop 0
	global_load_lds_dwordx4 v[182:183], off
	s_waitcnt vmcnt(8)
	s_waitcnt lgkmcnt(0)
	s_barrier
	s_setprio 1
	s_waitcnt lgkmcnt(0)
	v_mfma_f32_16x16x32_bf16 v[60:63], v[144:147], v[190:193], v[60:63]
	v_mfma_f32_16x16x32_bf16 v[56:59], v[162:165], v[190:193], v[56:59]
	v_mfma_f32_16x16x32_bf16 v[44:47], v[144:147], v[198:201], v[44:47]
	v_mfma_f32_16x16x32_bf16 v[40:43], v[162:165], v[198:201], v[40:43]
	v_mfma_f32_16x16x32_bf16 v[28:31], v[144:147], v[206:209], v[28:31]
	v_mfma_f32_16x16x32_bf16 v[24:27], v[162:165], v[206:209], v[24:27]
	v_mfma_f32_16x16x32_bf16 v[12:15], v[144:147], v[214:217], v[12:15]
	v_mfma_f32_16x16x32_bf16 v[8:11], v[162:165], v[214:217], v[8:11]
	v_mfma_f32_16x16x32_bf16 v[60:63], v[158:161], v[194:197], v[60:63]
	v_mfma_f32_16x16x32_bf16 v[56:59], v[166:169], v[194:197], v[56:59]
	v_mfma_f32_16x16x32_bf16 v[44:47], v[158:161], v[202:205], v[44:47]
	v_mfma_f32_16x16x32_bf16 v[40:43], v[166:169], v[202:205], v[40:43]
	v_mfma_f32_16x16x32_bf16 v[28:31], v[158:161], v[210:213], v[28:31]
	v_mfma_f32_16x16x32_bf16 v[24:27], v[166:169], v[210:213], v[24:27]
	v_mfma_f32_16x16x32_bf16 v[12:15], v[158:161], v[218:221], v[12:15]
	v_mfma_f32_16x16x32_bf16 v[8:11], v[166:169], v[218:221], v[8:11]
	s_setprio 0
	s_setprio 1
	v_mfma_f32_16x16x32_bf16 v[52:55], v[170:173], v[190:193], v[52:55]
	v_mfma_f32_16x16x32_bf16 v[48:51], v[178:181], v[190:193], v[48:51]
	v_mfma_f32_16x16x32_bf16 v[36:39], v[170:173], v[198:201], v[36:39]
	v_mfma_f32_16x16x32_bf16 v[32:35], v[178:181], v[198:201], v[32:35]
	v_mfma_f32_16x16x32_bf16 v[20:23], v[170:173], v[206:209], v[20:23]
	v_mfma_f32_16x16x32_bf16 v[16:19], v[178:181], v[206:209], v[16:19]
	v_mfma_f32_16x16x32_bf16 v[4:7], v[170:173], v[214:217], v[4:7]
	v_mfma_f32_16x16x32_bf16 v[0:3], v[178:181], v[214:217], v[0:3]
	v_mfma_f32_16x16x32_bf16 v[52:55], v[174:177], v[194:197], v[52:55]
	v_mfma_f32_16x16x32_bf16 v[48:51], v[186:189], v[194:197], v[48:51]
	v_mfma_f32_16x16x32_bf16 v[36:39], v[174:177], v[202:205], v[36:39]
	v_mfma_f32_16x16x32_bf16 v[32:35], v[186:189], v[202:205], v[32:35]
	v_mfma_f32_16x16x32_bf16 v[20:23], v[174:177], v[210:213], v[20:23]
	v_mfma_f32_16x16x32_bf16 v[16:19], v[186:189], v[210:213], v[16:19]
	v_mfma_f32_16x16x32_bf16 v[4:7], v[174:177], v[218:221], v[4:7]
	v_mfma_f32_16x16x32_bf16 v[0:3], v[186:189], v[218:221], v[0:3]
	s_setprio 0
	s_add_i32 s91, s91, 2
	s_add_u32 s36, s36, 0x100
	s_addc_u32 s37, s37, 0
	s_add_u32 s89, s89, 0x100
	s_addc_u32 s90, s90, 0
	s_cmp_gt_u32 s91, 13
	s_barrier
	s_cbranch_scc0 .LBB0_188
	s_and_b64 vcc, exec, s[22:23]
	s_cbranch_vccz .LBB0_191
	s_barrier

; #define PG8_STAGE(bufoff, gbase, voff) do { _Pragma("unroll") for (int _i = 0; _i < 2; ++_i) \
;         __builtin_amdgcn_global_load_lds((const unsigned*)((const char*)(gbase) + (voff)[_i]), (PG8_LAS unsigned*)(lds + (bufoff) + ldsw + _i * 8192), 16, 0, 0); } while (0)
; #define PG8_LDA(dst, b, h) do { _Pragma("unroll") for (int m = 0; m < 4; ++m) _Pragma("unroll") for (int k = 0; k < 2; ++k) dst[m][k] = *(const PG8_LAS bf16x8*)(lds + PG8_SA(b, h) + aoff + m * 2048 + k * 1024); } while (0)
; #define PG8_LDB(dst, b, h) do { _Pragma("unroll") for (int n = 0; n < 2; ++n) _Pragma("unroll") for (int k = 0; k < 2; ++k) dst[n][k] = *(const PG8_LAS bf16x8*)(lds + PG8_SB(b, h) + boff + n * 2048 + k * 1024); } while (0)
; #define PG8_MMA(ai, bj, At, Bt) do { __builtin_amdgcn_s_setprio(1); _Pragma("unroll") for (int m = 0; m < 4; ++m) _Pragma("unroll") for (int n = 0; n < 2; ++n) _Pragma("unroll") for (int k = 0; k < 2; ++k) \
;         acc[ai][bj][m][n] = __builtin_amdgcn_mfma_f32_16x16x32_bf16(Bt[n][k], At[m][k], acc[ai][bj][m][n], 0, 0, 0); __builtin_amdgcn_s_setprio(0); } while (0)
; #define PG8_WAIT_V(n) asm volatile("s_waitcnt vmcnt(" #n ")" ::: "memory")
; #define PG8_WAIT_L(n) asm volatile("s_waitcnt lgkmcnt(" #n ")" ::: "memory")
; #define PG8_BAR __builtin_amdgcn_s_barrier()
; #define PG8_SCHED __builtin_amdgcn_sched_barrier(0)
; template <class Epi, class Sched, bool ALIGN_EPI = false, bool SP2 = false>
; __device__ __forceinline__ void gemm_phase(PG8_LAS unsigned char* lds, const Gemm g, const Sched& S, const Epi& E) {
;     ...
;             const bool last = (t == nt - 2);
;             const char* a1 = cA + (size_t)(t + 1) * kstep;
;             const char* a2 = last ? nA : cA + (size_t)(t + 2) * kstep; const char* b2 = last ? nB : cB + (size_t)(t + 2) * kstep;
;             const char* a3 = a2 + kstep; const char* b3 = b2 + kstep;
;             if (last && has_next) S.a_ready(nxt);
;             if constexpr (SP2) {
;             PG8_LDB(B0, 0, 0); PG8_LDB(B1, 0, 1); PG8_SCHED; PG8_LDA(At, 0, 0); PG8_STAGE(PG8_SA(1, 1), a1 + hstep, voffA);
;             PG8_WAIT_V(8); PG8_WAIT_L(0); PG8_BAR; PG8_MMA(0, 0, At, B0); PG8_MMA(0, 1, At, B1); PG8_BAR; PG8_SCHED;
;             PG8_LDA(At, 0, 1); PG8_STAGE(PG8_SB(0, 0), b2, voffB); PG8_STAGE(PG8_SB(0, 1), b2 + hstep, voffB); PG8_STAGE(PG8_SA(0, 0), a2, voffA);
.LBB0_404:
	ds_read_b128 v[100:103], v223
	ds_read_b128 v[108:111], v223 offset:1024
	ds_read_b128 v[120:123], v223 offset:2048
	ds_read_b128 v[132:135], v223 offset:3072
	ds_read_b128 v[144:147], v224
	ds_read_b128 v[148:151], v224 offset:1024
	ds_read_b128 v[152:155], v224 offset:2048
	ds_read_b128 v[156:159], v224 offset:3072
	s_add_u32 s20, s18, 0xfffb0080
	s_addc_u32 s21, s19, -1
	s_cmp_eq_u32 s58, 16
	s_cselect_b32 s23, s7, s21
	s_cselect_b32 s22, s6, s20
	s_cselect_b32 s21, s9, s51
	s_cselect_b32 s20, s8, s50
	v_lshl_add_u64 v[212:213], s[18:19], 0, v[196:197]
	s_add_i32 m0, s30, 0xc000
	ds_read_b128 v[160:163], v225
	ds_read_b128 v[164:167], v225 offset:1024
	ds_read_b128 v[168:171], v225 offset:2048
	ds_read_b128 v[172:175], v225 offset:3072
	ds_read_b128 v[176:179], v225 offset:4096
	ds_read_b128 v[180:183], v225 offset:5120
	ds_read_b128 v[204:207], v225 offset:6144
	ds_read_b128 v[208:211], v225 offset:7168
	global_load_lds_dwordx4 v[212:213], off
	v_lshl_add_u64 v[212:213], s[18:19], 0, v[198:199]
	s_add_i32 m0, s30, 0xe000
	s_nop 0
	global_load_lds_dwordx4 v[212:213], off
	s_waitcnt vmcnt(8)
	s_waitcnt lgkmcnt(0)
	s_barrier
	s_setprio 1
	s_waitcnt lgkmcnt(0)
	v_mfma_f32_16x16x32_bf16 v[140:143], v[100:103], v[160:163], v[140:143]
	v_mfma_f32_16x16x32_bf16 v[136:139], v[120:123], v[160:163], v[136:139]
	v_mfma_f32_16x16x32_bf16 v[116:119], v[100:103], v[168:171], v[116:119]
	v_mfma_f32_16x16x32_bf16 v[112:115], v[120:123], v[168:171], v[112:115]
	v_mfma_f32_16x16x32_bf16 v[92:95], v[100:103], v[176:179], v[92:95]
	v_mfma_f32_16x16x32_bf16 v[88:91], v[120:123], v[176:179], v[88:91]
	v_mfma_f32_16x16x32_bf16 v[76:79], v[100:103], v[204:207], v[76:79]
	v_mfma_f32_16x16x32_bf16 v[72:75], v[120:123], v[204:207], v[72:75]
	v_mfma_f32_16x16x32_bf16 v[140:143], v[108:111], v[164:167], v[140:143]
	v_mfma_f32_16x16x32_bf16 v[136:139], v[132:135], v[164:167], v[136:139]
	v_mfma_f32_16x16x32_bf16 v[116:119], v[108:111], v[172:175], v[116:119]
	v_mfma_f32_16x16x32_bf16 v[112:115], v[132:135], v[172:175], v[112:115]
	v_mfma_f32_16x16x32_bf16 v[92:95], v[108:111], v[180:183], v[92:95]
	v_mfma_f32_16x16x32_bf16 v[88:91], v[132:135], v[180:183], v[88:91]
	v_mfma_f32_16x16x32_bf16 v[76:79], v[108:111], v[208:211], v[76:79]
	v_mfma_f32_16x16x32_bf16 v[72:75], v[132:135], v[208:211], v[72:75]
	s_setprio 0
	s_setprio 1
	v_mfma_f32_16x16x32_bf16 v[128:131], v[144:147], v[160:163], v[128:131]
	v_mfma_f32_16x16x32_bf16 v[124:127], v[152:155], v[160:163], v[124:127]
	v_mfma_f32_16x16x32_bf16 v[104:107], v[144:147], v[168:171], v[104:107]
	v_mfma_f32_16x16x32_bf16 v[96:99], v[152:155], v[168:171], v[96:99]
	v_mfma_f32_16x16x32_bf16 v[84:87], v[144:147], v[176:179], v[84:87]
	v_mfma_f32_16x16x32_bf16 v[80:83], v[152:155], v[176:179], v[80:83]
	v_mfma_f32_16x16x32_bf16 v[68:71], v[144:147], v[204:207], v[68:71]
	v_mfma_f32_16x16x32_bf16 v[64:67], v[152:155], v[204:207], v[64:67]
	v_mfma_f32_16x16x32_bf16 v[128:131], v[148:151], v[164:167], v[128:131]
	v_mfma_f32_16x16x32_bf16 v[124:127], v[156:159], v[164:167], v[124:127]
	v_mfma_f32_16x16x32_bf16 v[104:107], v[148:151], v[172:175], v[104:107]
	v_mfma_f32_16x16x32_bf16 v[96:99], v[156:159], v[172:175], v[96:99]
	v_mfma_f32_16x16x32_bf16 v[84:87], v[148:151], v[180:183], v[84:87]
	v_mfma_f32_16x16x32_bf16 v[80:83], v[156:159], v[180:183], v[80:83]
	v_mfma_f32_16x16x32_bf16 v[68:71], v[148:151], v[208:211], v[68:71]
	v_mfma_f32_16x16x32_bf16 v[64:67], v[156:159], v[208:211], v[64:67]
	s_setprio 0
	s_barrier
	s_add_i32 s69, s44, s29
	v_lshl_add_u64 v[212:213], s[20:21], 0, v[190:191]
	s_mov_b32 m0, s69
	ds_read_b128 v[160:163], v225 offset:16384
	ds_read_b128 v[164:167], v225 offset:17408
	ds_read_b128 v[168:171], v225 offset:18432
	ds_read_b128 v[172:175], v225 offset:19456
	ds_read_b128 v[176:179], v225 offset:20480
	ds_read_b128 v[180:183], v225 offset:21504
	ds_read_b128 v[204:207], v225 offset:22528
	ds_read_b128 v[208:211], v225 offset:23552
	global_load_lds_dwordx4 v[212:213], off
	s_add_i32 m0, s69, 0x2000
	s_add_u32 s70, s20, 0x50000
	v_lshl_add_u64 v[214:215], s[20:21], 0, v[194:195]
	s_addc_u32 s71, s21, 0
	s_add_i32 s69, s45, s29
	global_load_lds_dwordx4 v[214:215], off
	v_lshl_add_u64 v[216:217], s[70:71], 0, v[190:191]
	s_mov_b32 m0, s69
	v_lshl_add_u64 v[218:219], s[22:23], 0, v[192:193]
	global_load_lds_dwordx4 v[216:217], off
	v_lshl_add_u64 v[216:217], s[70:71], 0, v[194:195]
	s_add_i32 m0, s69, 0x2000
	s_nop 0
	global_load_lds_dwordx4 v[216:217], off
	v_lshl_add_u64 v[216:217], s[22:23], 0, v[188:189]
	s_mov_b32 m0, s30
	s_nop 0
	global_load_lds_dwordx4 v[216:217], off
	s_mov_b32 m0, s31
	s_nop 0
	global_load_lds_dwordx4 v[218:219], off
	s_waitcnt vmcnt(8)
	s_waitcnt lgkmcnt(0)
	s_barrier
; #define PG8_STAGE(bufoff, gbase, voff) do { _Pragma("unroll") for (int _i = 0; _i < 2; ++_i) \
;         __builtin_amdgcn_global_load_lds((const unsigned*)((const char*)(gbase) + (voff)[_i]), (PG8_LAS unsigned*)(lds + (bufoff) + ldsw + _i * 8192), 16, 0, 0); } while (0)
; #define PG8_LDA(dst, b, h) do { _Pragma("unroll") for (int m = 0; m < 4; ++m) _Pragma("unroll") for (int k = 0; k < 2; ++k) dst[m][k] = *(const PG8_LAS bf16x8*)(lds + PG8_SA(b, h) + aoff + m * 2048 + k * 1024); } while (0)
; #define PG8_LDB(dst, b, h) do { _Pragma("unroll") for (int n = 0; n < 2; ++n) _Pragma("unroll") for (int k = 0; k < 2; ++k) dst[n][k] = *(const PG8_LAS bf16x8*)(lds + PG8_SB(b, h) + boff + n * 2048 + k * 1024); } while (0)
; #define PG8_MMA(ai, bj, At, Bt) do { __builtin_amdgcn_s_setprio(1); _Pragma("unroll") for (int m = 0; m < 4; ++m) _Pragma("unroll") for (int n = 0; n < 2; ++n) _Pragma("unroll") for (int k = 0; k < 2; ++k) \
;         acc[ai][bj][m][n] = __builtin_amdgcn_mfma_f32_16x16x32_bf16(Bt[n][k], At[m][k], acc[ai][bj][m][n], 0, 0, 0); __builtin_amdgcn_s_setprio(0); } while (0)
; #define PG8_WAIT_V(n) asm volatile("s_waitcnt vmcnt(" #n ")" ::: "memory")
; #define PG8_WAIT_L(n) asm volatile("s_waitcnt lgkmcnt(" #n ")" ::: "memory")
; #define PG8_BAR __builtin_amdgcn_s_barrier()
; #define PG8_SCHED __builtin_amdgcn_sched_barrier(0)
; template <class Epi, class Sched, bool ALIGN_EPI = false, bool SP2 = false>
; __device__ __forceinline__ void gemm_phase(PG8_LAS unsigned char* lds, const Gemm g, const Sched& S, const Epi& E) {
;     ...
;             PG8_WAIT_V(8); PG8_WAIT_L(0); PG8_BAR; PG8_MMA(1, 0, At, B0); PG8_MMA(1, 1, At, B1); PG8_BAR; PG8_SCHED;
;             PG8_LDB(B0, 1, 0); PG8_LDB(B1, 1, 1); PG8_SCHED; PG8_LDA(At, 1, 0); PG8_STAGE(PG8_SA(0, 1), a2 + hstep, voffA);
;             PG8_WAIT_V(8); PG8_WAIT_L(0); PG8_BAR; PG8_MMA(0, 0, At, B0); PG8_MMA(0, 1, At, B1); PG8_BAR; PG8_SCHED;
	s_setprio 1
	s_waitcnt lgkmcnt(0)
	v_mfma_f32_16x16x32_bf16 v[60:63], v[100:103], v[160:163], v[60:63]
	v_mfma_f32_16x16x32_bf16 v[56:59], v[120:123], v[160:163], v[56:59]
	v_mfma_f32_16x16x32_bf16 v[44:47], v[100:103], v[168:171], v[44:47]
	v_mfma_f32_16x16x32_bf16 v[40:43], v[120:123], v[168:171], v[40:43]
	v_mfma_f32_16x16x32_bf16 v[28:31], v[100:103], v[176:179], v[28:31]
	v_mfma_f32_16x16x32_bf16 v[24:27], v[120:123], v[176:179], v[24:27]
	v_mfma_f32_16x16x32_bf16 v[12:15], v[100:103], v[204:207], v[12:15]
	v_mfma_f32_16x16x32_bf16 v[8:11], v[120:123], v[204:207], v[8:11]
	v_mfma_f32_16x16x32_bf16 v[60:63], v[108:111], v[164:167], v[60:63]
	v_mfma_f32_16x16x32_bf16 v[56:59], v[132:135], v[164:167], v[56:59]
	v_mfma_f32_16x16x32_bf16 v[44:47], v[108:111], v[172:175], v[44:47]
	v_mfma_f32_16x16x32_bf16 v[40:43], v[132:135], v[172:175], v[40:43]
	v_mfma_f32_16x16x32_bf16 v[28:31], v[108:111], v[180:183], v[28:31]
	v_mfma_f32_16x16x32_bf16 v[24:27], v[132:135], v[180:183], v[24:27]
	v_mfma_f32_16x16x32_bf16 v[12:15], v[108:111], v[208:211], v[12:15]
	v_mfma_f32_16x16x32_bf16 v[8:11], v[132:135], v[208:211], v[8:11]
	s_setprio 0
	s_setprio 1
	v_mfma_f32_16x16x32_bf16 v[52:55], v[144:147], v[160:163], v[52:55]
	v_mfma_f32_16x16x32_bf16 v[48:51], v[152:155], v[160:163], v[48:51]
	v_mfma_f32_16x16x32_bf16 v[36:39], v[144:147], v[168:171], v[36:39]
	v_mfma_f32_16x16x32_bf16 v[32:35], v[152:155], v[168:171], v[32:35]
	v_mfma_f32_16x16x32_bf16 v[20:23], v[144:147], v[176:179], v[20:23]
	v_mfma_f32_16x16x32_bf16 v[16:19], v[152:155], v[176:179], v[16:19]
	v_mfma_f32_16x16x32_bf16 v[4:7], v[144:147], v[204:207], v[4:7]
	v_mfma_f32_16x16x32_bf16 v[0:3], v[152:155], v[204:207], v[0:3]
	v_mfma_f32_16x16x32_bf16 v[52:55], v[148:151], v[164:167], v[52:55]
	v_mfma_f32_16x16x32_bf16 v[48:51], v[156:159], v[164:167], v[48:51]
	v_mfma_f32_16x16x32_bf16 v[36:39], v[148:151], v[172:175], v[36:39]
	v_mfma_f32_16x16x32_bf16 v[32:35], v[156:159], v[172:175], v[32:35]
	v_mfma_f32_16x16x32_bf16 v[20:23], v[148:151], v[180:183], v[20:23]
	v_mfma_f32_16x16x32_bf16 v[16:19], v[156:159], v[180:183], v[16:19]
	v_mfma_f32_16x16x32_bf16 v[4:7], v[148:151], v[208:211], v[4:7]
	v_mfma_f32_16x16x32_bf16 v[0:3], v[156:159], v[208:211], v[0:3]
	s_setprio 0
	s_barrier
	s_add_i32 s69, 0, 0x18000
	s_add_i32 s70, 0, 0x1c000
	v_add_u32_e32 v132, s69, v187
	v_add_u32_e32 v156, s70, v187
	ds_read_b128 v[100:103], v132
	ds_read_b128 v[108:111], v132 offset:1024
	ds_read_b128 v[120:123], v132 offset:2048
	ds_read_b128 v[132:135], v132 offset:3072
	ds_read_b128 v[144:147], v156
	ds_read_b128 v[148:151], v156 offset:1024
	ds_read_b128 v[152:155], v156 offset:2048
	ds_read_b128 v[156:159], v156 offset:3072
	s_add_u32 s22, s22, 0x50000
	s_addc_u32 s23, s23, 0
	s_mov_b32 m0, s34
	v_lshl_add_u64 v[220:221], s[22:23], 0, v[188:189]
	ds_read_b128 v[160:163], v225 offset:32768
	ds_read_b128 v[164:167], v225 offset:33792
	ds_read_b128 v[168:171], v225 offset:34816
	ds_read_b128 v[172:175], v225 offset:35840
	ds_read_b128 v[176:179], v225 offset:36864
	ds_read_b128 v[180:183], v225 offset:37888
	ds_read_b128 v[204:207], v225 offset:38912
	ds_read_b128 v[208:211], v225 offset:39936
	global_load_lds_dwordx4 v[220:221], off
	v_lshl_add_u64 v[220:221], s[22:23], 0, v[192:193]
	s_mov_b32 m0, s35
	s_nop 0
	global_load_lds_dwordx4 v[220:221], off
	s_waitcnt vmcnt(8)
	s_waitcnt lgkmcnt(0)
	s_barrier
	s_setprio 1
	s_waitcnt lgkmcnt(0)
	v_mfma_f32_16x16x32_bf16 v[140:143], v[100:103], v[160:163], v[140:143]
	v_mfma_f32_16x16x32_bf16 v[136:139], v[120:123], v[160:163], v[136:139]
	v_mfma_f32_16x16x32_bf16 v[116:119], v[100:103], v[168:171], v[116:119]
	v_mfma_f32_16x16x32_bf16 v[112:115], v[120:123], v[168:171], v[112:115]
	v_mfma_f32_16x16x32_bf16 v[92:95], v[100:103], v[176:179], v[92:95]
	v_mfma_f32_16x16x32_bf16 v[88:91], v[120:123], v[176:179], v[88:91]
	v_mfma_f32_16x16x32_bf16 v[76:79], v[100:103], v[204:207], v[76:79]
	v_mfma_f32_16x16x32_bf16 v[72:75], v[120:123], v[204:207], v[72:75]
	v_mfma_f32_16x16x32_bf16 v[140:143], v[108:111], v[164:167], v[140:143]
	v_mfma_f32_16x16x32_bf16 v[136:139], v[132:135], v[164:167], v[136:139]
	v_mfma_f32_16x16x32_bf16 v[116:119], v[108:111], v[172:175], v[116:119]
	v_mfma_f32_16x16x32_bf16 v[112:115], v[132:135], v[172:175], v[112:115]
	v_mfma_f32_16x16x32_bf16 v[92:95], v[108:111], v[180:183], v[92:95]
	v_mfma_f32_16x16x32_bf16 v[88:91], v[132:135], v[180:183], v[88:91]
	v_mfma_f32_16x16x32_bf16 v[76:79], v[108:111], v[208:211], v[76:79]
	v_mfma_f32_16x16x32_bf16 v[72:75], v[132:135], v[208:211], v[72:75]
	s_setprio 0
	s_setprio 1
	v_mfma_f32_16x16x32_bf16 v[128:131], v[144:147], v[160:163], v[128:131]
	v_mfma_f32_16x16x32_bf16 v[124:127], v[152:155], v[160:163], v[124:127]
	v_mfma_f32_16x16x32_bf16 v[104:107], v[144:147], v[168:171], v[104:107]
	v_mfma_f32_16x16x32_bf16 v[96:99], v[152:155], v[168:171], v[96:99]
	v_mfma_f32_16x16x32_bf16 v[84:87], v[144:147], v[176:179], v[84:87]
	v_mfma_f32_16x16x32_bf16 v[80:83], v[152:155], v[176:179], v[80:83]
	v_mfma_f32_16x16x32_bf16 v[68:71], v[144:147], v[204:207], v[68:71]
	v_mfma_f32_16x16x32_bf16 v[64:67], v[152:155], v[204:207], v[64:67]
	v_mfma_f32_16x16x32_bf16 v[128:131], v[148:151], v[164:167], v[128:131]
	v_mfma_f32_16x16x32_bf16 v[124:127], v[156:159], v[164:167], v[124:127]
	v_mfma_f32_16x16x32_bf16 v[104:107], v[148:151], v[172:175], v[104:107]
	v_mfma_f32_16x16x32_bf16 v[96:99], v[156:159], v[172:175], v[96:99]
	v_mfma_f32_16x16x32_bf16 v[84:87], v[148:151], v[180:183], v[84:87]
	v_mfma_f32_16x16x32_bf16 v[80:83], v[156:159], v[180:183], v[80:83]
	v_mfma_f32_16x16x32_bf16 v[68:71], v[148:151], v[208:211], v[68:71]
	v_mfma_f32_16x16x32_bf16 v[64:67], v[156:159], v[208:211], v[64:67]
	s_setprio 0
	s_barrier
; #define PG8_STAGE(bufoff, gbase, voff) do { _Pragma("unroll") for (int _i = 0; _i < 2; ++_i) \
;         __builtin_amdgcn_global_load_lds((const unsigned*)((const char*)(gbase) + (voff)[_i]), (PG8_LAS unsigned*)(lds + (bufoff) + ldsw + _i * 8192), 16, 0, 0); } while (0)
; #define PG8_LDA(dst, b, h) do { _Pragma("unroll") for (int m = 0; m < 4; ++m) _Pragma("unroll") for (int k = 0; k < 2; ++k) dst[m][k] = *(const PG8_LAS bf16x8*)(lds + PG8_SA(b, h) + aoff + m * 2048 + k * 1024); } while (0)
; #define PG8_MMA(ai, bj, At, Bt) do { __builtin_amdgcn_s_setprio(1); _Pragma("unroll") for (int m = 0; m < 4; ++m) _Pragma("unroll") for (int n = 0; n < 2; ++n) _Pragma("unroll") for (int k = 0; k < 2; ++k) \
;         acc[ai][bj][m][n] = __builtin_amdgcn_mfma_f32_16x16x32_bf16(Bt[n][k], At[m][k], acc[ai][bj][m][n], 0, 0, 0); __builtin_amdgcn_s_setprio(0); } while (0)
; #define PG8_WAIT_V(n) asm volatile("s_waitcnt vmcnt(" #n ")" ::: "memory")
; #define PG8_WAIT_L(n) asm volatile("s_waitcnt lgkmcnt(" #n ")" ::: "memory")
; #define PG8_BAR __builtin_amdgcn_s_barrier()
; #define PG8_SCHED __builtin_amdgcn_sched_barrier(0)
; template <class Epi, class Sched, bool ALIGN_EPI = false, bool SP2 = false>
; __device__ __forceinline__ void gemm_phase(PG8_LAS unsigned char* lds, const Gemm g, const Sched& S, const Epi& E) {
;     ...
;         for (int t = 0; t < nt; t += 2) {
;     ...
;             PG8_LDA(At, 1, 1); PG8_STAGE(PG8_SB(1, 0), b3, voffB); PG8_STAGE(PG8_SB(1, 1), b3 + hstep, voffB); PG8_STAGE(PG8_SA(1, 0), a3, voffA);
;             PG8_WAIT_V(8); PG8_WAIT_L(0); PG8_BAR; PG8_MMA(1, 0, At, B0); PG8_MMA(1, 1, At, B1); PG8_BAR; PG8_SCHED;
	s_add_i32 s22, s69, s29
	v_lshl_add_u64 v[212:213], v[212:213], 0, s[16:17]
	s_mov_b32 m0, s22
	ds_read_b128 v[160:163], v225 offset:49152
	ds_read_b128 v[164:167], v225 offset:50176
	ds_read_b128 v[168:171], v225 offset:51200
	ds_read_b128 v[172:175], v225 offset:52224
	ds_read_b128 v[176:179], v225 offset:53248
	ds_read_b128 v[180:183], v225 offset:54272
	ds_read_b128 v[204:207], v225 offset:55296
	ds_read_b128 v[208:211], v225 offset:56320
	global_load_lds_dwordx4 v[212:213], off
	s_add_i32 m0, s22, 0x2000
	s_add_u32 s20, s20, 0x50080
	v_lshl_add_u64 v[212:213], v[214:215], 0, s[16:17]
	s_addc_u32 s21, s21, 0
	s_add_i32 s22, s70, s29
	global_load_lds_dwordx4 v[212:213], off
	v_lshl_add_u64 v[212:213], s[20:21], 0, v[190:191]
	s_mov_b32 m0, s22
	s_nop 0
	global_load_lds_dwordx4 v[212:213], off
	v_lshl_add_u64 v[212:213], s[20:21], 0, v[194:195]
	s_add_i32 m0, s22, 0x2000
	s_nop 0
	global_load_lds_dwordx4 v[212:213], off
	v_lshl_add_u64 v[212:213], v[216:217], 0, s[16:17]
	s_mov_b32 m0, s37
	s_nop 0
	global_load_lds_dwordx4 v[212:213], off
	v_lshl_add_u64 v[212:213], v[218:219], 0, s[16:17]
	s_mov_b32 m0, s38
	s_nop 0
	global_load_lds_dwordx4 v[212:213], off
	s_waitcnt vmcnt(8)
	s_waitcnt lgkmcnt(0)
	s_barrier
	s_setprio 1
	s_waitcnt lgkmcnt(0)
	v_mfma_f32_16x16x32_bf16 v[60:63], v[100:103], v[160:163], v[60:63]
	v_mfma_f32_16x16x32_bf16 v[56:59], v[120:123], v[160:163], v[56:59]
	v_mfma_f32_16x16x32_bf16 v[44:47], v[100:103], v[168:171], v[44:47]
	v_mfma_f32_16x16x32_bf16 v[40:43], v[120:123], v[168:171], v[40:43]
	v_mfma_f32_16x16x32_bf16 v[28:31], v[100:103], v[176:179], v[28:31]
	v_mfma_f32_16x16x32_bf16 v[24:27], v[120:123], v[176:179], v[24:27]
	v_mfma_f32_16x16x32_bf16 v[12:15], v[100:103], v[204:207], v[12:15]
	v_mfma_f32_16x16x32_bf16 v[8:11], v[120:123], v[204:207], v[8:11]
	v_mfma_f32_16x16x32_bf16 v[60:63], v[108:111], v[164:167], v[60:63]
	v_mfma_f32_16x16x32_bf16 v[56:59], v[132:135], v[164:167], v[56:59]
	v_mfma_f32_16x16x32_bf16 v[44:47], v[108:111], v[172:175], v[44:47]
	v_mfma_f32_16x16x32_bf16 v[40:43], v[132:135], v[172:175], v[40:43]
	v_mfma_f32_16x16x32_bf16 v[28:31], v[108:111], v[180:183], v[28:31]
	v_mfma_f32_16x16x32_bf16 v[24:27], v[132:135], v[180:183], v[24:27]
	v_mfma_f32_16x16x32_bf16 v[12:15], v[108:111], v[208:211], v[12:15]
	v_mfma_f32_16x16x32_bf16 v[8:11], v[132:135], v[208:211], v[8:11]
	s_setprio 0
	s_setprio 1
	v_mfma_f32_16x16x32_bf16 v[52:55], v[144:147], v[160:163], v[52:55]
	v_mfma_f32_16x16x32_bf16 v[48:51], v[152:155], v[160:163], v[48:51]
	v_mfma_f32_16x16x32_bf16 v[36:39], v[144:147], v[168:171], v[36:39]
	v_mfma_f32_16x16x32_bf16 v[32:35], v[152:155], v[168:171], v[32:35]
	v_mfma_f32_16x16x32_bf16 v[20:23], v[144:147], v[176:179], v[20:23]
	v_mfma_f32_16x16x32_bf16 v[16:19], v[152:155], v[176:179], v[16:19]
	v_mfma_f32_16x16x32_bf16 v[4:7], v[144:147], v[204:207], v[4:7]
	v_mfma_f32_16x16x32_bf16 v[0:3], v[152:155], v[204:207], v[0:3]
	v_mfma_f32_16x16x32_bf16 v[52:55], v[148:151], v[164:167], v[52:55]
	v_mfma_f32_16x16x32_bf16 v[48:51], v[156:159], v[164:167], v[48:51]
	v_mfma_f32_16x16x32_bf16 v[36:39], v[148:151], v[172:175], v[36:39]
	v_mfma_f32_16x16x32_bf16 v[32:35], v[156:159], v[172:175], v[32:35]
	v_mfma_f32_16x16x32_bf16 v[20:23], v[148:151], v[180:183], v[20:23]
	v_mfma_f32_16x16x32_bf16 v[16:19], v[156:159], v[180:183], v[16:19]
	v_mfma_f32_16x16x32_bf16 v[4:7], v[148:151], v[208:211], v[4:7]
	v_mfma_f32_16x16x32_bf16 v[0:3], v[156:159], v[208:211], v[0:3]
	s_setprio 0
	s_add_i32 s58, s58, 2
	s_add_u32 s18, s18, 0x100
	s_addc_u32 s19, s19, 0
	s_add_u32 s50, s50, 0x100
	s_addc_u32 s51, s51, 0
	s_cmp_gt_u32 s58, 17
	s_barrier
	s_cbranch_scc0 .LBB0_404
; __device__ __forceinline__ unsigned cvt_pk_bf16(float lo, float hi) { unsigned r; asm volatile("v_cvt_pk_bf16_f32 %0, %1, %2" : "=v"(r) : "v"(lo), "v"(hi)); return r; }
;     __device__ __forceinline__ void operator()(const f32x4 (&acc)[2][2][4][2], const Unit& u, int wr, int wc, int fr, int fq) const {
;         const int row0 = u.pm * BM + wr * 64 + fr, col0 = u.pn * BM + wc * 32 + 8 * fq;
;         u32x4 rb[2][4][2];
; #pragma unroll
;         for (int ai = 0; ai < 2; ++ai)
; #pragma unroll
;             for (int m = 0; m < 4; ++m)
; #pragma unroll
;                 for (int bj = 0; bj < 2; ++bj) rb[ai][m][bj] = *(const u32x4*)(base + (size_t)(row0 + ai * HALF + m * 16) * ldc + col0 + bj * HALF);
;         asm volatile("" ::: "memory");
; #pragma unroll
;         for (int ai = 0; ai < 2; ++ai)
; #pragma unroll
;             for (int m = 0; m < 4; ++m) { const int row = row0 + ai * HALF + m * 16; float s = 0.f;
; #pragma unroll
;                 for (int bj = 0; bj < 2; ++bj) { const u32x4 w = rb[ai][m][bj];
;                     const f32x4 v0 = acc[ai][bj][m][0] + (f32x4){__uint_as_float(w.x << 16), __uint_as_float(w.x & 0xffff0000u), __uint_as_float(w.y << 16), __uint_as_float(w.y & 0xffff0000u)};
;                     const f32x4 v1 = acc[ai][bj][m][1] + (f32x4){__uint_as_float(w.z << 16), __uint_as_float(w.z & 0xffff0000u), __uint_as_float(w.w << 16), __uint_as_float(w.w & 0xffff0000u)};
;                     s += ((v0[0] * v0[0] + v0[1] * v0[1]) + (v0[2] * v0[2] + v0[3] * v0[3])) + ((v1[0] * v1[0] + v1[1] * v1[1]) + (v1[2] * v1[2] + v1[3] * v1[3]));
;                     u32x4 o; o.x = cvt_pk_bf16(v0[0], v0[1]); o.y = cvt_pk_bf16(v0[2], v0[3]); o.z = cvt_pk_bf16(v1[0], v1[1]); o.w = cvt_pk_bf16(v1[2], v1[3]);
;                     *(u32x4*)(outb + (size_t)row * ldc + col0 + bj * HALF) = o; }
;                 s += __shfl_xor(s, 16); s += __shfl_xor(s, 32);
;                 if (fq == 0) atomicAdd(ssq + row, s); }
	v_lshl_or_b32 v204, s48, 8, v222
	v_lshl_add_u32 v220, s49, 8, v185
	v_ashrrev_i32_e32 v205, 31, v204
	v_lshlrev_b64 v[238:239], 1, v[204:205]
	v_ashrrev_i32_e32 v221, 31, v220
	v_lshl_add_u64 v[100:101], s[12:13], 0, v[238:239]
	v_lshlrev_b64 v[240:241], 11, v[220:221]
	v_lshl_add_u64 v[102:103], v[100:101], 0, v[240:241]
	global_load_dwordx4 v[228:231], v[102:103], off
	global_load_dwordx4 v[234:237], v[102:103], off offset:256
	v_or_b32_e32 v218, 16, v220
	v_or_b32_e32 v216, 32, v220
	v_or_b32_e32 v214, 48, v220
	v_add_u32_e32 v212, 0x80, v220
	v_add_u32_e32 v210, 0x90, v220
	v_add_u32_e32 v208, 0xa0, v220
	v_add_u32_e32 v206, 0xb0, v220
	v_ashrrev_i32_e32 v219, 31, v218
	v_ashrrev_i32_e32 v217, 31, v216
	v_ashrrev_i32_e32 v215, 31, v214
	v_ashrrev_i32_e32 v213, 31, v212
	v_ashrrev_i32_e32 v211, 31, v210
	v_ashrrev_i32_e32 v209, 31, v208
	v_ashrrev_i32_e32 v207, 31, v206
	v_lshlrev_b64 v[102:103], 11, v[218:219]
	v_lshlrev_b64 v[108:109], 11, v[216:217]
	v_lshlrev_b64 v[110:111], 11, v[214:215]
	v_lshlrev_b64 v[120:121], 11, v[212:213]
	v_lshlrev_b64 v[122:123], 11, v[210:211]
	v_lshlrev_b64 v[132:133], 11, v[208:209]
	v_lshlrev_b64 v[134:135], 11, v[206:207]
	v_lshl_add_u64 v[102:103], v[100:101], 0, v[102:103]
	v_lshl_add_u64 v[108:109], v[100:101], 0, v[108:109]
	v_lshl_add_u64 v[110:111], v[100:101], 0, v[110:111]
	v_lshl_add_u64 v[120:121], v[100:101], 0, v[120:121]
	v_lshl_add_u64 v[122:123], v[100:101], 0, v[122:123]
	v_lshl_add_u64 v[242:243], v[100:101], 0, v[132:133]
	v_lshl_add_u64 v[100:101], v[100:101], 0, v[134:135]
	global_load_dwordx4 v[180:183], v[102:103], off
	global_load_dwordx4 v[176:179], v[102:103], off offset:256
	global_load_dwordx4 v[172:175], v[108:109], off
	global_load_dwordx4 v[168:171], v[108:109], off offset:256
	global_load_dwordx4 v[164:167], v[110:111], off
	global_load_dwordx4 v[160:163], v[110:111], off offset:256
	global_load_dwordx4 v[156:159], v[120:121], off
	global_load_dwordx4 v[152:155], v[120:121], off offset:256
	global_load_dwordx4 v[148:151], v[122:123], off
	global_load_dwordx4 v[144:147], v[122:123], off offset:256
	global_load_dwordx4 v[132:135], v[242:243], off
	s_nop 0
	global_load_dwordx4 v[120:123], v[242:243], off offset:256
	global_load_dwordx4 v[108:111], v[100:101], off
	s_nop 0
	global_load_dwordx4 v[100:103], v[100:101], off offset:256
	s_waitcnt vmcnt(0)
	v_lshlrev_b32_e32 v242, 16, v228
	v_and_b32_e32 v243, 0xffff0000, v228
	v_lshlrev_b32_e32 v228, 16, v229
	v_and_b32_e32 v229, 0xffff0000, v229
	v_lshlrev_b32_e32 v244, 16, v230
	v_and_b32_e32 v245, 0xffff0000, v230
	v_lshlrev_b32_e32 v230, 16, v231
	v_and_b32_e32 v231, 0xffff0000, v231
	v_lshlrev_b32_e32 v246, 16, v234
	v_and_b32_e32 v247, 0xffff0000, v234
	v_lshlrev_b32_e32 v234, 16, v235
	v_and_b32_e32 v235, 0xffff0000, v235
	v_pk_add_f32 v[142:143], v[142:143], v[228:229]
	v_pk_add_f32 v[140:141], v[140:141], v[242:243]
	v_pk_add_f32 v[138:139], v[138:139], v[230:231]
	v_pk_add_f32 v[136:137], v[136:137], v[244:245]
	v_pk_add_f32 v[130:131], v[130:131], v[234:235]
	v_mul_f32_e32 v227, v141, v141
	v_mul_f32_e32 v233, v143, v143
	v_mul_f32_e32 v234, v137, v137
	v_mul_f32_e32 v235, v139, v139
	v_lshlrev_b32_e32 v248, 16, v236
	v_and_b32_e32 v249, 0xffff0000, v236
	v_lshlrev_b32_e32 v236, 16, v237
	v_and_b32_e32 v237, 0xffff0000, v237
	v_fmac_f32_e32 v227, v140, v140
	v_fmac_f32_e32 v233, v142, v142
	v_fmac_f32_e32 v234, v136, v136
	v_fmac_f32_e32 v235, v138, v138
	v_pk_add_f32 v[228:229], v[128:129], v[246:247]
	v_pk_add_f32 v[230:231], v[126:127], v[236:237]
	v_cvt_pk_bf16_f32 v126, v140, v141
	v_cvt_pk_bf16_f32 v127, v142, v143
	v_cvt_pk_bf16_f32 v128, v136, v137
	v_add_f32_e32 v136, v227, v233
	v_add_f32_e32 v137, v234, v235
	v_cvt_pk_bf16_f32 v129, v138, v139
	v_add_f32_e32 v138, v136, v137
	v_pk_add_f32 v[136:137], v[124:125], v[248:249]
	v_mul_f32_e32 v124, v229, v229
	v_mul_f32_e32 v125, v131, v131
	v_fmac_f32_e32 v124, v228, v228
	v_fmac_f32_e32 v125, v130, v130
	v_add_f32_e32 v124, v124, v125
	v_mul_f32_e32 v125, v137, v137
	v_mul_f32_e32 v139, v231, v231
	v_fmac_f32_e32 v125, v136, v136
	v_fmac_f32_e32 v139, v230, v230
	v_add_f32_e32 v125, v125, v139
	v_add_f32_e32 v124, v124, v125
	v_add_f32_e32 v125, v138, v124
	v_and_b32_e32 v138, 64, v226
	v_xor_b32_e32 v124, 16, v226
	v_add_u32_e32 v140, 64, v138
	v_cmp_lt_i32_e32 vcc, v124, v140
	v_lshl_add_u64 v[138:139], s[12:13], 0, v[240:241]
	v_lshl_add_u64 v[138:139], v[138:139], 0, v[238:239]
	v_cndmask_b32_e32 v124, v226, v124, vcc
	v_lshlrev_b32_e32 v124, 2, v124
	ds_bpermute_b32 v141, v124, v125
	global_store_dwordx4 v[138:139], v[126:129], off
	s_nop 1
	v_cvt_pk_bf16_f32 v128, v228, v229
	s_waitcnt lgkmcnt(0)
	v_add_f32_e32 v126, v125, v141
	v_xor_b32_e32 v125, 32, v226
	v_cmp_lt_i32_e32 vcc, v125, v140
	v_cvt_pk_bf16_f32 v129, v130, v131
	v_cvt_pk_bf16_f32 v130, v136, v137
	v_cvt_pk_bf16_f32 v131, v230, v231
	global_store_dwordx4 v[138:139], v[128:131], off offset:256
	s_nop 0
	v_cndmask_b32_e32 v125, v226, v125, vcc
	v_lshlrev_b32_e32 v125, 2, v125
	ds_bpermute_b32 v127, v125, v126
	s_and_saveexec_b64 s[18:19], s[2:3]
	s_cbranch_execz .LBB0_407
	v_lshl_add_u64 v[128:129], v[220:221], 2, s[14:15]
	s_waitcnt lgkmcnt(0)
	v_add_f32_e32 v126, v126, v127
	global_atomic_add_f32 v[128:129], v126, off

; #define PG8_STAGE(bufoff, gbase, voff) do { _Pragma("unroll") for (int _i = 0; _i < 2; ++_i) \
;         __builtin_amdgcn_global_load_lds((const unsigned*)((const char*)(gbase) + (voff)[_i]), (PG8_LAS unsigned*)(lds + (bufoff) + ldsw + _i * 8192), 16, 0, 0); } while (0)
; #define PG8_LDA(dst, b, h) do { _Pragma("unroll") for (int m = 0; m < 4; ++m) _Pragma("unroll") for (int k = 0; k < 2; ++k) dst[m][k] = *(const PG8_LAS bf16x8*)(lds + PG8_SA(b, h) + aoff + m * 2048 + k * 1024); } while (0)
; #define PG8_LDB(dst, b, h) do { _Pragma("unroll") for (int n = 0; n < 2; ++n) _Pragma("unroll") for (int k = 0; k < 2; ++k) dst[n][k] = *(const PG8_LAS bf16x8*)(lds + PG8_SB(b, h) + boff + n * 2048 + k * 1024); } while (0)
; #define PG8_MMA(ai, bj, At, Bt) do { __builtin_amdgcn_s_setprio(1); _Pragma("unroll") for (int m = 0; m < 4; ++m) _Pragma("unroll") for (int n = 0; n < 2; ++n) _Pragma("unroll") for (int k = 0; k < 2; ++k) \
;         acc[ai][bj][m][n] = __builtin_amdgcn_mfma_f32_16x16x32_bf16(Bt[n][k], At[m][k], acc[ai][bj][m][n], 0, 0, 0); __builtin_amdgcn_s_setprio(0); } while (0)
; #define PG8_WAIT_V(n) asm volatile("s_waitcnt vmcnt(" #n ")" ::: "memory")
; #define PG8_WAIT_L(n) asm volatile("s_waitcnt lgkmcnt(" #n ")" ::: "memory")
; #define PG8_BAR __builtin_amdgcn_s_barrier()
; #define PG8_SCHED __builtin_amdgcn_sched_barrier(0)
; template <class Epi, class Sched, bool ALIGN_EPI = false, bool SP2 = false>
; __device__ __forceinline__ void gemm_phase(PG8_LAS unsigned char* lds, const Gemm g, const Sched& S, const Epi& E) {
;     ...
;             const bool last = (t == nt - 2);
;             const char* a1 = cA + (size_t)(t + 1) * kstep;
;             const char* a2 = last ? nA : cA + (size_t)(t + 2) * kstep; const char* b2 = last ? nB : cB + (size_t)(t + 2) * kstep;
;             const char* a3 = a2 + kstep; const char* b3 = b2 + kstep;
;             if (last && has_next) S.a_ready(nxt);
;             if constexpr (SP2) {
;             PG8_LDB(B0, 0, 0); PG8_LDB(B1, 0, 1); PG8_SCHED; PG8_LDA(At, 0, 0); PG8_STAGE(PG8_SA(1, 1), a1 + hstep, voffA);
;             PG8_WAIT_V(8); PG8_WAIT_L(0); PG8_BAR; PG8_MMA(0, 0, At, B0); PG8_MMA(0, 1, At, B1); PG8_BAR; PG8_SCHED;
;             PG8_LDA(At, 0, 1); PG8_STAGE(PG8_SB(0, 0), b2, voffB); PG8_STAGE(PG8_SB(0, 1), b2 + hstep, voffB); PG8_STAGE(PG8_SA(0, 0), a2, voffA);
.LBB0_490:
	ds_read_b128 v[144:147], v161
	ds_read_b128 v[168:171], v161 offset:1024
	ds_read_b128 v[172:175], v161 offset:2048
	ds_read_b128 v[176:179], v161 offset:3072
	ds_read_b128 v[180:183], v163
	ds_read_b128 v[188:191], v163 offset:1024
	ds_read_b128 v[192:195], v163 offset:2048
	ds_read_b128 v[196:199], v163 offset:3072
	s_add_u32 s28, s26, 0xfffc0080
	s_addc_u32 s29, s27, -1
	s_cmp_eq_u32 s78, 12
	s_cselect_b32 s31, s5, s29
	s_cselect_b32 s30, s19, s28
	s_cselect_b32 s29, s17, s77
	s_cselect_b32 s28, s25, s76
	v_lshl_add_u64 v[148:149], s[26:27], 0, v[136:137]
	s_add_i32 m0, s39, 0xc000
	ds_read_b128 v[200:203], v164
	ds_read_b128 v[204:207], v164 offset:1024
	ds_read_b128 v[208:211], v164 offset:2048
	ds_read_b128 v[212:215], v164 offset:3072
	ds_read_b128 v[216:219], v164 offset:4096
	ds_read_b128 v[220:223], v164 offset:5120
	ds_read_b128 v[224:227], v164 offset:6144
	ds_read_b128 v[228:231], v164 offset:7168
	global_load_lds_dwordx4 v[148:149], off
	v_lshl_add_u64 v[148:149], s[26:27], 0, v[138:139]
	s_add_i32 m0, s39, 0xe000
	s_nop 0
	global_load_lds_dwordx4 v[148:149], off
	s_waitcnt vmcnt(8)
	s_waitcnt lgkmcnt(0)
	s_barrier
	s_setprio 1
	s_waitcnt lgkmcnt(0)
	v_mfma_f32_16x16x32_bf16 v[124:127], v[144:147], v[200:203], v[124:127]
	v_mfma_f32_16x16x32_bf16 v[120:123], v[172:175], v[200:203], v[120:123]
	v_mfma_f32_16x16x32_bf16 v[108:111], v[144:147], v[208:211], v[108:111]
	v_mfma_f32_16x16x32_bf16 v[104:107], v[172:175], v[208:211], v[104:107]
	v_mfma_f32_16x16x32_bf16 v[92:95], v[144:147], v[216:219], v[92:95]
	v_mfma_f32_16x16x32_bf16 v[88:91], v[172:175], v[216:219], v[88:91]
	v_mfma_f32_16x16x32_bf16 v[76:79], v[144:147], v[224:227], v[76:79]
	v_mfma_f32_16x16x32_bf16 v[72:75], v[172:175], v[224:227], v[72:75]
	v_mfma_f32_16x16x32_bf16 v[124:127], v[168:171], v[204:207], v[124:127]
	v_mfma_f32_16x16x32_bf16 v[120:123], v[176:179], v[204:207], v[120:123]
	v_mfma_f32_16x16x32_bf16 v[108:111], v[168:171], v[212:215], v[108:111]
	v_mfma_f32_16x16x32_bf16 v[104:107], v[176:179], v[212:215], v[104:107]
	v_mfma_f32_16x16x32_bf16 v[92:95], v[168:171], v[220:223], v[92:95]
	v_mfma_f32_16x16x32_bf16 v[88:91], v[176:179], v[220:223], v[88:91]
	v_mfma_f32_16x16x32_bf16 v[76:79], v[168:171], v[228:231], v[76:79]
	v_mfma_f32_16x16x32_bf16 v[72:75], v[176:179], v[228:231], v[72:75]
	s_setprio 0
	s_setprio 1
	v_mfma_f32_16x16x32_bf16 v[116:119], v[180:183], v[200:203], v[116:119]
	v_mfma_f32_16x16x32_bf16 v[112:115], v[192:195], v[200:203], v[112:115]
	v_mfma_f32_16x16x32_bf16 v[100:103], v[180:183], v[208:211], v[100:103]
	v_mfma_f32_16x16x32_bf16 v[96:99], v[192:195], v[208:211], v[96:99]
	v_mfma_f32_16x16x32_bf16 v[84:87], v[180:183], v[216:219], v[84:87]
	v_mfma_f32_16x16x32_bf16 v[80:83], v[192:195], v[216:219], v[80:83]
	v_mfma_f32_16x16x32_bf16 v[68:71], v[180:183], v[224:227], v[68:71]
	v_mfma_f32_16x16x32_bf16 v[64:67], v[192:195], v[224:227], v[64:67]
	v_mfma_f32_16x16x32_bf16 v[116:119], v[188:191], v[204:207], v[116:119]
	v_mfma_f32_16x16x32_bf16 v[112:115], v[196:199], v[204:207], v[112:115]
	v_mfma_f32_16x16x32_bf16 v[100:103], v[188:191], v[212:215], v[100:103]
	v_mfma_f32_16x16x32_bf16 v[96:99], v[196:199], v[212:215], v[96:99]
	v_mfma_f32_16x16x32_bf16 v[84:87], v[188:191], v[220:223], v[84:87]
	v_mfma_f32_16x16x32_bf16 v[80:83], v[196:199], v[220:223], v[80:83]
	v_mfma_f32_16x16x32_bf16 v[68:71], v[188:191], v[228:231], v[68:71]
	v_mfma_f32_16x16x32_bf16 v[64:67], v[196:199], v[228:231], v[64:67]
	s_setprio 0
	s_barrier
	s_add_i32 s79, s74, s38
	v_lshl_add_u64 v[148:149], s[28:29], 0, v[130:131]
	s_mov_b32 m0, s79
	ds_read_b128 v[200:203], v164 offset:16384
	ds_read_b128 v[204:207], v164 offset:17408
	ds_read_b128 v[208:211], v164 offset:18432
	ds_read_b128 v[212:215], v164 offset:19456
	ds_read_b128 v[216:219], v164 offset:20480
	ds_read_b128 v[220:223], v164 offset:21504
	ds_read_b128 v[224:227], v164 offset:22528
	ds_read_b128 v[228:231], v164 offset:23552
	global_load_lds_dwordx4 v[148:149], off
	s_add_i32 m0, s79, 0x2000
	s_add_u32 s80, s28, 0x40000
	v_lshl_add_u64 v[234:235], s[28:29], 0, v[134:135]
	s_addc_u32 s81, s29, 0
	s_add_i32 s79, s75, s38
	global_load_lds_dwordx4 v[234:235], off
	v_lshl_add_u64 v[236:237], s[80:81], 0, v[130:131]
	s_mov_b32 m0, s79
	v_lshl_add_u64 v[238:239], s[30:31], 0, v[132:133]
	global_load_lds_dwordx4 v[236:237], off
	v_lshl_add_u64 v[236:237], s[80:81], 0, v[134:135]
	s_add_i32 m0, s79, 0x2000
	s_nop 0
	global_load_lds_dwordx4 v[236:237], off
	v_lshl_add_u64 v[236:237], s[30:31], 0, v[128:129]
	s_mov_b32 m0, s39
	s_nop 0
	global_load_lds_dwordx4 v[236:237], off
	s_mov_b32 m0, s42
	s_nop 0
	global_load_lds_dwordx4 v[238:239], off
	s_waitcnt vmcnt(8)
	s_waitcnt lgkmcnt(0)
	s_barrier
; #define PG8_STAGE(bufoff, gbase, voff) do { _Pragma("unroll") for (int _i = 0; _i < 2; ++_i) \
;         __builtin_amdgcn_global_load_lds((const unsigned*)((const char*)(gbase) + (voff)[_i]), (PG8_LAS unsigned*)(lds + (bufoff) + ldsw + _i * 8192), 16, 0, 0); } while (0)
; #define PG8_LDA(dst, b, h) do { _Pragma("unroll") for (int m = 0; m < 4; ++m) _Pragma("unroll") for (int k = 0; k < 2; ++k) dst[m][k] = *(const PG8_LAS bf16x8*)(lds + PG8_SA(b, h) + aoff + m * 2048 + k * 1024); } while (0)
; #define PG8_LDB(dst, b, h) do { _Pragma("unroll") for (int n = 0; n < 2; ++n) _Pragma("unroll") for (int k = 0; k < 2; ++k) dst[n][k] = *(const PG8_LAS bf16x8*)(lds + PG8_SB(b, h) + boff + n * 2048 + k * 1024); } while (0)
; #define PG8_MMA(ai, bj, At, Bt) do { __builtin_amdgcn_s_setprio(1); _Pragma("unroll") for (int m = 0; m < 4; ++m) _Pragma("unroll") for (int n = 0; n < 2; ++n) _Pragma("unroll") for (int k = 0; k < 2; ++k) \
;         acc[ai][bj][m][n] = __builtin_amdgcn_mfma_f32_16x16x32_bf16(Bt[n][k], At[m][k], acc[ai][bj][m][n], 0, 0, 0); __builtin_amdgcn_s_setprio(0); } while (0)
; #define PG8_WAIT_V(n) asm volatile("s_waitcnt vmcnt(" #n ")" ::: "memory")
; #define PG8_WAIT_L(n) asm volatile("s_waitcnt lgkmcnt(" #n ")" ::: "memory")
; #define PG8_BAR __builtin_amdgcn_s_barrier()
; #define PG8_SCHED __builtin_amdgcn_sched_barrier(0)
; template <class Epi, class Sched, bool ALIGN_EPI = false, bool SP2 = false>
; __device__ __forceinline__ void gemm_phase(PG8_LAS unsigned char* lds, const Gemm g, const Sched& S, const Epi& E) {
;     ...
;             PG8_WAIT_V(8); PG8_WAIT_L(0); PG8_BAR; PG8_MMA(1, 0, At, B0); PG8_MMA(1, 1, At, B1); PG8_BAR; PG8_SCHED;
;             PG8_LDB(B0, 1, 0); PG8_LDB(B1, 1, 1); PG8_SCHED; PG8_LDA(At, 1, 0); PG8_STAGE(PG8_SA(0, 1), a2 + hstep, voffA);
;             PG8_WAIT_V(8); PG8_WAIT_L(0); PG8_BAR; PG8_MMA(0, 0, At, B0); PG8_MMA(0, 1, At, B1); PG8_BAR; PG8_SCHED;
	s_setprio 1
	s_waitcnt lgkmcnt(0)
	v_mfma_f32_16x16x32_bf16 v[60:63], v[144:147], v[200:203], v[60:63]
	v_mfma_f32_16x16x32_bf16 v[56:59], v[172:175], v[200:203], v[56:59]
	v_mfma_f32_16x16x32_bf16 v[44:47], v[144:147], v[208:211], v[44:47]
	v_mfma_f32_16x16x32_bf16 v[40:43], v[172:175], v[208:211], v[40:43]
	v_mfma_f32_16x16x32_bf16 v[28:31], v[144:147], v[216:219], v[28:31]
	v_mfma_f32_16x16x32_bf16 v[24:27], v[172:175], v[216:219], v[24:27]
	v_mfma_f32_16x16x32_bf16 v[12:15], v[144:147], v[224:227], v[12:15]
	v_mfma_f32_16x16x32_bf16 v[8:11], v[172:175], v[224:227], v[8:11]
	v_mfma_f32_16x16x32_bf16 v[60:63], v[168:171], v[204:207], v[60:63]
	v_mfma_f32_16x16x32_bf16 v[56:59], v[176:179], v[204:207], v[56:59]
	v_mfma_f32_16x16x32_bf16 v[44:47], v[168:171], v[212:215], v[44:47]
	v_mfma_f32_16x16x32_bf16 v[40:43], v[176:179], v[212:215], v[40:43]
	v_mfma_f32_16x16x32_bf16 v[28:31], v[168:171], v[220:223], v[28:31]
	v_mfma_f32_16x16x32_bf16 v[24:27], v[176:179], v[220:223], v[24:27]
	v_mfma_f32_16x16x32_bf16 v[12:15], v[168:171], v[228:231], v[12:15]
	v_mfma_f32_16x16x32_bf16 v[8:11], v[176:179], v[228:231], v[8:11]
	s_setprio 0
	s_setprio 1
	v_mfma_f32_16x16x32_bf16 v[52:55], v[180:183], v[200:203], v[52:55]
	v_mfma_f32_16x16x32_bf16 v[48:51], v[192:195], v[200:203], v[48:51]
	v_mfma_f32_16x16x32_bf16 v[36:39], v[180:183], v[208:211], v[36:39]
	v_mfma_f32_16x16x32_bf16 v[32:35], v[192:195], v[208:211], v[32:35]
	v_mfma_f32_16x16x32_bf16 v[20:23], v[180:183], v[216:219], v[20:23]
	v_mfma_f32_16x16x32_bf16 v[16:19], v[192:195], v[216:219], v[16:19]
	v_mfma_f32_16x16x32_bf16 v[4:7], v[180:183], v[224:227], v[4:7]
	v_mfma_f32_16x16x32_bf16 v[0:3], v[192:195], v[224:227], v[0:3]
	v_mfma_f32_16x16x32_bf16 v[52:55], v[188:191], v[204:207], v[52:55]
	v_mfma_f32_16x16x32_bf16 v[48:51], v[196:199], v[204:207], v[48:51]
	v_mfma_f32_16x16x32_bf16 v[36:39], v[188:191], v[212:215], v[36:39]
	v_mfma_f32_16x16x32_bf16 v[32:35], v[196:199], v[212:215], v[32:35]
	v_mfma_f32_16x16x32_bf16 v[20:23], v[188:191], v[220:223], v[20:23]
	v_mfma_f32_16x16x32_bf16 v[16:19], v[196:199], v[220:223], v[16:19]
	v_mfma_f32_16x16x32_bf16 v[4:7], v[188:191], v[228:231], v[4:7]
	v_mfma_f32_16x16x32_bf16 v[0:3], v[196:199], v[228:231], v[0:3]
	s_setprio 0
	s_barrier
	s_add_i32 s79, 0, 0x18000
	v_add_u32_e32 v167, s79, v157
	s_add_i32 s80, 0, 0x1c000
	ds_read_b128 v[144:147], v167
	ds_read_b128 v[168:171], v167 offset:1024
	ds_read_b128 v[172:175], v167 offset:2048
	ds_read_b128 v[176:179], v167 offset:3072
	v_add_u32_e32 v167, s80, v157
	ds_read_b128 v[180:183], v167
	ds_read_b128 v[188:191], v167 offset:1024
	ds_read_b128 v[192:195], v167 offset:2048
	ds_read_b128 v[196:199], v167 offset:3072
	s_add_u32 s30, s30, 0x40000
	s_addc_u32 s31, s31, 0
	s_mov_b32 m0, s43
	v_lshl_add_u64 v[240:241], s[30:31], 0, v[128:129]
	ds_read_b128 v[200:203], v164 offset:32768
	ds_read_b128 v[204:207], v164 offset:33792
	ds_read_b128 v[208:211], v164 offset:34816
	ds_read_b128 v[212:215], v164 offset:35840
	ds_read_b128 v[216:219], v164 offset:36864
	ds_read_b128 v[220:223], v164 offset:37888
	ds_read_b128 v[224:227], v164 offset:38912
	ds_read_b128 v[228:231], v164 offset:39936
	global_load_lds_dwordx4 v[240:241], off
	v_lshl_add_u64 v[240:241], s[30:31], 0, v[132:133]
	s_mov_b32 m0, s44
	s_nop 0
	global_load_lds_dwordx4 v[240:241], off
	s_waitcnt vmcnt(8)
	s_waitcnt lgkmcnt(0)
	s_barrier
	s_setprio 1
	s_waitcnt lgkmcnt(0)
	v_mfma_f32_16x16x32_bf16 v[124:127], v[144:147], v[200:203], v[124:127]
	v_mfma_f32_16x16x32_bf16 v[120:123], v[172:175], v[200:203], v[120:123]
	v_mfma_f32_16x16x32_bf16 v[108:111], v[144:147], v[208:211], v[108:111]
	v_mfma_f32_16x16x32_bf16 v[104:107], v[172:175], v[208:211], v[104:107]
	v_mfma_f32_16x16x32_bf16 v[92:95], v[144:147], v[216:219], v[92:95]
	v_mfma_f32_16x16x32_bf16 v[88:91], v[172:175], v[216:219], v[88:91]
	v_mfma_f32_16x16x32_bf16 v[76:79], v[144:147], v[224:227], v[76:79]
	v_mfma_f32_16x16x32_bf16 v[72:75], v[172:175], v[224:227], v[72:75]
	v_mfma_f32_16x16x32_bf16 v[124:127], v[168:171], v[204:207], v[124:127]
	v_mfma_f32_16x16x32_bf16 v[120:123], v[176:179], v[204:207], v[120:123]
	v_mfma_f32_16x16x32_bf16 v[108:111], v[168:171], v[212:215], v[108:111]
	v_mfma_f32_16x16x32_bf16 v[104:107], v[176:179], v[212:215], v[104:107]
	v_mfma_f32_16x16x32_bf16 v[92:95], v[168:171], v[220:223], v[92:95]
	v_mfma_f32_16x16x32_bf16 v[88:91], v[176:179], v[220:223], v[88:91]
	v_mfma_f32_16x16x32_bf16 v[76:79], v[168:171], v[228:231], v[76:79]
	v_mfma_f32_16x16x32_bf16 v[72:75], v[176:179], v[228:231], v[72:75]
	s_setprio 0
	s_setprio 1
	v_mfma_f32_16x16x32_bf16 v[116:119], v[180:183], v[200:203], v[116:119]
	v_mfma_f32_16x16x32_bf16 v[112:115], v[192:195], v[200:203], v[112:115]
	v_mfma_f32_16x16x32_bf16 v[100:103], v[180:183], v[208:211], v[100:103]
	v_mfma_f32_16x16x32_bf16 v[96:99], v[192:195], v[208:211], v[96:99]
	v_mfma_f32_16x16x32_bf16 v[84:87], v[180:183], v[216:219], v[84:87]
	v_mfma_f32_16x16x32_bf16 v[80:83], v[192:195], v[216:219], v[80:83]
	v_mfma_f32_16x16x32_bf16 v[68:71], v[180:183], v[224:227], v[68:71]
	v_mfma_f32_16x16x32_bf16 v[64:67], v[192:195], v[224:227], v[64:67]
	v_mfma_f32_16x16x32_bf16 v[116:119], v[188:191], v[204:207], v[116:119]
	v_mfma_f32_16x16x32_bf16 v[112:115], v[196:199], v[204:207], v[112:115]
	v_mfma_f32_16x16x32_bf16 v[100:103], v[188:191], v[212:215], v[100:103]
	v_mfma_f32_16x16x32_bf16 v[96:99], v[196:199], v[212:215], v[96:99]
	v_mfma_f32_16x16x32_bf16 v[84:87], v[188:191], v[220:223], v[84:87]
	v_mfma_f32_16x16x32_bf16 v[80:83], v[196:199], v[220:223], v[80:83]
	v_mfma_f32_16x16x32_bf16 v[68:71], v[188:191], v[228:231], v[68:71]
	v_mfma_f32_16x16x32_bf16 v[64:67], v[196:199], v[228:231], v[64:67]
	s_setprio 0
	s_barrier
; #define PG8_STAGE(bufoff, gbase, voff) do { _Pragma("unroll") for (int _i = 0; _i < 2; ++_i) \
;         __builtin_amdgcn_global_load_lds((const unsigned*)((const char*)(gbase) + (voff)[_i]), (PG8_LAS unsigned*)(lds + (bufoff) + ldsw + _i * 8192), 16, 0, 0); } while (0)
; #define PG8_LDA(dst, b, h) do { _Pragma("unroll") for (int m = 0; m < 4; ++m) _Pragma("unroll") for (int k = 0; k < 2; ++k) dst[m][k] = *(const PG8_LAS bf16x8*)(lds + PG8_SA(b, h) + aoff + m * 2048 + k * 1024); } while (0)
; #define PG8_MMA(ai, bj, At, Bt) do { __builtin_amdgcn_s_setprio(1); _Pragma("unroll") for (int m = 0; m < 4; ++m) _Pragma("unroll") for (int n = 0; n < 2; ++n) _Pragma("unroll") for (int k = 0; k < 2; ++k) \
;         acc[ai][bj][m][n] = __builtin_amdgcn_mfma_f32_16x16x32_bf16(Bt[n][k], At[m][k], acc[ai][bj][m][n], 0, 0, 0); __builtin_amdgcn_s_setprio(0); } while (0)
; #define PG8_WAIT_V(n) asm volatile("s_waitcnt vmcnt(" #n ")" ::: "memory")
; #define PG8_WAIT_L(n) asm volatile("s_waitcnt lgkmcnt(" #n ")" ::: "memory")
; #define PG8_BAR __builtin_amdgcn_s_barrier()
; #define PG8_SCHED __builtin_amdgcn_sched_barrier(0)
; template <class Epi, class Sched, bool ALIGN_EPI = false, bool SP2 = false>
; __device__ __forceinline__ void gemm_phase(PG8_LAS unsigned char* lds, const Gemm g, const Sched& S, const Epi& E) {
;     ...
;             PG8_LDA(At, 1, 1); PG8_STAGE(PG8_SB(1, 0), b3, voffB); PG8_STAGE(PG8_SB(1, 1), b3 + hstep, voffB); PG8_STAGE(PG8_SA(1, 0), a3, voffA);
;             PG8_WAIT_V(8); PG8_WAIT_L(0); PG8_BAR; PG8_MMA(1, 0, At, B0); PG8_MMA(1, 1, At, B1); PG8_BAR; PG8_SCHED;
;     ...
;         if constexpr (ALIGN_EPI) { if (wr == 0) PG8_BAR; }
	s_add_i32 s30, s79, s38
	v_lshl_add_u64 v[148:149], v[148:149], 0, s[12:13]
	s_mov_b32 m0, s30
	ds_read_b128 v[200:203], v164 offset:49152
	ds_read_b128 v[204:207], v164 offset:50176
	ds_read_b128 v[208:211], v164 offset:51200
	ds_read_b128 v[212:215], v164 offset:52224
	ds_read_b128 v[216:219], v164 offset:53248
	ds_read_b128 v[220:223], v164 offset:54272
	ds_read_b128 v[224:227], v164 offset:55296
	ds_read_b128 v[228:231], v164 offset:56320
	global_load_lds_dwordx4 v[148:149], off
	s_add_i32 m0, s30, 0x2000
	s_add_u32 s28, s28, 0x40080
	v_lshl_add_u64 v[148:149], v[234:235], 0, s[12:13]
	s_addc_u32 s29, s29, 0
	s_add_i32 s30, s80, s38
	global_load_lds_dwordx4 v[148:149], off
	v_lshl_add_u64 v[148:149], s[28:29], 0, v[130:131]
	s_mov_b32 m0, s30
	s_nop 0
	global_load_lds_dwordx4 v[148:149], off
	v_lshl_add_u64 v[148:149], s[28:29], 0, v[134:135]
	s_add_i32 m0, s30, 0x2000
	s_nop 0
	global_load_lds_dwordx4 v[148:149], off
	v_lshl_add_u64 v[148:149], v[236:237], 0, s[12:13]
	s_mov_b32 m0, s50
	s_nop 0
	global_load_lds_dwordx4 v[148:149], off
	v_lshl_add_u64 v[148:149], v[238:239], 0, s[12:13]
	s_mov_b32 m0, s51
	s_nop 0
	global_load_lds_dwordx4 v[148:149], off
	s_waitcnt vmcnt(8)
	s_waitcnt lgkmcnt(0)
	s_barrier
	s_setprio 1
	s_waitcnt lgkmcnt(0)
	v_mfma_f32_16x16x32_bf16 v[60:63], v[144:147], v[200:203], v[60:63]
	v_mfma_f32_16x16x32_bf16 v[56:59], v[172:175], v[200:203], v[56:59]
	v_mfma_f32_16x16x32_bf16 v[44:47], v[144:147], v[208:211], v[44:47]
	v_mfma_f32_16x16x32_bf16 v[40:43], v[172:175], v[208:211], v[40:43]
	v_mfma_f32_16x16x32_bf16 v[28:31], v[144:147], v[216:219], v[28:31]
	v_mfma_f32_16x16x32_bf16 v[24:27], v[172:175], v[216:219], v[24:27]
	v_mfma_f32_16x16x32_bf16 v[12:15], v[144:147], v[224:227], v[12:15]
	v_mfma_f32_16x16x32_bf16 v[8:11], v[172:175], v[224:227], v[8:11]
	v_mfma_f32_16x16x32_bf16 v[60:63], v[168:171], v[204:207], v[60:63]
	v_mfma_f32_16x16x32_bf16 v[56:59], v[176:179], v[204:207], v[56:59]
	v_mfma_f32_16x16x32_bf16 v[44:47], v[168:171], v[212:215], v[44:47]
	v_mfma_f32_16x16x32_bf16 v[40:43], v[176:179], v[212:215], v[40:43]
	v_mfma_f32_16x16x32_bf16 v[28:31], v[168:171], v[220:223], v[28:31]
	v_mfma_f32_16x16x32_bf16 v[24:27], v[176:179], v[220:223], v[24:27]
	v_mfma_f32_16x16x32_bf16 v[12:15], v[168:171], v[228:231], v[12:15]
	v_mfma_f32_16x16x32_bf16 v[8:11], v[176:179], v[228:231], v[8:11]
	s_setprio 0
	s_setprio 1
	v_mfma_f32_16x16x32_bf16 v[52:55], v[180:183], v[200:203], v[52:55]
	v_mfma_f32_16x16x32_bf16 v[48:51], v[192:195], v[200:203], v[48:51]
	v_mfma_f32_16x16x32_bf16 v[36:39], v[180:183], v[208:211], v[36:39]
	v_mfma_f32_16x16x32_bf16 v[32:35], v[192:195], v[208:211], v[32:35]
	v_mfma_f32_16x16x32_bf16 v[20:23], v[180:183], v[216:219], v[20:23]
	v_mfma_f32_16x16x32_bf16 v[16:19], v[192:195], v[216:219], v[16:19]
	v_mfma_f32_16x16x32_bf16 v[4:7], v[180:183], v[224:227], v[4:7]
	v_mfma_f32_16x16x32_bf16 v[0:3], v[192:195], v[224:227], v[0:3]
	v_mfma_f32_16x16x32_bf16 v[52:55], v[188:191], v[204:207], v[52:55]
	v_mfma_f32_16x16x32_bf16 v[48:51], v[196:199], v[204:207], v[48:51]
	v_mfma_f32_16x16x32_bf16 v[36:39], v[188:191], v[212:215], v[36:39]
	v_mfma_f32_16x16x32_bf16 v[32:35], v[196:199], v[212:215], v[32:35]
	v_mfma_f32_16x16x32_bf16 v[20:23], v[188:191], v[220:223], v[20:23]
	v_mfma_f32_16x16x32_bf16 v[16:19], v[196:199], v[220:223], v[16:19]
	v_mfma_f32_16x16x32_bf16 v[4:7], v[188:191], v[228:231], v[4:7]
	v_mfma_f32_16x16x32_bf16 v[0:3], v[196:199], v[228:231], v[0:3]
	s_setprio 0
	s_add_i32 s78, s78, 2
	s_add_u32 s26, s26, 0x100
	s_addc_u32 s27, s27, 0
	s_add_u32 s76, s76, 0x100
	s_addc_u32 s77, s77, 0
	s_cmp_gt_u32 s78, 13
	s_barrier
	s_cbranch_scc0 .LBB0_490
	s_and_b64 vcc, exec, s[14:15]
	s_cbranch_vccz .LBB0_493
	s_barrier

; #define PG8_STAGE(bufoff, gbase, voff) do { _Pragma("unroll") for (int _i = 0; _i < 2; ++_i) \
;         __builtin_amdgcn_global_load_lds((const unsigned*)((const char*)(gbase) + (voff)[_i]), (PG8_LAS unsigned*)(lds + (bufoff) + ldsw + _i * 8192), 16, 0, 0); } while (0)
; #define PG8_LDA(dst, b, h) do { _Pragma("unroll") for (int m = 0; m < 4; ++m) _Pragma("unroll") for (int k = 0; k < 2; ++k) dst[m][k] = *(const PG8_LAS bf16x8*)(lds + PG8_SA(b, h) + aoff + m * 2048 + k * 1024); } while (0)
; #define PG8_LDB(dst, b, h) do { _Pragma("unroll") for (int n = 0; n < 2; ++n) _Pragma("unroll") for (int k = 0; k < 2; ++k) dst[n][k] = *(const PG8_LAS bf16x8*)(lds + PG8_SB(b, h) + boff + n * 2048 + k * 1024); } while (0)
; #define PG8_MMA(ai, bj, At, Bt) do { __builtin_amdgcn_s_setprio(1); _Pragma("unroll") for (int m = 0; m < 4; ++m) _Pragma("unroll") for (int n = 0; n < 2; ++n) _Pragma("unroll") for (int k = 0; k < 2; ++k) \
;         acc[ai][bj][m][n] = __builtin_amdgcn_mfma_f32_16x16x32_bf16(Bt[n][k], At[m][k], acc[ai][bj][m][n], 0, 0, 0); __builtin_amdgcn_s_setprio(0); } while (0)
; #define PG8_WAIT_V(n) asm volatile("s_waitcnt vmcnt(" #n ")" ::: "memory")
; #define PG8_WAIT_L(n) asm volatile("s_waitcnt lgkmcnt(" #n ")" ::: "memory")
; #define PG8_BAR __builtin_amdgcn_s_barrier()
; #define PG8_SCHED __builtin_amdgcn_sched_barrier(0)
; template <class Epi, class Sched, bool ALIGN_EPI = false, bool SP2 = false>
; __device__ __forceinline__ void gemm_phase(PG8_LAS unsigned char* lds, const Gemm g, const Sched& S, const Epi& E) {
;     ...
;             const bool last = (t == nt - 2);
;             const char* a1 = cA + (size_t)(t + 1) * kstep;
;             const char* a2 = last ? nA : cA + (size_t)(t + 2) * kstep; const char* b2 = last ? nB : cB + (size_t)(t + 2) * kstep;
;             const char* a3 = a2 + kstep; const char* b3 = b2 + kstep;
;             if (last && has_next) S.a_ready(nxt);
;             if constexpr (SP2) {
;             PG8_LDB(B0, 0, 0); PG8_LDB(B1, 0, 1); PG8_SCHED; PG8_LDA(At, 0, 0); PG8_STAGE(PG8_SA(1, 1), a1 + hstep, voffA);
;             PG8_WAIT_V(8); PG8_WAIT_L(0); PG8_BAR; PG8_MMA(0, 0, At, B0); PG8_MMA(0, 1, At, B1); PG8_BAR; PG8_SCHED;
;             PG8_LDA(At, 0, 1); PG8_STAGE(PG8_SB(0, 0), b2, voffB); PG8_STAGE(PG8_SB(0, 1), b2 + hstep, voffB); PG8_STAGE(PG8_SA(0, 0), a2, voffA);
.LBB0_576:
	ds_read_b128 v[146:149], v167
	ds_read_b128 v[150:153], v167 offset:1024
	ds_read_b128 v[154:157], v167 offset:2048
	ds_read_b128 v[158:161], v167 offset:3072
	ds_read_b128 v[172:175], v168
	ds_read_b128 v[176:179], v168 offset:1024
	ds_read_b128 v[180:183], v168 offset:2048
	ds_read_b128 v[188:191], v168 offset:3072
	s_add_u32 s22, s20, 0xfffc0080
	s_addc_u32 s23, s21, -1
	s_cmp_eq_u32 s70, 12
	s_cselect_b32 s25, s13, s23
	s_cselect_b32 s24, s50, s22
	s_cselect_b32 s23, s11, s69
	s_cselect_b32 s22, s51, s58
	v_lshl_add_u64 v[224:225], s[20:21], 0, v[138:139]
	s_add_i32 m0, s19, 0xc000
	ds_read_b128 v[192:195], v169
	ds_read_b128 v[196:199], v169 offset:1024
	ds_read_b128 v[200:203], v169 offset:2048
	ds_read_b128 v[204:207], v169 offset:3072
	ds_read_b128 v[208:211], v169 offset:4096
	ds_read_b128 v[212:215], v169 offset:5120
	ds_read_b128 v[216:219], v169 offset:6144
	ds_read_b128 v[220:223], v169 offset:7168
	global_load_lds_dwordx4 v[224:225], off
	v_lshl_add_u64 v[224:225], s[20:21], 0, v[140:141]
	s_add_i32 m0, s19, 0xe000
	s_nop 0
	global_load_lds_dwordx4 v[224:225], off
	s_waitcnt vmcnt(8)
	s_waitcnt lgkmcnt(0)
	s_barrier
	s_setprio 1
	s_waitcnt lgkmcnt(0)
	v_mfma_f32_16x16x32_bf16 v[124:127], v[146:149], v[192:195], v[124:127]
	v_mfma_f32_16x16x32_bf16 v[120:123], v[154:157], v[192:195], v[120:123]
	v_mfma_f32_16x16x32_bf16 v[116:119], v[146:149], v[200:203], v[116:119]
	v_mfma_f32_16x16x32_bf16 v[112:115], v[154:157], v[200:203], v[112:115]
	v_mfma_f32_16x16x32_bf16 v[92:95], v[146:149], v[208:211], v[92:95]
	v_mfma_f32_16x16x32_bf16 v[88:91], v[154:157], v[208:211], v[88:91]
	v_mfma_f32_16x16x32_bf16 v[76:79], v[146:149], v[216:219], v[76:79]
	v_mfma_f32_16x16x32_bf16 v[72:75], v[154:157], v[216:219], v[72:75]
	v_mfma_f32_16x16x32_bf16 v[124:127], v[150:153], v[196:199], v[124:127]
	v_mfma_f32_16x16x32_bf16 v[120:123], v[158:161], v[196:199], v[120:123]
	v_mfma_f32_16x16x32_bf16 v[116:119], v[150:153], v[204:207], v[116:119]
	v_mfma_f32_16x16x32_bf16 v[112:115], v[158:161], v[204:207], v[112:115]
	v_mfma_f32_16x16x32_bf16 v[92:95], v[150:153], v[212:215], v[92:95]
	v_mfma_f32_16x16x32_bf16 v[88:91], v[158:161], v[212:215], v[88:91]
	v_mfma_f32_16x16x32_bf16 v[76:79], v[150:153], v[220:223], v[76:79]
	v_mfma_f32_16x16x32_bf16 v[72:75], v[158:161], v[220:223], v[72:75]
	s_setprio 0
	s_setprio 1
	v_mfma_f32_16x16x32_bf16 v[108:111], v[172:175], v[192:195], v[108:111]
	v_mfma_f32_16x16x32_bf16 v[104:107], v[180:183], v[192:195], v[104:107]
	v_mfma_f32_16x16x32_bf16 v[100:103], v[172:175], v[200:203], v[100:103]
	v_mfma_f32_16x16x32_bf16 v[96:99], v[180:183], v[200:203], v[96:99]
	v_mfma_f32_16x16x32_bf16 v[84:87], v[172:175], v[208:211], v[84:87]
	v_mfma_f32_16x16x32_bf16 v[80:83], v[180:183], v[208:211], v[80:83]
	v_mfma_f32_16x16x32_bf16 v[68:71], v[172:175], v[216:219], v[68:71]
	v_mfma_f32_16x16x32_bf16 v[64:67], v[180:183], v[216:219], v[64:67]
	v_mfma_f32_16x16x32_bf16 v[108:111], v[176:179], v[196:199], v[108:111]
	v_mfma_f32_16x16x32_bf16 v[104:107], v[188:191], v[196:199], v[104:107]
	v_mfma_f32_16x16x32_bf16 v[100:103], v[176:179], v[204:207], v[100:103]
	v_mfma_f32_16x16x32_bf16 v[96:99], v[188:191], v[204:207], v[96:99]
	v_mfma_f32_16x16x32_bf16 v[84:87], v[176:179], v[212:215], v[84:87]
	v_mfma_f32_16x16x32_bf16 v[80:83], v[188:191], v[212:215], v[80:83]
	v_mfma_f32_16x16x32_bf16 v[68:71], v[176:179], v[220:223], v[68:71]
	v_mfma_f32_16x16x32_bf16 v[64:67], v[188:191], v[220:223], v[64:67]
	s_setprio 0
	s_barrier
	s_add_i32 s71, s47, s30
	v_lshl_add_u64 v[224:225], s[22:23], 0, v[130:131]
	s_mov_b32 m0, s71
	ds_read_b128 v[192:195], v169 offset:16384
	ds_read_b128 v[196:199], v169 offset:17408
	ds_read_b128 v[200:203], v169 offset:18432
	ds_read_b128 v[204:207], v169 offset:19456
	ds_read_b128 v[208:211], v169 offset:20480
	ds_read_b128 v[212:215], v169 offset:21504
	ds_read_b128 v[216:219], v169 offset:22528
	ds_read_b128 v[220:223], v169 offset:23552
	global_load_lds_dwordx4 v[224:225], off
	s_add_i32 m0, s71, 0x2000
	s_add_u32 s72, s22, 0x40000
	v_lshl_add_u64 v[226:227], s[22:23], 0, v[134:135]
	s_addc_u32 s73, s23, 0
	s_add_i32 s71, s48, s30
	global_load_lds_dwordx4 v[226:227], off
	v_lshl_add_u64 v[228:229], s[72:73], 0, v[130:131]
	s_mov_b32 m0, s71
	v_lshl_add_u64 v[230:231], s[24:25], 0, v[132:133]
	global_load_lds_dwordx4 v[228:229], off
	v_lshl_add_u64 v[228:229], s[72:73], 0, v[134:135]
	s_add_i32 m0, s71, 0x2000
	s_nop 0
	global_load_lds_dwordx4 v[228:229], off
	v_lshl_add_u64 v[228:229], s[24:25], 0, v[128:129]
	s_mov_b32 m0, s19
	s_nop 0
	global_load_lds_dwordx4 v[228:229], off
	s_mov_b32 m0, s31
	s_nop 0
	global_load_lds_dwordx4 v[230:231], off
	s_waitcnt vmcnt(8)
	s_waitcnt lgkmcnt(0)
	s_barrier
; #define PG8_STAGE(bufoff, gbase, voff) do { _Pragma("unroll") for (int _i = 0; _i < 2; ++_i) \
;         __builtin_amdgcn_global_load_lds((const unsigned*)((const char*)(gbase) + (voff)[_i]), (PG8_LAS unsigned*)(lds + (bufoff) + ldsw + _i * 8192), 16, 0, 0); } while (0)
; #define PG8_LDA(dst, b, h) do { _Pragma("unroll") for (int m = 0; m < 4; ++m) _Pragma("unroll") for (int k = 0; k < 2; ++k) dst[m][k] = *(const PG8_LAS bf16x8*)(lds + PG8_SA(b, h) + aoff + m * 2048 + k * 1024); } while (0)
; #define PG8_LDB(dst, b, h) do { _Pragma("unroll") for (int n = 0; n < 2; ++n) _Pragma("unroll") for (int k = 0; k < 2; ++k) dst[n][k] = *(const PG8_LAS bf16x8*)(lds + PG8_SB(b, h) + boff + n * 2048 + k * 1024); } while (0)
; #define PG8_MMA(ai, bj, At, Bt) do { __builtin_amdgcn_s_setprio(1); _Pragma("unroll") for (int m = 0; m < 4; ++m) _Pragma("unroll") for (int n = 0; n < 2; ++n) _Pragma("unroll") for (int k = 0; k < 2; ++k) \
;         acc[ai][bj][m][n] = __builtin_amdgcn_mfma_f32_16x16x32_bf16(Bt[n][k], At[m][k], acc[ai][bj][m][n], 0, 0, 0); __builtin_amdgcn_s_setprio(0); } while (0)
; #define PG8_WAIT_V(n) asm volatile("s_waitcnt vmcnt(" #n ")" ::: "memory")
; #define PG8_WAIT_L(n) asm volatile("s_waitcnt lgkmcnt(" #n ")" ::: "memory")
; #define PG8_BAR __builtin_amdgcn_s_barrier()
; #define PG8_SCHED __builtin_amdgcn_sched_barrier(0)
; template <class Epi, class Sched, bool ALIGN_EPI = false, bool SP2 = false>
; __device__ __forceinline__ void gemm_phase(PG8_LAS unsigned char* lds, const Gemm g, const Sched& S, const Epi& E) {
;     ...
;             PG8_WAIT_V(8); PG8_WAIT_L(0); PG8_BAR; PG8_MMA(1, 0, At, B0); PG8_MMA(1, 1, At, B1); PG8_BAR; PG8_SCHED;
;             PG8_LDB(B0, 1, 0); PG8_LDB(B1, 1, 1); PG8_SCHED; PG8_LDA(At, 1, 0); PG8_STAGE(PG8_SA(0, 1), a2 + hstep, voffA);
;             PG8_WAIT_V(8); PG8_WAIT_L(0); PG8_BAR; PG8_MMA(0, 0, At, B0); PG8_MMA(0, 1, At, B1); PG8_BAR; PG8_SCHED;
	s_setprio 1
	s_waitcnt lgkmcnt(0)
	v_mfma_f32_16x16x32_bf16 v[60:63], v[146:149], v[192:195], v[60:63]
	v_mfma_f32_16x16x32_bf16 v[56:59], v[154:157], v[192:195], v[56:59]
	v_mfma_f32_16x16x32_bf16 v[44:47], v[146:149], v[200:203], v[44:47]
	v_mfma_f32_16x16x32_bf16 v[40:43], v[154:157], v[200:203], v[40:43]
	v_mfma_f32_16x16x32_bf16 v[28:31], v[146:149], v[208:211], v[28:31]
	v_mfma_f32_16x16x32_bf16 v[24:27], v[154:157], v[208:211], v[24:27]
	v_mfma_f32_16x16x32_bf16 v[12:15], v[146:149], v[216:219], v[12:15]
	v_mfma_f32_16x16x32_bf16 v[8:11], v[154:157], v[216:219], v[8:11]
	v_mfma_f32_16x16x32_bf16 v[60:63], v[150:153], v[196:199], v[60:63]
	v_mfma_f32_16x16x32_bf16 v[56:59], v[158:161], v[196:199], v[56:59]
	v_mfma_f32_16x16x32_bf16 v[44:47], v[150:153], v[204:207], v[44:47]
	v_mfma_f32_16x16x32_bf16 v[40:43], v[158:161], v[204:207], v[40:43]
	v_mfma_f32_16x16x32_bf16 v[28:31], v[150:153], v[212:215], v[28:31]
	v_mfma_f32_16x16x32_bf16 v[24:27], v[158:161], v[212:215], v[24:27]
	v_mfma_f32_16x16x32_bf16 v[12:15], v[150:153], v[220:223], v[12:15]
	v_mfma_f32_16x16x32_bf16 v[8:11], v[158:161], v[220:223], v[8:11]
	s_setprio 0
	s_setprio 1
	v_mfma_f32_16x16x32_bf16 v[52:55], v[172:175], v[192:195], v[52:55]
	v_mfma_f32_16x16x32_bf16 v[48:51], v[180:183], v[192:195], v[48:51]
	v_mfma_f32_16x16x32_bf16 v[36:39], v[172:175], v[200:203], v[36:39]
	v_mfma_f32_16x16x32_bf16 v[32:35], v[180:183], v[200:203], v[32:35]
	v_mfma_f32_16x16x32_bf16 v[20:23], v[172:175], v[208:211], v[20:23]
	v_mfma_f32_16x16x32_bf16 v[16:19], v[180:183], v[208:211], v[16:19]
	v_mfma_f32_16x16x32_bf16 v[4:7], v[172:175], v[216:219], v[4:7]
	v_mfma_f32_16x16x32_bf16 v[0:3], v[180:183], v[216:219], v[0:3]
	v_mfma_f32_16x16x32_bf16 v[52:55], v[176:179], v[196:199], v[52:55]
	v_mfma_f32_16x16x32_bf16 v[48:51], v[188:191], v[196:199], v[48:51]
	v_mfma_f32_16x16x32_bf16 v[36:39], v[176:179], v[204:207], v[36:39]
	v_mfma_f32_16x16x32_bf16 v[32:35], v[188:191], v[204:207], v[32:35]
	v_mfma_f32_16x16x32_bf16 v[20:23], v[176:179], v[212:215], v[20:23]
	v_mfma_f32_16x16x32_bf16 v[16:19], v[188:191], v[212:215], v[16:19]
	v_mfma_f32_16x16x32_bf16 v[4:7], v[176:179], v[220:223], v[4:7]
	v_mfma_f32_16x16x32_bf16 v[0:3], v[188:191], v[220:223], v[0:3]
	s_setprio 0
	s_barrier
	s_add_i32 s71, 0, 0x18000
	s_add_i32 s72, 0, 0x1c000
	v_add_u32_e32 v158, s71, v164
	v_add_u32_e32 v171, s72, v164
	ds_read_b128 v[146:149], v158
	ds_read_b128 v[150:153], v158 offset:1024
	ds_read_b128 v[154:157], v158 offset:2048
	ds_read_b128 v[158:161], v158 offset:3072
	ds_read_b128 v[172:175], v171
	ds_read_b128 v[176:179], v171 offset:1024
	ds_read_b128 v[180:183], v171 offset:2048
	ds_read_b128 v[188:191], v171 offset:3072
	s_add_u32 s24, s24, 0x40000
	s_addc_u32 s25, s25, 0
	s_mov_b32 m0, s36
	v_lshl_add_u64 v[234:235], s[24:25], 0, v[128:129]
	ds_read_b128 v[192:195], v169 offset:32768
	ds_read_b128 v[196:199], v169 offset:33792
	ds_read_b128 v[200:203], v169 offset:34816
	ds_read_b128 v[204:207], v169 offset:35840
	ds_read_b128 v[208:211], v169 offset:36864
	ds_read_b128 v[212:215], v169 offset:37888
	ds_read_b128 v[216:219], v169 offset:38912
	ds_read_b128 v[220:223], v169 offset:39936
	global_load_lds_dwordx4 v[234:235], off
	v_lshl_add_u64 v[234:235], s[24:25], 0, v[132:133]
	s_mov_b32 m0, s37
	s_nop 0
	global_load_lds_dwordx4 v[234:235], off
	s_waitcnt vmcnt(8)
	s_waitcnt lgkmcnt(0)
	s_barrier
	s_setprio 1
	s_waitcnt lgkmcnt(0)
	v_mfma_f32_16x16x32_bf16 v[124:127], v[146:149], v[192:195], v[124:127]
	v_mfma_f32_16x16x32_bf16 v[120:123], v[154:157], v[192:195], v[120:123]
	v_mfma_f32_16x16x32_bf16 v[116:119], v[146:149], v[200:203], v[116:119]
	v_mfma_f32_16x16x32_bf16 v[112:115], v[154:157], v[200:203], v[112:115]
	v_mfma_f32_16x16x32_bf16 v[92:95], v[146:149], v[208:211], v[92:95]
	v_mfma_f32_16x16x32_bf16 v[88:91], v[154:157], v[208:211], v[88:91]
	v_mfma_f32_16x16x32_bf16 v[76:79], v[146:149], v[216:219], v[76:79]
	v_mfma_f32_16x16x32_bf16 v[72:75], v[154:157], v[216:219], v[72:75]
	v_mfma_f32_16x16x32_bf16 v[124:127], v[150:153], v[196:199], v[124:127]
	v_mfma_f32_16x16x32_bf16 v[120:123], v[158:161], v[196:199], v[120:123]
	v_mfma_f32_16x16x32_bf16 v[116:119], v[150:153], v[204:207], v[116:119]
	v_mfma_f32_16x16x32_bf16 v[112:115], v[158:161], v[204:207], v[112:115]
	v_mfma_f32_16x16x32_bf16 v[92:95], v[150:153], v[212:215], v[92:95]
	v_mfma_f32_16x16x32_bf16 v[88:91], v[158:161], v[212:215], v[88:91]
	v_mfma_f32_16x16x32_bf16 v[76:79], v[150:153], v[220:223], v[76:79]
	v_mfma_f32_16x16x32_bf16 v[72:75], v[158:161], v[220:223], v[72:75]
	s_setprio 0
	s_setprio 1
	v_mfma_f32_16x16x32_bf16 v[108:111], v[172:175], v[192:195], v[108:111]
	v_mfma_f32_16x16x32_bf16 v[104:107], v[180:183], v[192:195], v[104:107]
	v_mfma_f32_16x16x32_bf16 v[100:103], v[172:175], v[200:203], v[100:103]
	v_mfma_f32_16x16x32_bf16 v[96:99], v[180:183], v[200:203], v[96:99]
	v_mfma_f32_16x16x32_bf16 v[84:87], v[172:175], v[208:211], v[84:87]
	v_mfma_f32_16x16x32_bf16 v[80:83], v[180:183], v[208:211], v[80:83]
	v_mfma_f32_16x16x32_bf16 v[68:71], v[172:175], v[216:219], v[68:71]
	v_mfma_f32_16x16x32_bf16 v[64:67], v[180:183], v[216:219], v[64:67]
	v_mfma_f32_16x16x32_bf16 v[108:111], v[176:179], v[196:199], v[108:111]
	v_mfma_f32_16x16x32_bf16 v[104:107], v[188:191], v[196:199], v[104:107]
	v_mfma_f32_16x16x32_bf16 v[100:103], v[176:179], v[204:207], v[100:103]
	v_mfma_f32_16x16x32_bf16 v[96:99], v[188:191], v[204:207], v[96:99]
	v_mfma_f32_16x16x32_bf16 v[84:87], v[176:179], v[212:215], v[84:87]
	v_mfma_f32_16x16x32_bf16 v[80:83], v[188:191], v[212:215], v[80:83]
	v_mfma_f32_16x16x32_bf16 v[68:71], v[176:179], v[220:223], v[68:71]
	v_mfma_f32_16x16x32_bf16 v[64:67], v[188:191], v[220:223], v[64:67]
	s_setprio 0
	s_barrier
; #define PG8_STAGE(bufoff, gbase, voff) do { _Pragma("unroll") for (int _i = 0; _i < 2; ++_i) \
;         __builtin_amdgcn_global_load_lds((const unsigned*)((const char*)(gbase) + (voff)[_i]), (PG8_LAS unsigned*)(lds + (bufoff) + ldsw + _i * 8192), 16, 0, 0); } while (0)
; #define PG8_LDA(dst, b, h) do { _Pragma("unroll") for (int m = 0; m < 4; ++m) _Pragma("unroll") for (int k = 0; k < 2; ++k) dst[m][k] = *(const PG8_LAS bf16x8*)(lds + PG8_SA(b, h) + aoff + m * 2048 + k * 1024); } while (0)
; #define PG8_WAIT_V(n) asm volatile("s_waitcnt vmcnt(" #n ")" ::: "memory")
; #define PG8_WAIT_L(n) asm volatile("s_waitcnt lgkmcnt(" #n ")" ::: "memory")
; #define PG8_BAR __builtin_amdgcn_s_barrier()
;     __device__ __forceinline__ void operator()(const f32x4 (&acc)[2][2][4][2], const Unit& u, int wr, int wc, int fr, int fq) const {
;         const int row0 = u.pm * BM + wr * 64 + fr, col0 = u.pn * BM + wc * 32 + 8 * fq;
;         f32x4 cs[2][2];
; #pragma unroll
;         for (int bj = 0; bj < 2; ++bj)
; #pragma unroll
;             for (int n = 0; n < 2; ++n) { const f32x4 q = *(const f32x4*)(ssq + col0 + bj * HALF + 4 * n);
; #pragma unroll
;                 for (int e = 0; e < 4; ++e) cs[bj][n][e] = __builtin_amdgcn_rsqf(q[e] * (1.0f / 1024.0f) + 1e-6f); }
; #pragma unroll
;         for (int ai = 0; ai < 2; ++ai)
; #pragma unroll
;             for (int m = 0; m < 4; ++m) { const int row = row0 + ai * HALF + m * 16, h = row >> 6, d = row & 63, dt = d >> 5, r = d & 31;
; #pragma unroll
;                 for (int bj = 0; bj < 2; ++bj) { const int col = col0 + bj * HALF, b = col >> 12, tl = col & 4095, kt = tl >> 5, k0 = tl & 31, s = k0 >> 4, half = (k0 >> 3) & 1, bh = b * 16 + h;
;                     const f32x4 v0 = acc[ai][bj][m][0] * cs[bj][0], v1 = acc[ai][bj][m][1] * cs[bj][1];
;                     bf16_t* p = VF + (((size_t)((((bh * 128 + kt) * 2 + dt) * 2 + s) * 64 + r)) << 3) + 4 * half;
; template <class Epi, class Sched, bool ALIGN_EPI = false, bool SP2 = false>
; __device__ __forceinline__ void gemm_phase(PG8_LAS unsigned char* lds, const Gemm g, const Sched& S, const Epi& E) {
;     ...
;             PG8_LDA(At, 1, 1); PG8_STAGE(PG8_SB(1, 0), b3, voffB); PG8_STAGE(PG8_SB(1, 1), b3 + hstep, voffB); PG8_STAGE(PG8_SA(1, 0), a3, voffA);
;             PG8_WAIT_V(8); PG8_WAIT_L(0); PG8_BAR; PG8_MMA(1, 0, At, B0); PG8_MMA(1, 1, At, B1); PG8_BAR; PG8_SCHED;
	s_add_i32 s24, s71, s30
	v_lshl_add_u64 v[224:225], v[224:225], 0, s[4:5]
	s_mov_b32 m0, s24
	ds_read_b128 v[192:195], v169 offset:49152
	ds_read_b128 v[196:199], v169 offset:50176
	ds_read_b128 v[200:203], v169 offset:51200
	ds_read_b128 v[204:207], v169 offset:52224
	ds_read_b128 v[208:211], v169 offset:53248
	ds_read_b128 v[212:215], v169 offset:54272
	ds_read_b128 v[216:219], v169 offset:55296
	ds_read_b128 v[220:223], v169 offset:56320
	global_load_lds_dwordx4 v[224:225], off
	s_add_i32 m0, s24, 0x2000
	s_add_u32 s22, s22, 0x40080
	v_lshl_add_u64 v[224:225], v[226:227], 0, s[4:5]
	s_addc_u32 s23, s23, 0
	s_add_i32 s24, s72, s30
	global_load_lds_dwordx4 v[224:225], off
	v_lshl_add_u64 v[224:225], s[22:23], 0, v[130:131]
	s_mov_b32 m0, s24
	s_nop 0
	global_load_lds_dwordx4 v[224:225], off
	v_lshl_add_u64 v[224:225], s[22:23], 0, v[134:135]
	s_add_i32 m0, s24, 0x2000
	s_nop 0
	global_load_lds_dwordx4 v[224:225], off
	v_lshl_add_u64 v[224:225], v[228:229], 0, s[4:5]
	s_mov_b32 m0, s43
	s_nop 0
	global_load_lds_dwordx4 v[224:225], off
	v_lshl_add_u64 v[224:225], v[230:231], 0, s[4:5]
	s_mov_b32 m0, s44
	s_nop 0
	global_load_lds_dwordx4 v[224:225], off
	s_waitcnt vmcnt(8)
	s_waitcnt lgkmcnt(0)
	s_barrier
	s_setprio 1
	s_waitcnt lgkmcnt(0)
	v_mfma_f32_16x16x32_bf16 v[60:63], v[146:149], v[192:195], v[60:63]
	v_mfma_f32_16x16x32_bf16 v[56:59], v[154:157], v[192:195], v[56:59]
	v_mfma_f32_16x16x32_bf16 v[44:47], v[146:149], v[200:203], v[44:47]
	v_mfma_f32_16x16x32_bf16 v[40:43], v[154:157], v[200:203], v[40:43]
	v_mfma_f32_16x16x32_bf16 v[28:31], v[146:149], v[208:211], v[28:31]
	v_mfma_f32_16x16x32_bf16 v[24:27], v[154:157], v[208:211], v[24:27]
	v_mfma_f32_16x16x32_bf16 v[12:15], v[146:149], v[216:219], v[12:15]
	v_mfma_f32_16x16x32_bf16 v[8:11], v[154:157], v[216:219], v[8:11]
	v_mfma_f32_16x16x32_bf16 v[60:63], v[150:153], v[196:199], v[60:63]
	v_mfma_f32_16x16x32_bf16 v[56:59], v[158:161], v[196:199], v[56:59]
	v_mfma_f32_16x16x32_bf16 v[44:47], v[150:153], v[204:207], v[44:47]
	v_mfma_f32_16x16x32_bf16 v[40:43], v[158:161], v[204:207], v[40:43]
	v_mfma_f32_16x16x32_bf16 v[28:31], v[150:153], v[212:215], v[28:31]
	v_mfma_f32_16x16x32_bf16 v[24:27], v[158:161], v[212:215], v[24:27]
	v_mfma_f32_16x16x32_bf16 v[12:15], v[150:153], v[220:223], v[12:15]
	v_mfma_f32_16x16x32_bf16 v[8:11], v[158:161], v[220:223], v[8:11]
	s_setprio 0
	s_setprio 1
	v_mfma_f32_16x16x32_bf16 v[52:55], v[172:175], v[192:195], v[52:55]
	v_mfma_f32_16x16x32_bf16 v[48:51], v[180:183], v[192:195], v[48:51]
	v_mfma_f32_16x16x32_bf16 v[36:39], v[172:175], v[200:203], v[36:39]
	v_mfma_f32_16x16x32_bf16 v[32:35], v[180:183], v[200:203], v[32:35]
	v_mfma_f32_16x16x32_bf16 v[20:23], v[172:175], v[208:211], v[20:23]
	v_mfma_f32_16x16x32_bf16 v[16:19], v[180:183], v[208:211], v[16:19]
	v_mfma_f32_16x16x32_bf16 v[4:7], v[172:175], v[216:219], v[4:7]
	v_mfma_f32_16x16x32_bf16 v[0:3], v[180:183], v[216:219], v[0:3]
	v_mfma_f32_16x16x32_bf16 v[52:55], v[176:179], v[196:199], v[52:55]
	v_mfma_f32_16x16x32_bf16 v[48:51], v[188:191], v[196:199], v[48:51]
	v_mfma_f32_16x16x32_bf16 v[36:39], v[176:179], v[204:207], v[36:39]
	v_mfma_f32_16x16x32_bf16 v[32:35], v[188:191], v[204:207], v[32:35]
	v_mfma_f32_16x16x32_bf16 v[20:23], v[176:179], v[212:215], v[20:23]
	v_mfma_f32_16x16x32_bf16 v[16:19], v[188:191], v[212:215], v[16:19]
	v_mfma_f32_16x16x32_bf16 v[4:7], v[176:179], v[220:223], v[4:7]
	v_mfma_f32_16x16x32_bf16 v[0:3], v[188:191], v[220:223], v[0:3]
	s_setprio 0
	s_add_i32 s70, s70, 2
	s_add_u32 s20, s20, 0x100
	s_addc_u32 s21, s21, 0
	s_add_u32 s58, s58, 0x100
	s_addc_u32 s69, s69, 0
	s_cmp_gt_u32 s70, 13
	s_barrier
	s_cbranch_scc0 .LBB0_576
	s_lshl_b32 s11, s49, 8
	s_or_b32 s11, s11, s42
	v_or_b32_e32 v146, s11, v163
	v_ashrrev_i32_e32 v147, 31, v146
	v_lshl_add_u64 v[158:159], v[146:147], 2, s[8:9]
	global_load_dwordx4 v[146:149], v[158:159], off
	global_load_dwordx4 v[150:153], v[158:159], off offset:16
	global_load_dwordx4 v[154:157], v[158:159], off offset:512
	s_nop 0
	global_load_dwordx4 v[158:161], v[158:159], off offset:528
	s_lshl_b32 s20, s18, 8
	s_add_i32 s20, s20, s39
	s_and_b32 s18, s49, 0x7ffff0
	s_lshr_b32 s13, s20, 6
	s_lshr_b32 s11, s11, 3
	s_add_i32 s13, s13, s18
	s_and_b32 s11, s11, 0x1ec
	v_lshl_or_b32 v171, s13, 9, v165
	s_or_b32 s13, s11, 16
	v_or_b32_e32 v172, s11, v171
	v_or_b32_e32 v173, s13, v171
	v_lshlrev_b32_e32 v175, 6, v172
	v_lshlrev_b32_e32 v173, 6, v173
	v_or_b32_e32 v172, v175, v162
	v_or_b32_e32 v174, v173, v162
	v_or_b32_e32 v176, v175, v166
	v_or_b32_e32 v178, v173, v166
	v_ashrrev_i32_e32 v173, 31, v172
	v_ashrrev_i32_e32 v175, 31, v174
	v_lshl_add_u64 v[172:173], v[172:173], 4, v[136:137]
	v_lshl_add_u64 v[174:175], v[174:175], 4, v[136:137]
	v_ashrrev_i32_e32 v177, 31, v176
	v_lshl_add_u64 v[176:177], v[176:177], 4, v[136:137]
	s_addk_i32 s20, 0x80
	s_lshr_b32 s20, s20, 6
	s_add_i32 s20, s20, s18
	s_and_b64 vcc, exec, s[2:3]
	s_mov_b32 s49, s10
	s_mov_b32 s18, s12
	s_mov_b64 s[22:23], s[16:17]
	s_waitcnt vmcnt(0)
; __device__ __forceinline__ unsigned cvt_pk_bf16(float lo, float hi) { unsigned r; asm volatile("v_cvt_pk_bf16_f32 %0, %1, %2" : "=v"(r) : "v"(lo), "v"(hi)); return r; }
;     __device__ __forceinline__ void operator()(const f32x4 (&acc)[2][2][4][2], const Unit& u, int wr, int wc, int fr, int fq) const {
;     ...
;             for (int n = 0; n < 2; ++n) { const f32x4 q = *(const f32x4*)(ssq + col0 + bj * HALF + 4 * n);
; #pragma unroll
;                 for (int e = 0; e < 4; ++e) cs[bj][n][e] = __builtin_amdgcn_rsqf(q[e] * (1.0f / 1024.0f) + 1e-6f); }
; #pragma unroll
;         for (int ai = 0; ai < 2; ++ai)
; #pragma unroll
;             for (int m = 0; m < 4; ++m) { const int row = row0 + ai * HALF + m * 16, h = row >> 6, d = row & 63, dt = d >> 5, r = d & 31;
; #pragma unroll
;                 for (int bj = 0; bj < 2; ++bj) { const int col = col0 + bj * HALF, b = col >> 12, tl = col & 4095, kt = tl >> 5, k0 = tl & 31, s = k0 >> 4, half = (k0 >> 3) & 1, bh = b * 16 + h;
;                     const f32x4 v0 = acc[ai][bj][m][0] * cs[bj][0], v1 = acc[ai][bj][m][1] * cs[bj][1];
;                     bf16_t* p = VF + (((size_t)((((bh * 128 + kt) * 2 + dt) * 2 + s) * 64 + r)) << 3) + 4 * half;
;                     *(unsigned long long*)p = (unsigned long long)cvt_pk_bf16(v0[0], v0[1]) | ((unsigned long long)cvt_pk_bf16(v0[2], v0[3]) << 32);
;                     *(unsigned long long*)(p + 256) = (unsigned long long)cvt_pk_bf16(v1[0], v1[1]) | ((unsigned long long)cvt_pk_bf16(v1[2], v1[3]) << 32); }
	v_fmamk_f32 v146, v146, 0x3a800000, v170
	v_fmamk_f32 v147, v147, 0x3a800000, v170
	v_fmamk_f32 v148, v148, 0x3a800000, v170
	v_fmamk_f32 v149, v149, 0x3a800000, v170
	v_fmamk_f32 v150, v150, 0x3a800000, v170
	v_fmamk_f32 v151, v151, 0x3a800000, v170
	v_fmamk_f32 v179, v154, 0x3a800000, v170
	v_fmamk_f32 v180, v155, 0x3a800000, v170
	v_fmamk_f32 v183, v158, 0x3a800000, v170
	v_fmamk_f32 v185, v159, 0x3a800000, v170
	v_fmamk_f32 v152, v152, 0x3a800000, v170
	v_fmamk_f32 v153, v153, 0x3a800000, v170
	v_fmamk_f32 v181, v156, 0x3a800000, v170
	v_fmamk_f32 v182, v157, 0x3a800000, v170
	v_fmamk_f32 v187, v160, 0x3a800000, v170
	v_fmamk_f32 v188, v161, 0x3a800000, v170
	v_rsq_f32_e32 v156, v146
	v_rsq_f32_e32 v157, v147
	v_rsq_f32_e32 v160, v148
	v_rsq_f32_e32 v161, v149
	v_rsq_f32_e32 v154, v150
	v_rsq_f32_e32 v155, v151
	v_rsq_f32_e32 v148, v179
	v_rsq_f32_e32 v149, v180
	v_rsq_f32_e32 v146, v183
	v_rsq_f32_e32 v147, v185
	v_rsq_f32_e32 v158, v152
	v_rsq_f32_e32 v159, v153
	v_rsq_f32_e32 v152, v181
	v_rsq_f32_e32 v153, v182
	v_rsq_f32_e32 v150, v187
	v_rsq_f32_e32 v151, v188
	v_pk_mul_f32 v[124:125], v[124:125], v[156:157]
	v_pk_mul_f32 v[120:121], v[120:121], v[154:155]
	v_pk_mul_f32 v[108:109], v[108:109], v[148:149]
	v_pk_mul_f32 v[104:105], v[104:105], v[146:147]
	v_pk_mul_f32 v[126:127], v[126:127], v[160:161]
	v_pk_mul_f32 v[122:123], v[122:123], v[158:159]
	v_pk_mul_f32 v[110:111], v[110:111], v[152:153]
	v_pk_mul_f32 v[106:107], v[106:107], v[150:151]
	v_cvt_pk_bf16_f32 v124, v124, v125
	v_cvt_pk_bf16_f32 v125, v126, v127
	global_store_dwordx2 v[172:173], v[124:125], off
	v_cvt_pk_bf16_f32 v120, v120, v121
	v_cvt_pk_bf16_f32 v121, v122, v123
	global_store_dwordx2 v[172:173], v[120:121], off offset:512
	v_cvt_pk_bf16_f32 v108, v108, v109
	v_cvt_pk_bf16_f32 v109, v110, v111
	global_store_dwordx2 v[174:175], v[108:109], off
	v_cvt_pk_bf16_f32 v104, v104, v105
	v_cvt_pk_bf16_f32 v105, v106, v107
	global_store_dwordx2 v[174:175], v[104:105], off offset:512
	v_pk_mul_f32 v[118:119], v[118:119], v[160:161]
	v_pk_mul_f32 v[116:117], v[116:117], v[156:157]
	v_pk_mul_f32 v[114:115], v[114:115], v[158:159]
	v_cvt_pk_bf16_f32 v104, v116, v117
	v_cvt_pk_bf16_f32 v105, v118, v119
	v_pk_mul_f32 v[112:113], v[112:113], v[154:155]
	global_store_dwordx2 v[176:177], v[104:105], off
	v_cvt_pk_bf16_f32 v104, v112, v113
	v_cvt_pk_bf16_f32 v105, v114, v115
	v_ashrrev_i32_e32 v179, 31, v178
	v_pk_mul_f32 v[100:101], v[100:101], v[148:149]
	v_pk_mul_f32 v[98:99], v[98:99], v[150:151]
	v_pk_mul_f32 v[96:97], v[96:97], v[146:147]
	global_store_dwordx2 v[176:177], v[104:105], off offset:512
	v_lshl_add_u64 v[104:105], v[178:179], 4, v[136:137]
	v_pk_mul_f32 v[102:103], v[102:103], v[152:153]
	v_cvt_pk_bf16_f32 v100, v100, v101
	v_pk_mul_f32 v[92:93], v[92:93], v[156:157]
	v_cvt_pk_bf16_f32 v101, v102, v103
	global_store_dwordx2 v[104:105], v[100:101], off
	v_cvt_pk_bf16_f32 v96, v96, v97
	v_cvt_pk_bf16_f32 v97, v98, v99
	v_or_b32_e32 v98, 2, v171
	global_store_dwordx2 v[104:105], v[96:97], off offset:512
	v_or_b32_e32 v96, s11, v98
	v_lshlrev_b32_e32 v99, 6, v96
	v_or_b32_e32 v96, v99, v162
	v_ashrrev_i32_e32 v97, 31, v96
	v_pk_mul_f32 v[88:89], v[88:89], v[154:155]
	v_lshl_add_u64 v[96:97], v[96:97], 4, v[136:137]
	v_pk_mul_f32 v[94:95], v[94:95], v[160:161]
	v_cvt_pk_bf16_f32 v92, v92, v93
	v_pk_mul_f32 v[90:91], v[90:91], v[158:159]
	v_cvt_pk_bf16_f32 v93, v94, v95
	global_store_dwordx2 v[96:97], v[92:93], off
	v_cvt_pk_bf16_f32 v88, v88, v89
	v_cvt_pk_bf16_f32 v89, v90, v91
	global_store_dwordx2 v[96:97], v[88:89], off offset:512
	v_or_b32_e32 v88, s13, v98
	v_lshlrev_b32_e32 v90, 6, v88
	v_or_b32_e32 v88, v90, v162
	v_ashrrev_i32_e32 v89, 31, v88
	v_pk_mul_f32 v[84:85], v[84:85], v[148:149]
	v_pk_mul_f32 v[80:81], v[80:81], v[146:147]
	v_lshl_add_u64 v[88:89], v[88:89], 4, v[136:137]
	v_pk_mul_f32 v[86:87], v[86:87], v[152:153]
	v_cvt_pk_bf16_f32 v84, v84, v85
	v_pk_mul_f32 v[82:83], v[82:83], v[150:151]
	v_cvt_pk_bf16_f32 v85, v86, v87
	global_store_dwordx2 v[88:89], v[84:85], off
	v_cvt_pk_bf16_f32 v80, v80, v81
	v_cvt_pk_bf16_f32 v81, v82, v83
	global_store_dwordx2 v[88:89], v[80:81], off offset:512
	v_or_b32_e32 v80, v99, v166
	v_ashrrev_i32_e32 v81, 31, v80
	v_pk_mul_f32 v[76:77], v[76:77], v[156:157]
	v_pk_mul_f32 v[72:73], v[72:73], v[154:155]
	v_lshl_add_u64 v[80:81], v[80:81], 4, v[136:137]
	v_pk_mul_f32 v[78:79], v[78:79], v[160:161]
	v_cvt_pk_bf16_f32 v76, v76, v77
	v_pk_mul_f32 v[74:75], v[74:75], v[158:159]
	v_cvt_pk_bf16_f32 v77, v78, v79
	global_store_dwordx2 v[80:81], v[76:77], off
	v_cvt_pk_bf16_f32 v72, v72, v73
	v_cvt_pk_bf16_f32 v73, v74, v75
	global_store_dwordx2 v[80:81], v[72:73], off offset:512
	v_or_b32_e32 v72, v90, v166
	v_ashrrev_i32_e32 v73, 31, v72
	v_pk_mul_f32 v[68:69], v[68:69], v[148:149]
	v_pk_mul_f32 v[66:67], v[66:67], v[150:151]
	v_pk_mul_f32 v[64:65], v[64:65], v[146:147]
; __device__ __forceinline__ unsigned cvt_pk_bf16(float lo, float hi) { unsigned r; asm volatile("v_cvt_pk_bf16_f32 %0, %1, %2" : "=v"(r) : "v"(lo), "v"(hi)); return r; }
; #define PG8_WAIT_V(n) asm volatile("s_waitcnt vmcnt(" #n ")" ::: "memory")
; #define PG8_BAR __builtin_amdgcn_s_barrier()
;     __device__ __forceinline__ void operator()(const f32x4 (&acc)[2][2][4][2], const Unit& u, int wr, int wc, int fr, int fq) const {
;     ...
;             for (int m = 0; m < 4; ++m) { const int row = row0 + ai * HALF + m * 16, h = row >> 6, d = row & 63, dt = d >> 5, r = d & 31;
; #pragma unroll
;                 for (int bj = 0; bj < 2; ++bj) { const int col = col0 + bj * HALF, b = col >> 12, tl = col & 4095, kt = tl >> 5, k0 = tl & 31, s = k0 >> 4, half = (k0 >> 3) & 1, bh = b * 16 + h;
;                     const f32x4 v0 = acc[ai][bj][m][0] * cs[bj][0], v1 = acc[ai][bj][m][1] * cs[bj][1];
;                     bf16_t* p = VF + (((size_t)((((bh * 128 + kt) * 2 + dt) * 2 + s) * 64 + r)) << 3) + 4 * half;
;                     *(unsigned long long*)p = (unsigned long long)cvt_pk_bf16(v0[0], v0[1]) | ((unsigned long long)cvt_pk_bf16(v0[2], v0[3]) << 32);
;                     *(unsigned long long*)(p + 256) = (unsigned long long)cvt_pk_bf16(v1[0], v1[1]) | ((unsigned long long)cvt_pk_bf16(v1[2], v1[3]) << 32); }
; template <class Epi, class Sched, bool ALIGN_EPI = false, bool SP2 = false>
; __device__ __forceinline__ void gemm_phase(PG8_LAS unsigned char* lds, const Gemm g, const Sched& S, const Epi& E) {
;     ...
;         if (!has_next) break;
; #pragma unroll
;         for (int a = 0; a < 2; ++a)
; #pragma unroll
;             for (int b = 0; b < 2; ++b)
; #pragma unroll
;                 for (int m = 0; m < 4; ++m)
; #pragma unroll
;                     for (int n = 0; n < 2; ++n) acc[a][b][m][n] = (f32x4){0.f, 0.f, 0.f, 0.f};
;         cur = nxt; cA = nA; cB = nB; ++ui;
;         if constexpr (ALIGN_EPI) { if (wr == 1) PG8_BAR; }
;     }
;     PG8_WAIT_V(0);
;     if constexpr (!ALIGN_EPI) { if (wr == 0) PG8_BAR; }
	v_lshl_add_u64 v[72:73], v[72:73], 4, v[136:137]
	v_pk_mul_f32 v[70:71], v[70:71], v[152:153]
	v_cvt_pk_bf16_f32 v68, v68, v69
	v_pk_mul_f32 v[60:61], v[60:61], v[156:157]
	v_cvt_pk_bf16_f32 v69, v70, v71
	global_store_dwordx2 v[72:73], v[68:69], off
	v_cvt_pk_bf16_f32 v64, v64, v65
	v_cvt_pk_bf16_f32 v65, v66, v67
	v_lshl_or_b32 v66, s20, 9, v165
	global_store_dwordx2 v[72:73], v[64:65], off offset:512
	v_or_b32_e32 v64, s11, v66
	v_lshlrev_b32_e32 v67, 6, v64
	v_or_b32_e32 v64, v67, v162
	v_ashrrev_i32_e32 v65, 31, v64
	v_pk_mul_f32 v[56:57], v[56:57], v[154:155]
	v_lshl_add_u64 v[64:65], v[64:65], 4, v[136:137]
	v_pk_mul_f32 v[62:63], v[62:63], v[160:161]
	v_cvt_pk_bf16_f32 v60, v60, v61
	v_pk_mul_f32 v[58:59], v[58:59], v[158:159]
	v_cvt_pk_bf16_f32 v61, v62, v63
	global_store_dwordx2 v[64:65], v[60:61], off
	v_cvt_pk_bf16_f32 v56, v56, v57
	v_cvt_pk_bf16_f32 v57, v58, v59
	global_store_dwordx2 v[64:65], v[56:57], off offset:512
	v_or_b32_e32 v56, s13, v66
	v_lshlrev_b32_e32 v58, 6, v56
	v_or_b32_e32 v56, v58, v162
	v_ashrrev_i32_e32 v57, 31, v56
	v_pk_mul_f32 v[52:53], v[52:53], v[148:149]
	v_pk_mul_f32 v[48:49], v[48:49], v[146:147]
	v_lshl_add_u64 v[56:57], v[56:57], 4, v[136:137]
	v_pk_mul_f32 v[54:55], v[54:55], v[152:153]
	v_cvt_pk_bf16_f32 v52, v52, v53
	v_pk_mul_f32 v[50:51], v[50:51], v[150:151]
	v_cvt_pk_bf16_f32 v53, v54, v55
	global_store_dwordx2 v[56:57], v[52:53], off
	v_cvt_pk_bf16_f32 v48, v48, v49
	v_cvt_pk_bf16_f32 v49, v50, v51
	global_store_dwordx2 v[56:57], v[48:49], off offset:512
	v_or_b32_e32 v48, v67, v166
	v_ashrrev_i32_e32 v49, 31, v48
	v_pk_mul_f32 v[44:45], v[44:45], v[156:157]
	v_pk_mul_f32 v[40:41], v[40:41], v[154:155]
	v_lshl_add_u64 v[48:49], v[48:49], 4, v[136:137]
	v_pk_mul_f32 v[46:47], v[46:47], v[160:161]
	v_cvt_pk_bf16_f32 v44, v44, v45
	v_pk_mul_f32 v[42:43], v[42:43], v[158:159]
	v_cvt_pk_bf16_f32 v45, v46, v47
	global_store_dwordx2 v[48:49], v[44:45], off
	v_cvt_pk_bf16_f32 v40, v40, v41
	v_cvt_pk_bf16_f32 v41, v42, v43
	global_store_dwordx2 v[48:49], v[40:41], off offset:512
	v_or_b32_e32 v40, v58, v166
	v_ashrrev_i32_e32 v41, 31, v40
	v_pk_mul_f32 v[36:37], v[36:37], v[148:149]
	v_pk_mul_f32 v[34:35], v[34:35], v[150:151]
	v_pk_mul_f32 v[32:33], v[32:33], v[146:147]
	v_lshl_add_u64 v[40:41], v[40:41], 4, v[136:137]
	v_pk_mul_f32 v[38:39], v[38:39], v[152:153]
	v_cvt_pk_bf16_f32 v36, v36, v37
	v_pk_mul_f32 v[28:29], v[28:29], v[156:157]
	v_cvt_pk_bf16_f32 v37, v38, v39
	global_store_dwordx2 v[40:41], v[36:37], off
	v_cvt_pk_bf16_f32 v32, v32, v33
	v_cvt_pk_bf16_f32 v33, v34, v35
	v_or_b32_e32 v34, 2, v66
	global_store_dwordx2 v[40:41], v[32:33], off offset:512
	v_or_b32_e32 v32, s11, v34
	v_lshlrev_b32_e32 v35, 6, v32
	v_or_b32_e32 v32, v35, v162
	v_ashrrev_i32_e32 v33, 31, v32
	v_pk_mul_f32 v[24:25], v[24:25], v[154:155]
	v_lshl_add_u64 v[32:33], v[32:33], 4, v[136:137]
	v_pk_mul_f32 v[30:31], v[30:31], v[160:161]
	v_cvt_pk_bf16_f32 v28, v28, v29
	v_pk_mul_f32 v[26:27], v[26:27], v[158:159]
	v_cvt_pk_bf16_f32 v29, v30, v31
	global_store_dwordx2 v[32:33], v[28:29], off
	v_cvt_pk_bf16_f32 v24, v24, v25
	v_cvt_pk_bf16_f32 v25, v26, v27
	global_store_dwordx2 v[32:33], v[24:25], off offset:512
	v_or_b32_e32 v24, s13, v34
	v_lshlrev_b32_e32 v26, 6, v24
	v_or_b32_e32 v24, v26, v162
	v_ashrrev_i32_e32 v25, 31, v24
	v_pk_mul_f32 v[20:21], v[20:21], v[148:149]
	v_pk_mul_f32 v[16:17], v[16:17], v[146:147]
	v_lshl_add_u64 v[24:25], v[24:25], 4, v[136:137]
	v_pk_mul_f32 v[22:23], v[22:23], v[152:153]
	v_cvt_pk_bf16_f32 v20, v20, v21
	v_pk_mul_f32 v[18:19], v[18:19], v[150:151]
	v_cvt_pk_bf16_f32 v21, v22, v23
	global_store_dwordx2 v[24:25], v[20:21], off
	v_cvt_pk_bf16_f32 v16, v16, v17
	v_cvt_pk_bf16_f32 v17, v18, v19
	global_store_dwordx2 v[24:25], v[16:17], off offset:512
	v_or_b32_e32 v16, v35, v166
	v_ashrrev_i32_e32 v17, 31, v16
	v_pk_mul_f32 v[12:13], v[12:13], v[156:157]
	v_pk_mul_f32 v[8:9], v[8:9], v[154:155]
	v_lshl_add_u64 v[16:17], v[16:17], 4, v[136:137]
	v_pk_mul_f32 v[14:15], v[14:15], v[160:161]
	v_cvt_pk_bf16_f32 v12, v12, v13
	v_pk_mul_f32 v[10:11], v[10:11], v[158:159]
	v_cvt_pk_bf16_f32 v13, v14, v15
	global_store_dwordx2 v[16:17], v[12:13], off
	v_cvt_pk_bf16_f32 v8, v8, v9
	v_cvt_pk_bf16_f32 v9, v10, v11
	global_store_dwordx2 v[16:17], v[8:9], off offset:512
	v_or_b32_e32 v8, v26, v166
	v_ashrrev_i32_e32 v9, 31, v8
	v_pk_mul_f32 v[4:5], v[4:5], v[148:149]
	v_pk_mul_f32 v[0:1], v[0:1], v[146:147]
	v_lshl_add_u64 v[8:9], v[8:9], 4, v[136:137]
	v_pk_mul_f32 v[6:7], v[6:7], v[152:153]
	v_pk_mul_f32 v[2:3], v[2:3], v[150:151]
	v_cvt_pk_bf16_f32 v4, v4, v5
	v_cvt_pk_bf16_f32 v5, v6, v7
	global_store_dwordx2 v[8:9], v[4:5], off
	v_cvt_pk_bf16_f32 v0, v0, v1
	v_cvt_pk_bf16_f32 v1, v2, v3
	global_store_dwordx2 v[8:9], v[0:1], off offset:512
	s_mov_b64 s[20:21], s[14:15]
	s_cbranch_vccz .LBB0_569
	s_waitcnt vmcnt(0)
	s_cmpk_gt_u32 s26, 0xff
	s_cbranch_scc1 .LBB0_580
	s_barrier

; #define PG8_STAGE(bufoff, gbase, voff) do { _Pragma("unroll") for (int _i = 0; _i < 2; ++_i) \
;         __builtin_amdgcn_global_load_lds((const unsigned*)((const char*)(gbase) + (voff)[_i]), (PG8_LAS unsigned*)(lds + (bufoff) + ldsw + _i * 8192), 16, 0, 0); } while (0)
; #define PG8_LDA(dst, b, h) do { _Pragma("unroll") for (int m = 0; m < 4; ++m) _Pragma("unroll") for (int k = 0; k < 2; ++k) dst[m][k] = *(const PG8_LAS bf16x8*)(lds + PG8_SA(b, h) + aoff + m * 2048 + k * 1024); } while (0)
; #define PG8_LDB(dst, b, h) do { _Pragma("unroll") for (int n = 0; n < 2; ++n) _Pragma("unroll") for (int k = 0; k < 2; ++k) dst[n][k] = *(const PG8_LAS bf16x8*)(lds + PG8_SB(b, h) + boff + n * 2048 + k * 1024); } while (0)
; #define PG8_MMA(ai, bj, At, Bt) do { __builtin_amdgcn_s_setprio(1); _Pragma("unroll") for (int m = 0; m < 4; ++m) _Pragma("unroll") for (int n = 0; n < 2; ++n) _Pragma("unroll") for (int k = 0; k < 2; ++k) \
;         acc[ai][bj][m][n] = __builtin_amdgcn_mfma_f32_16x16x32_bf16(Bt[n][k], At[m][k], acc[ai][bj][m][n], 0, 0, 0); __builtin_amdgcn_s_setprio(0); } while (0)
; #define PG8_WAIT_V(n) asm volatile("s_waitcnt vmcnt(" #n ")" ::: "memory")
; #define PG8_WAIT_L(n) asm volatile("s_waitcnt lgkmcnt(" #n ")" ::: "memory")
; #define PG8_BAR __builtin_amdgcn_s_barrier()
; #define PG8_SCHED __builtin_amdgcn_sched_barrier(0)
; template <class Epi, class Sched, bool ALIGN_EPI = false, bool SP2 = false>
; __device__ __forceinline__ void gemm_phase(PG8_LAS unsigned char* lds, const Gemm g, const Sched& S, const Epi& E) {
;     ...
;             const bool last = (t == nt - 2);
;             const char* a1 = cA + (size_t)(t + 1) * kstep;
;             const char* a2 = last ? nA : cA + (size_t)(t + 2) * kstep; const char* b2 = last ? nB : cB + (size_t)(t + 2) * kstep;
;             const char* a3 = a2 + kstep; const char* b3 = b2 + kstep;
;             if (last && has_next) S.a_ready(nxt);
;             if constexpr (SP2) {
;             PG8_LDB(B0, 0, 0); PG8_LDB(B1, 0, 1); PG8_SCHED; PG8_LDA(At, 0, 0); PG8_STAGE(PG8_SA(1, 1), a1 + hstep, voffA);
;             PG8_WAIT_V(8); PG8_WAIT_L(0); PG8_BAR; PG8_MMA(0, 0, At, B0); PG8_MMA(0, 1, At, B1); PG8_BAR; PG8_SCHED;
;             PG8_LDA(At, 0, 1); PG8_STAGE(PG8_SB(0, 0), b2, voffB); PG8_STAGE(PG8_SB(0, 1), b2 + hstep, voffB); PG8_STAGE(PG8_SA(0, 0), a2, voffA);
.LBB0_716:
	ds_read_b128 v[140:143], v223
	ds_read_b128 v[144:147], v223 offset:1024
	ds_read_b128 v[148:151], v223 offset:2048
	ds_read_b128 v[152:155], v223 offset:3072
	ds_read_b128 v[156:159], v224
	ds_read_b128 v[160:163], v224 offset:1024
	ds_read_b128 v[164:167], v224 offset:2048
	ds_read_b128 v[168:171], v224 offset:3072
	s_add_u32 s26, s24, 0xfffc0080
	s_addc_u32 s27, s25, -1
	s_cmp_eq_u32 s58, 12
	s_cselect_b32 s29, s15, s27
	s_cselect_b32 s28, s21, s26
	s_cselect_b32 s27, s13, s57
	s_cselect_b32 s26, s51, s56
	v_lshl_add_u64 v[206:207], s[24:25], 0, v[132:133]
	s_add_i32 m0, s23, 0xc000
	ds_read_b128 v[172:175], v225
	ds_read_b128 v[176:179], v225 offset:1024
	ds_read_b128 v[180:183], v225 offset:2048
	ds_read_b128 v[186:189], v225 offset:3072
	ds_read_b128 v[190:193], v225 offset:4096
	ds_read_b128 v[194:197], v225 offset:5120
	ds_read_b128 v[198:201], v225 offset:6144
	ds_read_b128 v[202:205], v225 offset:7168
	global_load_lds_dwordx4 v[206:207], off
	v_lshl_add_u64 v[206:207], s[24:25], 0, v[134:135]
	s_add_i32 m0, s23, 0xe000
	s_nop 0
	global_load_lds_dwordx4 v[206:207], off
	s_waitcnt vmcnt(8)
	s_waitcnt lgkmcnt(0)
	s_barrier
	s_setprio 1
	s_waitcnt lgkmcnt(0)
	v_mfma_f32_16x16x32_bf16 v[124:127], v[140:143], v[172:175], v[124:127]
	v_mfma_f32_16x16x32_bf16 v[120:123], v[148:151], v[172:175], v[120:123]
	v_mfma_f32_16x16x32_bf16 v[108:111], v[140:143], v[180:183], v[108:111]
	v_mfma_f32_16x16x32_bf16 v[104:107], v[148:151], v[180:183], v[104:107]
	v_mfma_f32_16x16x32_bf16 v[92:95], v[140:143], v[190:193], v[92:95]
	v_mfma_f32_16x16x32_bf16 v[88:91], v[148:151], v[190:193], v[88:91]
	v_mfma_f32_16x16x32_bf16 v[76:79], v[140:143], v[198:201], v[76:79]
	v_mfma_f32_16x16x32_bf16 v[72:75], v[148:151], v[198:201], v[72:75]
	v_mfma_f32_16x16x32_bf16 v[124:127], v[144:147], v[176:179], v[124:127]
	v_mfma_f32_16x16x32_bf16 v[120:123], v[152:155], v[176:179], v[120:123]
	v_mfma_f32_16x16x32_bf16 v[108:111], v[144:147], v[186:189], v[108:111]
	v_mfma_f32_16x16x32_bf16 v[104:107], v[152:155], v[186:189], v[104:107]
	v_mfma_f32_16x16x32_bf16 v[92:95], v[144:147], v[194:197], v[92:95]
	v_mfma_f32_16x16x32_bf16 v[88:91], v[152:155], v[194:197], v[88:91]
	v_mfma_f32_16x16x32_bf16 v[76:79], v[144:147], v[202:205], v[76:79]
	v_mfma_f32_16x16x32_bf16 v[72:75], v[152:155], v[202:205], v[72:75]
	s_setprio 0
	s_setprio 1
	v_mfma_f32_16x16x32_bf16 v[116:119], v[156:159], v[172:175], v[116:119]
	v_mfma_f32_16x16x32_bf16 v[112:115], v[164:167], v[172:175], v[112:115]
	v_mfma_f32_16x16x32_bf16 v[100:103], v[156:159], v[180:183], v[100:103]
	v_mfma_f32_16x16x32_bf16 v[96:99], v[164:167], v[180:183], v[96:99]
	v_mfma_f32_16x16x32_bf16 v[84:87], v[156:159], v[190:193], v[84:87]
	v_mfma_f32_16x16x32_bf16 v[80:83], v[164:167], v[190:193], v[80:83]
	v_mfma_f32_16x16x32_bf16 v[68:71], v[156:159], v[198:201], v[68:71]
	v_mfma_f32_16x16x32_bf16 v[64:67], v[164:167], v[198:201], v[64:67]
	v_mfma_f32_16x16x32_bf16 v[116:119], v[160:163], v[176:179], v[116:119]
	v_mfma_f32_16x16x32_bf16 v[112:115], v[168:171], v[176:179], v[112:115]
	v_mfma_f32_16x16x32_bf16 v[100:103], v[160:163], v[186:189], v[100:103]
	v_mfma_f32_16x16x32_bf16 v[96:99], v[168:171], v[186:189], v[96:99]
	v_mfma_f32_16x16x32_bf16 v[84:87], v[160:163], v[194:197], v[84:87]
	v_mfma_f32_16x16x32_bf16 v[80:83], v[168:171], v[194:197], v[80:83]
	v_mfma_f32_16x16x32_bf16 v[68:71], v[160:163], v[202:205], v[68:71]
	v_mfma_f32_16x16x32_bf16 v[64:67], v[168:171], v[202:205], v[64:67]
	s_setprio 0
	s_barrier
	s_add_i32 s63, s49, s37
	v_lshl_add_u64 v[206:207], s[26:27], 0, v[128:129]
	s_mov_b32 m0, s63
	ds_read_b128 v[172:175], v225 offset:16384
	ds_read_b128 v[176:179], v225 offset:17408
	ds_read_b128 v[180:183], v225 offset:18432
	ds_read_b128 v[186:189], v225 offset:19456
	ds_read_b128 v[190:193], v225 offset:20480
	ds_read_b128 v[194:197], v225 offset:21504
	ds_read_b128 v[198:201], v225 offset:22528
	ds_read_b128 v[202:205], v225 offset:23552
	global_load_lds_dwordx4 v[206:207], off
	s_add_i32 m0, s63, 0x2000
	s_add_u32 s66, s26, 0x40000
	v_lshl_add_u64 v[208:209], s[26:27], 0, v[130:131]
	s_addc_u32 s67, s27, 0
	s_add_i32 s63, s50, s37
	global_load_lds_dwordx4 v[208:209], off
	v_lshl_add_u64 v[210:211], s[66:67], 0, v[128:129]
	s_mov_b32 m0, s63
	v_lshl_add_u64 v[212:213], s[28:29], 0, v[130:131]
	global_load_lds_dwordx4 v[210:211], off
	v_lshl_add_u64 v[210:211], s[66:67], 0, v[130:131]
	s_add_i32 m0, s63, 0x2000
	s_nop 0
	global_load_lds_dwordx4 v[210:211], off
	v_lshl_add_u64 v[210:211], s[28:29], 0, v[128:129]
	s_mov_b32 m0, s23
	s_nop 0
	global_load_lds_dwordx4 v[210:211], off
	s_mov_b32 m0, s38
	s_nop 0
	global_load_lds_dwordx4 v[212:213], off
	s_waitcnt vmcnt(8)
	s_waitcnt lgkmcnt(0)
	s_barrier
; #define PG8_STAGE(bufoff, gbase, voff) do { _Pragma("unroll") for (int _i = 0; _i < 2; ++_i) \
;         __builtin_amdgcn_global_load_lds((const unsigned*)((const char*)(gbase) + (voff)[_i]), (PG8_LAS unsigned*)(lds + (bufoff) + ldsw + _i * 8192), 16, 0, 0); } while (0)
; #define PG8_LDA(dst, b, h) do { _Pragma("unroll") for (int m = 0; m < 4; ++m) _Pragma("unroll") for (int k = 0; k < 2; ++k) dst[m][k] = *(const PG8_LAS bf16x8*)(lds + PG8_SA(b, h) + aoff + m * 2048 + k * 1024); } while (0)
; #define PG8_LDB(dst, b, h) do { _Pragma("unroll") for (int n = 0; n < 2; ++n) _Pragma("unroll") for (int k = 0; k < 2; ++k) dst[n][k] = *(const PG8_LAS bf16x8*)(lds + PG8_SB(b, h) + boff + n * 2048 + k * 1024); } while (0)
; #define PG8_MMA(ai, bj, At, Bt) do { __builtin_amdgcn_s_setprio(1); _Pragma("unroll") for (int m = 0; m < 4; ++m) _Pragma("unroll") for (int n = 0; n < 2; ++n) _Pragma("unroll") for (int k = 0; k < 2; ++k) \
;         acc[ai][bj][m][n] = __builtin_amdgcn_mfma_f32_16x16x32_bf16(Bt[n][k], At[m][k], acc[ai][bj][m][n], 0, 0, 0); __builtin_amdgcn_s_setprio(0); } while (0)
; #define PG8_WAIT_V(n) asm volatile("s_waitcnt vmcnt(" #n ")" ::: "memory")
; #define PG8_WAIT_L(n) asm volatile("s_waitcnt lgkmcnt(" #n ")" ::: "memory")
; #define PG8_BAR __builtin_amdgcn_s_barrier()
; #define PG8_SCHED __builtin_amdgcn_sched_barrier(0)
; template <class Epi, class Sched, bool ALIGN_EPI = false, bool SP2 = false>
; __device__ __forceinline__ void gemm_phase(PG8_LAS unsigned char* lds, const Gemm g, const Sched& S, const Epi& E) {
;     ...
;             PG8_WAIT_V(8); PG8_WAIT_L(0); PG8_BAR; PG8_MMA(1, 0, At, B0); PG8_MMA(1, 1, At, B1); PG8_BAR; PG8_SCHED;
;             PG8_LDB(B0, 1, 0); PG8_LDB(B1, 1, 1); PG8_SCHED; PG8_LDA(At, 1, 0); PG8_STAGE(PG8_SA(0, 1), a2 + hstep, voffA);
;             PG8_WAIT_V(8); PG8_WAIT_L(0); PG8_BAR; PG8_MMA(0, 0, At, B0); PG8_MMA(0, 1, At, B1); PG8_BAR; PG8_SCHED;
	s_setprio 1
	s_waitcnt lgkmcnt(0)
	v_mfma_f32_16x16x32_bf16 v[60:63], v[140:143], v[172:175], v[60:63]
	v_mfma_f32_16x16x32_bf16 v[56:59], v[148:151], v[172:175], v[56:59]
	v_mfma_f32_16x16x32_bf16 v[44:47], v[140:143], v[180:183], v[44:47]
	v_mfma_f32_16x16x32_bf16 v[40:43], v[148:151], v[180:183], v[40:43]
	v_mfma_f32_16x16x32_bf16 v[28:31], v[140:143], v[190:193], v[28:31]
	v_mfma_f32_16x16x32_bf16 v[24:27], v[148:151], v[190:193], v[24:27]
	v_mfma_f32_16x16x32_bf16 v[12:15], v[140:143], v[198:201], v[12:15]
	v_mfma_f32_16x16x32_bf16 v[8:11], v[148:151], v[198:201], v[8:11]
	v_mfma_f32_16x16x32_bf16 v[60:63], v[144:147], v[176:179], v[60:63]
	v_mfma_f32_16x16x32_bf16 v[56:59], v[152:155], v[176:179], v[56:59]
	v_mfma_f32_16x16x32_bf16 v[44:47], v[144:147], v[186:189], v[44:47]
	v_mfma_f32_16x16x32_bf16 v[40:43], v[152:155], v[186:189], v[40:43]
	v_mfma_f32_16x16x32_bf16 v[28:31], v[144:147], v[194:197], v[28:31]
	v_mfma_f32_16x16x32_bf16 v[24:27], v[152:155], v[194:197], v[24:27]
	v_mfma_f32_16x16x32_bf16 v[12:15], v[144:147], v[202:205], v[12:15]
	v_mfma_f32_16x16x32_bf16 v[8:11], v[152:155], v[202:205], v[8:11]
	s_setprio 0
	s_setprio 1
	v_mfma_f32_16x16x32_bf16 v[52:55], v[156:159], v[172:175], v[52:55]
	v_mfma_f32_16x16x32_bf16 v[48:51], v[164:167], v[172:175], v[48:51]
	v_mfma_f32_16x16x32_bf16 v[36:39], v[156:159], v[180:183], v[36:39]
	v_mfma_f32_16x16x32_bf16 v[32:35], v[164:167], v[180:183], v[32:35]
	v_mfma_f32_16x16x32_bf16 v[20:23], v[156:159], v[190:193], v[20:23]
	v_mfma_f32_16x16x32_bf16 v[16:19], v[164:167], v[190:193], v[16:19]
	v_mfma_f32_16x16x32_bf16 v[4:7], v[156:159], v[198:201], v[4:7]
	v_mfma_f32_16x16x32_bf16 v[0:3], v[164:167], v[198:201], v[0:3]
	v_mfma_f32_16x16x32_bf16 v[52:55], v[160:163], v[176:179], v[52:55]
	v_mfma_f32_16x16x32_bf16 v[48:51], v[168:171], v[176:179], v[48:51]
	v_mfma_f32_16x16x32_bf16 v[36:39], v[160:163], v[186:189], v[36:39]
	v_mfma_f32_16x16x32_bf16 v[32:35], v[168:171], v[186:189], v[32:35]
	v_mfma_f32_16x16x32_bf16 v[20:23], v[160:163], v[194:197], v[20:23]
	v_mfma_f32_16x16x32_bf16 v[16:19], v[168:171], v[194:197], v[16:19]
	v_mfma_f32_16x16x32_bf16 v[4:7], v[160:163], v[202:205], v[4:7]
	v_mfma_f32_16x16x32_bf16 v[0:3], v[168:171], v[202:205], v[0:3]
	s_setprio 0
	s_barrier
	s_add_i32 s63, 0, 0x18000
	s_add_i32 s66, 0, 0x1c000
	v_add_u32_e32 v152, s63, v221
	v_add_u32_e32 v168, s66, v221
	ds_read_b128 v[140:143], v152
	ds_read_b128 v[144:147], v152 offset:1024
	ds_read_b128 v[148:151], v152 offset:2048
	ds_read_b128 v[152:155], v152 offset:3072
	ds_read_b128 v[156:159], v168
	ds_read_b128 v[160:163], v168 offset:1024
	ds_read_b128 v[164:167], v168 offset:2048
	ds_read_b128 v[168:171], v168 offset:3072
	s_add_u32 s28, s28, 0x40000
	s_addc_u32 s29, s29, 0
	s_mov_b32 m0, s39
	v_lshl_add_u64 v[214:215], s[28:29], 0, v[128:129]
	ds_read_b128 v[172:175], v225 offset:32768
	ds_read_b128 v[176:179], v225 offset:33792
	ds_read_b128 v[180:183], v225 offset:34816
	ds_read_b128 v[186:189], v225 offset:35840
	ds_read_b128 v[190:193], v225 offset:36864
	ds_read_b128 v[194:197], v225 offset:37888
	ds_read_b128 v[198:201], v225 offset:38912
	ds_read_b128 v[202:205], v225 offset:39936
	global_load_lds_dwordx4 v[214:215], off
	v_lshl_add_u64 v[214:215], s[28:29], 0, v[130:131]
	s_mov_b32 m0, s42
	s_nop 0
	global_load_lds_dwordx4 v[214:215], off
	s_waitcnt vmcnt(8)
	s_waitcnt lgkmcnt(0)
	s_barrier
	s_setprio 1
	s_waitcnt lgkmcnt(0)
	v_mfma_f32_16x16x32_bf16 v[124:127], v[140:143], v[172:175], v[124:127]
	v_mfma_f32_16x16x32_bf16 v[120:123], v[148:151], v[172:175], v[120:123]
	v_mfma_f32_16x16x32_bf16 v[108:111], v[140:143], v[180:183], v[108:111]
	v_mfma_f32_16x16x32_bf16 v[104:107], v[148:151], v[180:183], v[104:107]
	v_mfma_f32_16x16x32_bf16 v[92:95], v[140:143], v[190:193], v[92:95]
	v_mfma_f32_16x16x32_bf16 v[88:91], v[148:151], v[190:193], v[88:91]
	v_mfma_f32_16x16x32_bf16 v[76:79], v[140:143], v[198:201], v[76:79]
	v_mfma_f32_16x16x32_bf16 v[72:75], v[148:151], v[198:201], v[72:75]
	v_mfma_f32_16x16x32_bf16 v[124:127], v[144:147], v[176:179], v[124:127]
	v_mfma_f32_16x16x32_bf16 v[120:123], v[152:155], v[176:179], v[120:123]
	v_mfma_f32_16x16x32_bf16 v[108:111], v[144:147], v[186:189], v[108:111]
	v_mfma_f32_16x16x32_bf16 v[104:107], v[152:155], v[186:189], v[104:107]
	v_mfma_f32_16x16x32_bf16 v[92:95], v[144:147], v[194:197], v[92:95]
	v_mfma_f32_16x16x32_bf16 v[88:91], v[152:155], v[194:197], v[88:91]
	v_mfma_f32_16x16x32_bf16 v[76:79], v[144:147], v[202:205], v[76:79]
	v_mfma_f32_16x16x32_bf16 v[72:75], v[152:155], v[202:205], v[72:75]
	s_setprio 0
	s_setprio 1
	v_mfma_f32_16x16x32_bf16 v[116:119], v[156:159], v[172:175], v[116:119]
	v_mfma_f32_16x16x32_bf16 v[112:115], v[164:167], v[172:175], v[112:115]
	v_mfma_f32_16x16x32_bf16 v[100:103], v[156:159], v[180:183], v[100:103]
	v_mfma_f32_16x16x32_bf16 v[96:99], v[164:167], v[180:183], v[96:99]
	v_mfma_f32_16x16x32_bf16 v[84:87], v[156:159], v[190:193], v[84:87]
	v_mfma_f32_16x16x32_bf16 v[80:83], v[164:167], v[190:193], v[80:83]
	v_mfma_f32_16x16x32_bf16 v[68:71], v[156:159], v[198:201], v[68:71]
	v_mfma_f32_16x16x32_bf16 v[64:67], v[164:167], v[198:201], v[64:67]
	v_mfma_f32_16x16x32_bf16 v[116:119], v[160:163], v[176:179], v[116:119]
	v_mfma_f32_16x16x32_bf16 v[112:115], v[168:171], v[176:179], v[112:115]
	v_mfma_f32_16x16x32_bf16 v[100:103], v[160:163], v[186:189], v[100:103]
	v_mfma_f32_16x16x32_bf16 v[96:99], v[168:171], v[186:189], v[96:99]
	v_mfma_f32_16x16x32_bf16 v[84:87], v[160:163], v[194:197], v[84:87]
	v_mfma_f32_16x16x32_bf16 v[80:83], v[168:171], v[194:197], v[80:83]
	v_mfma_f32_16x16x32_bf16 v[68:71], v[160:163], v[202:205], v[68:71]
	v_mfma_f32_16x16x32_bf16 v[64:67], v[168:171], v[202:205], v[64:67]
	s_setprio 0
	s_barrier
; #define PG8_STAGE(bufoff, gbase, voff) do { _Pragma("unroll") for (int _i = 0; _i < 2; ++_i) \
;         __builtin_amdgcn_global_load_lds((const unsigned*)((const char*)(gbase) + (voff)[_i]), (PG8_LAS unsigned*)(lds + (bufoff) + ldsw + _i * 8192), 16, 0, 0); } while (0)
; #define PG8_LDA(dst, b, h) do { _Pragma("unroll") for (int m = 0; m < 4; ++m) _Pragma("unroll") for (int k = 0; k < 2; ++k) dst[m][k] = *(const PG8_LAS bf16x8*)(lds + PG8_SA(b, h) + aoff + m * 2048 + k * 1024); } while (0)
; #define PG8_MMA(ai, bj, At, Bt) do { __builtin_amdgcn_s_setprio(1); _Pragma("unroll") for (int m = 0; m < 4; ++m) _Pragma("unroll") for (int n = 0; n < 2; ++n) _Pragma("unroll") for (int k = 0; k < 2; ++k) \
;         acc[ai][bj][m][n] = __builtin_amdgcn_mfma_f32_16x16x32_bf16(Bt[n][k], At[m][k], acc[ai][bj][m][n], 0, 0, 0); __builtin_amdgcn_s_setprio(0); } while (0)
; #define PG8_WAIT_V(n) asm volatile("s_waitcnt vmcnt(" #n ")" ::: "memory")
; #define PG8_WAIT_L(n) asm volatile("s_waitcnt lgkmcnt(" #n ")" ::: "memory")
; #define PG8_BAR __builtin_amdgcn_s_barrier()
; #define PG8_SCHED __builtin_amdgcn_sched_barrier(0)
; template <class Epi, class Sched, bool ALIGN_EPI = false, bool SP2 = false>
; __device__ __forceinline__ void gemm_phase(PG8_LAS unsigned char* lds, const Gemm g, const Sched& S, const Epi& E) {
;     ...
;         for (int t = 0; t < nt; t += 2) {
;     ...
;             PG8_LDA(At, 1, 1); PG8_STAGE(PG8_SB(1, 0), b3, voffB); PG8_STAGE(PG8_SB(1, 1), b3 + hstep, voffB); PG8_STAGE(PG8_SA(1, 0), a3, voffA);
;             PG8_WAIT_V(8); PG8_WAIT_L(0); PG8_BAR; PG8_MMA(1, 0, At, B0); PG8_MMA(1, 1, At, B1); PG8_BAR; PG8_SCHED;
	s_add_i32 s28, s63, s37
	v_lshl_add_u64 v[206:207], v[206:207], 0, s[10:11]
	s_mov_b32 m0, s28
	ds_read_b128 v[172:175], v225 offset:49152
	ds_read_b128 v[176:179], v225 offset:50176
	ds_read_b128 v[180:183], v225 offset:51200
	ds_read_b128 v[186:189], v225 offset:52224
	ds_read_b128 v[190:193], v225 offset:53248
	ds_read_b128 v[194:197], v225 offset:54272
	ds_read_b128 v[198:201], v225 offset:55296
	ds_read_b128 v[202:205], v225 offset:56320
	global_load_lds_dwordx4 v[206:207], off
	s_add_i32 m0, s28, 0x2000
	s_add_u32 s26, s26, 0x40080
	v_lshl_add_u64 v[206:207], v[208:209], 0, s[10:11]
	s_addc_u32 s27, s27, 0
	s_add_i32 s28, s66, s37
	global_load_lds_dwordx4 v[206:207], off
	v_lshl_add_u64 v[206:207], s[26:27], 0, v[128:129]
	s_mov_b32 m0, s28
	s_nop 0
	global_load_lds_dwordx4 v[206:207], off
	v_lshl_add_u64 v[206:207], s[26:27], 0, v[130:131]
	s_add_i32 m0, s28, 0x2000
	s_nop 0
	global_load_lds_dwordx4 v[206:207], off
	v_lshl_add_u64 v[206:207], v[210:211], 0, s[10:11]
	s_mov_b32 m0, s44
	s_nop 0
	global_load_lds_dwordx4 v[206:207], off
	v_lshl_add_u64 v[206:207], v[212:213], 0, s[10:11]
	s_mov_b32 m0, s45
	s_nop 0
	global_load_lds_dwordx4 v[206:207], off
	s_waitcnt vmcnt(8)
	s_waitcnt lgkmcnt(0)
	s_barrier
	s_setprio 1
	s_waitcnt lgkmcnt(0)
	v_mfma_f32_16x16x32_bf16 v[60:63], v[140:143], v[172:175], v[60:63]
	v_mfma_f32_16x16x32_bf16 v[56:59], v[148:151], v[172:175], v[56:59]
	v_mfma_f32_16x16x32_bf16 v[44:47], v[140:143], v[180:183], v[44:47]
	v_mfma_f32_16x16x32_bf16 v[40:43], v[148:151], v[180:183], v[40:43]
	v_mfma_f32_16x16x32_bf16 v[28:31], v[140:143], v[190:193], v[28:31]
	v_mfma_f32_16x16x32_bf16 v[24:27], v[148:151], v[190:193], v[24:27]
	v_mfma_f32_16x16x32_bf16 v[12:15], v[140:143], v[198:201], v[12:15]
	v_mfma_f32_16x16x32_bf16 v[8:11], v[148:151], v[198:201], v[8:11]
	v_mfma_f32_16x16x32_bf16 v[60:63], v[144:147], v[176:179], v[60:63]
	v_mfma_f32_16x16x32_bf16 v[56:59], v[152:155], v[176:179], v[56:59]
	v_mfma_f32_16x16x32_bf16 v[44:47], v[144:147], v[186:189], v[44:47]
	v_mfma_f32_16x16x32_bf16 v[40:43], v[152:155], v[186:189], v[40:43]
	v_mfma_f32_16x16x32_bf16 v[28:31], v[144:147], v[194:197], v[28:31]
	v_mfma_f32_16x16x32_bf16 v[24:27], v[152:155], v[194:197], v[24:27]
	v_mfma_f32_16x16x32_bf16 v[12:15], v[144:147], v[202:205], v[12:15]
	v_mfma_f32_16x16x32_bf16 v[8:11], v[152:155], v[202:205], v[8:11]
	s_setprio 0
	s_setprio 1
	v_mfma_f32_16x16x32_bf16 v[52:55], v[156:159], v[172:175], v[52:55]
	v_mfma_f32_16x16x32_bf16 v[48:51], v[164:167], v[172:175], v[48:51]
	v_mfma_f32_16x16x32_bf16 v[36:39], v[156:159], v[180:183], v[36:39]
	v_mfma_f32_16x16x32_bf16 v[32:35], v[164:167], v[180:183], v[32:35]
	v_mfma_f32_16x16x32_bf16 v[20:23], v[156:159], v[190:193], v[20:23]
	v_mfma_f32_16x16x32_bf16 v[16:19], v[164:167], v[190:193], v[16:19]
	v_mfma_f32_16x16x32_bf16 v[4:7], v[156:159], v[198:201], v[4:7]
	v_mfma_f32_16x16x32_bf16 v[0:3], v[164:167], v[198:201], v[0:3]
	v_mfma_f32_16x16x32_bf16 v[52:55], v[160:163], v[176:179], v[52:55]
	v_mfma_f32_16x16x32_bf16 v[48:51], v[168:171], v[176:179], v[48:51]
	v_mfma_f32_16x16x32_bf16 v[36:39], v[160:163], v[186:189], v[36:39]
	v_mfma_f32_16x16x32_bf16 v[32:35], v[168:171], v[186:189], v[32:35]
	v_mfma_f32_16x16x32_bf16 v[20:23], v[160:163], v[194:197], v[20:23]
	v_mfma_f32_16x16x32_bf16 v[16:19], v[168:171], v[194:197], v[16:19]
	v_mfma_f32_16x16x32_bf16 v[4:7], v[160:163], v[202:205], v[4:7]
	v_mfma_f32_16x16x32_bf16 v[0:3], v[168:171], v[202:205], v[0:3]
	s_setprio 0
	s_add_i32 s58, s58, 2
	s_add_u32 s24, s24, 0x100
	s_addc_u32 s25, s25, 0
	s_add_u32 s56, s56, 0x100
	s_addc_u32 s57, s57, 0
	s_cmp_gt_u32 s58, 13
	s_barrier
	s_cbranch_scc0 .LBB0_716
; __device__ __forceinline__ unsigned cvt_pk_bf16(float lo, float hi) { unsigned r; asm volatile("v_cvt_pk_bf16_f32 %0, %1, %2" : "=v"(r) : "v"(lo), "v"(hi)); return r; }
;     __device__ __forceinline__ void operator()(const f32x4 (&acc)[2][2][4][2], const Unit& u, int wr, int wc, int fr, int fq) const {
;         const int row0 = u.pm * BM + wr * 64 + fr, col0 = u.pn * BM + wc * 32 + 4 * fq;
;         unsigned long long rb[2][4][2][2];
;         if (BB) {
; #pragma unroll
;             for (int ai = 0; ai < 2; ++ai)
; #pragma unroll
;                 for (int m = 0; m < 4; ++m)
; #pragma unroll
;                     for (int bj = 0; bj < 2; ++bj)
; #pragma unroll
;                         for (int n = 0; n < 2; ++n) rb[ai][m][bj][n] = *(const unsigned long long*)((const bf16_t*)base + (size_t)(row0 + ai * HALF + m * 16) * ldc + col0 + bj * HALF + n * 16);
;             asm volatile("" ::: "memory"); }
; #pragma unroll
;         for (int ai = 0; ai < 2; ++ai)
; #pragma unroll
;             for (int m = 0; m < 4; ++m) { const int row = row0 + ai * HALF + m * 16; const size_t off = (size_t)row * ldc + col0; float s = 0.f;
; #pragma unroll
;                 for (int bj = 0; bj < 2; ++bj)
; #pragma unroll
;                     for (int n = 0; n < 2; ++n) { f32x4 bs;
;                         if (BB) { const unsigned long long rw = rb[ai][m][bj][n]; const unsigned lo = (unsigned)rw, hi = (unsigned)(rw >> 32);
;                             bs = (f32x4){__uint_as_float(lo << 16), __uint_as_float(lo & 0xffff0000u), __uint_as_float(hi << 16), __uint_as_float(hi & 0xffff0000u)}; }
;                         else bs = *(const f32x4*)((const float*)base + off + bj * HALF + n * 16);
;                         const f32x4 v = bs + acc[ai][bj][m][n];
;                         if (WF) *(f32x4*)(out + off + bj * HALF + n * 16) = v;
;                         s += (v[0] * v[0] + v[1] * v[1]) + (v[2] * v[2] + v[3] * v[3]);
;                         if (WB) { unsigned lo = cvt_pk_bf16(v[0], v[1]), hi = cvt_pk_bf16(v[2], v[3]); *(unsigned long long*)(outb + off + bj * HALF + n * 16) = (unsigned long long)lo | ((unsigned long long)hi << 32); } }
;                 s += __shfl_xor(s, 16); s += __shfl_xor(s, 32);
;                 if (fq == 0) atomicAdd(ssq + row, s);
	v_lshl_add_u32 v212, s20, 8, v220
	v_lshl_or_b32 v140, s22, 8, v222
	v_ashrrev_i32_e32 v141, 31, v140
	v_ashrrev_i32_e32 v213, 31, v212
	v_lshl_add_u64 v[144:145], v[140:141], 1, s[6:7]
	v_lshlrev_b64 v[142:143], 11, v[212:213]
	v_lshl_add_u64 v[142:143], v[144:145], 0, v[142:143]
	global_load_dwordx2 v[228:229], v[142:143], off
	global_load_dwordx2 v[230:231], v[142:143], off offset:32
	global_load_dwordx2 v[234:235], v[142:143], off offset:256
	global_load_dwordx2 v[236:237], v[142:143], off offset:288
	v_or_b32_e32 v202, 16, v212
	v_ashrrev_i32_e32 v203, 31, v202
	v_lshlrev_b64 v[142:143], 11, v[202:203]
	v_or_b32_e32 v192, 32, v212
	v_lshl_add_u64 v[142:143], v[144:145], 0, v[142:143]
	v_ashrrev_i32_e32 v193, 31, v192
	global_load_dwordx2 v[214:215], v[142:143], off
	global_load_dwordx2 v[210:211], v[142:143], off offset:32
	global_load_dwordx2 v[208:209], v[142:143], off offset:256
	global_load_dwordx2 v[206:207], v[142:143], off offset:288
	v_lshlrev_b64 v[142:143], 11, v[192:193]
	v_or_b32_e32 v180, 48, v212
	v_lshl_add_u64 v[142:143], v[144:145], 0, v[142:143]
	v_ashrrev_i32_e32 v181, 31, v180
	global_load_dwordx2 v[204:205], v[142:143], off
	global_load_dwordx2 v[200:201], v[142:143], off offset:32
	global_load_dwordx2 v[198:199], v[142:143], off offset:256
	global_load_dwordx2 v[196:197], v[142:143], off offset:288
	v_lshlrev_b64 v[142:143], 11, v[180:181]
	v_add_u32_e32 v170, 0x80, v212
	v_lshl_add_u64 v[142:143], v[144:145], 0, v[142:143]
	v_ashrrev_i32_e32 v171, 31, v170
	global_load_dwordx2 v[194:195], v[142:143], off
	global_load_dwordx2 v[190:191], v[142:143], off offset:32
	global_load_dwordx2 v[188:189], v[142:143], off offset:256
	global_load_dwordx2 v[186:187], v[142:143], off offset:288
	v_lshlrev_b64 v[142:143], 11, v[170:171]
	v_add_u32_e32 v160, 0x90, v212
	v_lshl_add_u64 v[142:143], v[144:145], 0, v[142:143]
	v_ashrrev_i32_e32 v161, 31, v160
	global_load_dwordx2 v[182:183], v[142:143], off
	global_load_dwordx2 v[178:179], v[142:143], off offset:32
	global_load_dwordx2 v[176:177], v[142:143], off offset:256
	global_load_dwordx2 v[174:175], v[142:143], off offset:288
	v_lshlrev_b64 v[142:143], 11, v[160:161]
	v_add_u32_e32 v150, 0xa0, v212
	v_lshl_add_u64 v[142:143], v[144:145], 0, v[142:143]
	v_ashrrev_i32_e32 v151, 31, v150
	global_load_dwordx2 v[172:173], v[142:143], off
	global_load_dwordx2 v[168:169], v[142:143], off offset:32
	global_load_dwordx2 v[166:167], v[142:143], off offset:256
	global_load_dwordx2 v[164:165], v[142:143], off offset:288
	v_lshlrev_b64 v[142:143], 11, v[150:151]
	v_lshl_add_u64 v[142:143], v[144:145], 0, v[142:143]
	global_load_dwordx2 v[162:163], v[142:143], off
	global_load_dwordx2 v[158:159], v[142:143], off offset:32
	global_load_dwordx2 v[156:157], v[142:143], off offset:256
	global_load_dwordx2 v[154:155], v[142:143], off offset:288
	v_add_u32_e32 v142, 0xb0, v212
	v_ashrrev_i32_e32 v143, 31, v142
	v_lshlrev_b64 v[146:147], 11, v[142:143]
	v_lshl_add_u64 v[144:145], v[144:145], 0, v[146:147]
	global_load_dwordx2 v[152:153], v[144:145], off
	global_load_dwordx2 v[148:149], v[144:145], off offset:32
	global_load_dwordx2 v[146:147], v[144:145], off offset:256
	s_nop 0
	global_load_dwordx2 v[144:145], v[144:145], off offset:288
	v_and_b32_e32 v233, 64, v226
	v_xor_b32_e32 v227, 16, v226
	v_add_u32_e32 v233, 64, v233
	v_xor_b32_e32 v238, 32, v226
	v_cmp_lt_i32_e32 vcc, v227, v233
	s_waitcnt vmcnt(0)
	v_and_b32_e32 v239, 0xffff0000, v228
	v_cndmask_b32_e32 v227, v226, v227, vcc
	v_cmp_lt_i32_e32 vcc, v238, v233
	v_lshlrev_b32_e32 v240, 16, v230
	v_and_b32_e32 v241, 0xffff0000, v230
	v_cndmask_b32_e32 v233, v226, v238, vcc
	v_lshlrev_b32_e32 v238, 16, v228
	v_lshlrev_b32_e32 v228, 16, v229
	v_and_b32_e32 v229, 0xffff0000, v229
	v_pk_add_f32 v[126:127], v[126:127], v[228:229]
	v_pk_add_f32 v[124:125], v[124:125], v[238:239]
	v_mul_f32_e32 v229, v127, v127
	v_mul_f32_e32 v228, v125, v125
	v_fmac_f32_e32 v228, v124, v124
	v_fmac_f32_e32 v229, v126, v126
	v_add_f32_e32 v238, v228, v229
	v_lshlrev_b32_e32 v228, 16, v231
	v_and_b32_e32 v229, 0xffff0000, v231
	v_pk_add_f32 v[122:123], v[122:123], v[228:229]
	v_pk_add_f32 v[120:121], v[120:121], v[240:241]
	v_mul_f32_e32 v229, v123, v123
	v_mul_f32_e32 v228, v121, v121
	v_fmac_f32_e32 v228, v120, v120
	v_fmac_f32_e32 v229, v122, v122
	v_add_f32_e32 v228, v228, v229
	v_add_f32_e32 v238, v238, v228
	v_lshlrev_b32_e32 v228, 16, v234
	v_and_b32_e32 v229, 0xffff0000, v234
	v_lshlrev_b32_e32 v230, 16, v235
	v_and_b32_e32 v231, 0xffff0000, v235
	v_pk_add_f32 v[118:119], v[118:119], v[230:231]
	v_pk_add_f32 v[116:117], v[116:117], v[228:229]
	v_mul_f32_e32 v229, v119, v119
	v_mul_f32_e32 v228, v117, v117
	v_fmac_f32_e32 v228, v116, v116
	v_fmac_f32_e32 v229, v118, v118
	v_add_f32_e32 v228, v228, v229
	v_add_f32_e32 v234, v238, v228
	v_lshlrev_b32_e32 v228, 16, v236
	v_and_b32_e32 v229, 0xffff0000, v236
	v_lshlrev_b32_e32 v230, 16, v237
	v_and_b32_e32 v231, 0xffff0000, v237
	v_pk_add_f32 v[230:231], v[114:115], v[230:231]
	v_pk_add_f32 v[228:229], v[112:113], v[228:229]
	v_mul_f32_e32 v113, v231, v231
	v_mul_f32_e32 v112, v229, v229
	v_fmac_f32_e32 v112, v228, v228
	v_fmac_f32_e32 v113, v230, v230
	v_add_f32_e32 v112, v112, v113
	v_lshlrev_b32_e32 v227, 2, v227
	v_add_f32_e32 v113, v234, v112
	ds_bpermute_b32 v236, v227, v113
	v_lshlrev_b64 v[114:115], 12, v[212:213]
	v_lshlrev_b32_e32 v112, 2, v233
	v_lshl_add_u64 v[114:115], s[52:53], 0, v[114:115]
	v_lshl_add_u64 v[234:235], v[140:141], 2, v[114:115]
	s_waitcnt lgkmcnt(0)
	v_add_f32_e32 v113, v113, v236
	ds_bpermute_b32 v114, v112, v113
	global_store_dwordx4 v[234:235], v[124:127], off
	global_store_dwordx4 v[234:235], v[120:123], off offset:64
	global_store_dwordx4 v[234:235], v[116:119], off offset:512
	global_store_dwordx4 v[234:235], v[228:231], off offset:576
	s_and_saveexec_b64 s[20:21], s[2:3]
	s_cbranch_execz .LBB0_719
	v_lshl_add_u64 v[116:117], v[212:213], 2, s[8:9]
	s_waitcnt lgkmcnt(0)
	v_add_f32_e32 v113, v113, v114
	global_atomic_add_f32 v[116:117], v113, off

; #define PG8_STAGE(bufoff, gbase, voff) do { _Pragma("unroll") for (int _i = 0; _i < 2; ++_i) \
;         __builtin_amdgcn_global_load_lds((const unsigned*)((const char*)(gbase) + (voff)[_i]), (PG8_LAS unsigned*)(lds + (bufoff) + ldsw + _i * 8192), 16, 0, 0); } while (0)
; #define PG8_LDA(dst, b, h) do { _Pragma("unroll") for (int m = 0; m < 4; ++m) _Pragma("unroll") for (int k = 0; k < 2; ++k) dst[m][k] = *(const PG8_LAS bf16x8*)(lds + PG8_SA(b, h) + aoff + m * 2048 + k * 1024); } while (0)
; #define PG8_LDB(dst, b, h) do { _Pragma("unroll") for (int n = 0; n < 2; ++n) _Pragma("unroll") for (int k = 0; k < 2; ++k) dst[n][k] = *(const PG8_LAS bf16x8*)(lds + PG8_SB(b, h) + boff + n * 2048 + k * 1024); } while (0)
; #define PG8_MMA(ai, bj, At, Bt) do { __builtin_amdgcn_s_setprio(1); _Pragma("unroll") for (int m = 0; m < 4; ++m) _Pragma("unroll") for (int n = 0; n < 2; ++n) _Pragma("unroll") for (int k = 0; k < 2; ++k) \
;         acc[ai][bj][m][n] = __builtin_amdgcn_mfma_f32_16x16x32_bf16(Bt[n][k], At[m][k], acc[ai][bj][m][n], 0, 0, 0); __builtin_amdgcn_s_setprio(0); } while (0)
; #define PG8_WAIT_V(n) asm volatile("s_waitcnt vmcnt(" #n ")" ::: "memory")
; #define PG8_WAIT_L(n) asm volatile("s_waitcnt lgkmcnt(" #n ")" ::: "memory")
; #define PG8_BAR __builtin_amdgcn_s_barrier()
; #define PG8_SCHED __builtin_amdgcn_sched_barrier(0)
; template <class Epi, class Sched, bool ALIGN_EPI = false, bool SP2 = false>
; __device__ __forceinline__ void gemm_phase(PG8_LAS unsigned char* lds, const Gemm g, const Sched& S, const Epi& E) {
;     ...
;             const bool last = (t == nt - 2);
;             const char* a1 = cA + (size_t)(t + 1) * kstep;
;             const char* a2 = last ? nA : cA + (size_t)(t + 2) * kstep; const char* b2 = last ? nB : cB + (size_t)(t + 2) * kstep;
;             const char* a3 = a2 + kstep; const char* b3 = b2 + kstep;
;             if (last && has_next) S.a_ready(nxt);
;             if constexpr (SP2) {
;             PG8_LDB(B0, 0, 0); PG8_LDB(B1, 0, 1); PG8_SCHED; PG8_LDA(At, 0, 0); PG8_STAGE(PG8_SA(1, 1), a1 + hstep, voffA);
;             PG8_WAIT_V(8); PG8_WAIT_L(0); PG8_BAR; PG8_MMA(0, 0, At, B0); PG8_MMA(0, 1, At, B1); PG8_BAR; PG8_SCHED;
;             PG8_LDA(At, 0, 1); PG8_STAGE(PG8_SB(0, 0), b2, voffB); PG8_STAGE(PG8_SB(0, 1), b2 + hstep, voffB); PG8_STAGE(PG8_SA(0, 0), a2, voffA);
.LBB0_809:
	v_add_u32_e32 v147, s49, v145
	ds_read_b128 v[148:151], v147
	ds_read_b128 v[152:155], v147 offset:1024
	ds_read_b128 v[156:159], v147 offset:2048
	ds_read_b128 v[160:163], v147 offset:3072
	v_add_u32_e32 v147, s50, v145
	s_add_u32 s26, s10, s24
	ds_read_b128 v[164:167], v147
	ds_read_b128 v[168:171], v147 offset:1024
	ds_read_b128 v[172:175], v147 offset:2048
	ds_read_b128 v[176:179], v147 offset:3072
	s_addc_u32 s27, s11, s25
	s_add_u32 s26, s26, 0x100
	s_addc_u32 s27, s27, 0
	s_add_u32 s59, s21, s24
	s_addc_u32 s60, s51, s25
	s_cmpk_eq_i32 s24, 0x700
	s_cselect_b32 s29, s17, s27
	s_cselect_b32 s28, s56, s26
	s_cselect_b32 s27, s15, s60
	s_cselect_b32 s26, s57, s59
	v_lshl_add_u64 v[184:185], v[140:141], 0, s[24:25]
	s_add_i32 m0, s39, 0xc000
	ds_read_b128 v[180:183], v146
	ds_read_b128 v[188:191], v146 offset:1024
	ds_read_b128 v[192:195], v146 offset:2048
	ds_read_b128 v[196:199], v146 offset:3072
	ds_read_b128 v[200:203], v146 offset:4096
	ds_read_b128 v[204:207], v146 offset:5120
	ds_read_b128 v[208:211], v146 offset:6144
	ds_read_b128 v[212:215], v146 offset:7168
	global_load_lds_dwordx4 v[184:185], off
	v_lshl_add_u64 v[184:185], v[142:143], 0, s[24:25]
	s_add_i32 m0, s39, 0xe000
	s_nop 0
	global_load_lds_dwordx4 v[184:185], off
	s_waitcnt vmcnt(8)
	s_waitcnt lgkmcnt(0)
	s_barrier
	s_setprio 1
	s_waitcnt lgkmcnt(0)
	v_mfma_f32_16x16x32_bf16 v[124:127], v[148:151], v[180:183], v[124:127]
	v_mfma_f32_16x16x32_bf16 v[120:123], v[156:159], v[180:183], v[120:123]
	v_mfma_f32_16x16x32_bf16 v[108:111], v[148:151], v[192:195], v[108:111]
	v_mfma_f32_16x16x32_bf16 v[104:107], v[156:159], v[192:195], v[104:107]
	v_mfma_f32_16x16x32_bf16 v[92:95], v[148:151], v[200:203], v[92:95]
	v_mfma_f32_16x16x32_bf16 v[88:91], v[156:159], v[200:203], v[88:91]
	v_mfma_f32_16x16x32_bf16 v[76:79], v[148:151], v[208:211], v[76:79]
	v_mfma_f32_16x16x32_bf16 v[72:75], v[156:159], v[208:211], v[72:75]
	v_mfma_f32_16x16x32_bf16 v[124:127], v[152:155], v[188:191], v[124:127]
	v_mfma_f32_16x16x32_bf16 v[120:123], v[160:163], v[188:191], v[120:123]
	v_mfma_f32_16x16x32_bf16 v[108:111], v[152:155], v[196:199], v[108:111]
	v_mfma_f32_16x16x32_bf16 v[104:107], v[160:163], v[196:199], v[104:107]
	v_mfma_f32_16x16x32_bf16 v[92:95], v[152:155], v[204:207], v[92:95]
	v_mfma_f32_16x16x32_bf16 v[88:91], v[160:163], v[204:207], v[88:91]
	v_mfma_f32_16x16x32_bf16 v[76:79], v[152:155], v[212:215], v[76:79]
	v_mfma_f32_16x16x32_bf16 v[72:75], v[160:163], v[212:215], v[72:75]
	s_setprio 0
	s_setprio 1
	v_mfma_f32_16x16x32_bf16 v[116:119], v[164:167], v[180:183], v[116:119]
	v_mfma_f32_16x16x32_bf16 v[112:115], v[172:175], v[180:183], v[112:115]
	v_mfma_f32_16x16x32_bf16 v[100:103], v[164:167], v[192:195], v[100:103]
	v_mfma_f32_16x16x32_bf16 v[96:99], v[172:175], v[192:195], v[96:99]
	v_mfma_f32_16x16x32_bf16 v[84:87], v[164:167], v[200:203], v[84:87]
	v_mfma_f32_16x16x32_bf16 v[80:83], v[172:175], v[200:203], v[80:83]
	v_mfma_f32_16x16x32_bf16 v[68:71], v[164:167], v[208:211], v[68:71]
	v_mfma_f32_16x16x32_bf16 v[64:67], v[172:175], v[208:211], v[64:67]
	v_mfma_f32_16x16x32_bf16 v[116:119], v[168:171], v[188:191], v[116:119]
	v_mfma_f32_16x16x32_bf16 v[112:115], v[176:179], v[188:191], v[112:115]
	v_mfma_f32_16x16x32_bf16 v[100:103], v[168:171], v[196:199], v[100:103]
	v_mfma_f32_16x16x32_bf16 v[96:99], v[176:179], v[196:199], v[96:99]
	v_mfma_f32_16x16x32_bf16 v[84:87], v[168:171], v[204:207], v[84:87]
	v_mfma_f32_16x16x32_bf16 v[80:83], v[176:179], v[204:207], v[80:83]
	v_mfma_f32_16x16x32_bf16 v[68:71], v[168:171], v[212:215], v[68:71]
	v_mfma_f32_16x16x32_bf16 v[64:67], v[176:179], v[212:215], v[64:67]
	s_setprio 0
	s_barrier
	s_add_i32 s59, s49, s38
	v_lshl_add_u64 v[184:185], s[26:27], 0, v[128:129]
	s_mov_b32 m0, s59
	ds_read_b128 v[180:183], v146 offset:16384
	ds_read_b128 v[188:191], v146 offset:17408
	ds_read_b128 v[192:195], v146 offset:18432
	ds_read_b128 v[196:199], v146 offset:19456
	ds_read_b128 v[200:203], v146 offset:20480
	ds_read_b128 v[204:207], v146 offset:21504
	ds_read_b128 v[208:211], v146 offset:22528
	ds_read_b128 v[212:215], v146 offset:23552
	global_load_lds_dwordx4 v[184:185], off
	s_add_i32 m0, s59, 0x2000
	s_add_u32 s60, s26, 0x40000
	v_lshl_add_u64 v[218:219], s[26:27], 0, v[130:131]
	s_addc_u32 s61, s27, 0
	s_add_i32 s59, s50, s38
	global_load_lds_dwordx4 v[218:219], off
	v_lshl_add_u64 v[220:221], s[60:61], 0, v[128:129]
	s_mov_b32 m0, s59
	v_lshl_add_u64 v[222:223], s[28:29], 0, v[130:131]
	global_load_lds_dwordx4 v[220:221], off
	v_lshl_add_u64 v[220:221], s[60:61], 0, v[130:131]
	s_add_i32 m0, s59, 0x2000
	s_nop 0
	global_load_lds_dwordx4 v[220:221], off
	v_lshl_add_u64 v[220:221], s[28:29], 0, v[128:129]
	s_mov_b32 m0, s39
	s_nop 0
	global_load_lds_dwordx4 v[220:221], off
	s_mov_b32 m0, s42
	s_nop 0
	global_load_lds_dwordx4 v[222:223], off
	s_waitcnt vmcnt(8)
	s_waitcnt lgkmcnt(0)
	s_barrier
; #define PG8_STAGE(bufoff, gbase, voff) do { _Pragma("unroll") for (int _i = 0; _i < 2; ++_i) \
;         __builtin_amdgcn_global_load_lds((const unsigned*)((const char*)(gbase) + (voff)[_i]), (PG8_LAS unsigned*)(lds + (bufoff) + ldsw + _i * 8192), 16, 0, 0); } while (0)
; #define PG8_LDA(dst, b, h) do { _Pragma("unroll") for (int m = 0; m < 4; ++m) _Pragma("unroll") for (int k = 0; k < 2; ++k) dst[m][k] = *(const PG8_LAS bf16x8*)(lds + PG8_SA(b, h) + aoff + m * 2048 + k * 1024); } while (0)
; #define PG8_LDB(dst, b, h) do { _Pragma("unroll") for (int n = 0; n < 2; ++n) _Pragma("unroll") for (int k = 0; k < 2; ++k) dst[n][k] = *(const PG8_LAS bf16x8*)(lds + PG8_SB(b, h) + boff + n * 2048 + k * 1024); } while (0)
; #define PG8_MMA(ai, bj, At, Bt) do { __builtin_amdgcn_s_setprio(1); _Pragma("unroll") for (int m = 0; m < 4; ++m) _Pragma("unroll") for (int n = 0; n < 2; ++n) _Pragma("unroll") for (int k = 0; k < 2; ++k) \
;         acc[ai][bj][m][n] = __builtin_amdgcn_mfma_f32_16x16x32_bf16(Bt[n][k], At[m][k], acc[ai][bj][m][n], 0, 0, 0); __builtin_amdgcn_s_setprio(0); } while (0)
; #define PG8_WAIT_V(n) asm volatile("s_waitcnt vmcnt(" #n ")" ::: "memory")
; #define PG8_WAIT_L(n) asm volatile("s_waitcnt lgkmcnt(" #n ")" ::: "memory")
; #define PG8_BAR __builtin_amdgcn_s_barrier()
; #define PG8_SCHED __builtin_amdgcn_sched_barrier(0)
; template <class Epi, class Sched, bool ALIGN_EPI = false, bool SP2 = false>
; __device__ __forceinline__ void gemm_phase(PG8_LAS unsigned char* lds, const Gemm g, const Sched& S, const Epi& E) {
;     ...
;             PG8_WAIT_V(8); PG8_WAIT_L(0); PG8_BAR; PG8_MMA(1, 0, At, B0); PG8_MMA(1, 1, At, B1); PG8_BAR; PG8_SCHED;
;             PG8_LDB(B0, 1, 0); PG8_LDB(B1, 1, 1); PG8_SCHED; PG8_LDA(At, 1, 0); PG8_STAGE(PG8_SA(0, 1), a2 + hstep, voffA);
;             PG8_WAIT_V(8); PG8_WAIT_L(0); PG8_BAR; PG8_MMA(0, 0, At, B0); PG8_MMA(0, 1, At, B1); PG8_BAR; PG8_SCHED;
	s_setprio 1
	s_waitcnt lgkmcnt(0)
	v_mfma_f32_16x16x32_bf16 v[60:63], v[148:151], v[180:183], v[60:63]
	v_mfma_f32_16x16x32_bf16 v[56:59], v[156:159], v[180:183], v[56:59]
	v_mfma_f32_16x16x32_bf16 v[44:47], v[148:151], v[192:195], v[44:47]
	v_mfma_f32_16x16x32_bf16 v[40:43], v[156:159], v[192:195], v[40:43]
	v_mfma_f32_16x16x32_bf16 v[28:31], v[148:151], v[200:203], v[28:31]
	v_mfma_f32_16x16x32_bf16 v[24:27], v[156:159], v[200:203], v[24:27]
	v_mfma_f32_16x16x32_bf16 v[12:15], v[148:151], v[208:211], v[12:15]
	v_mfma_f32_16x16x32_bf16 v[8:11], v[156:159], v[208:211], v[8:11]
	v_mfma_f32_16x16x32_bf16 v[60:63], v[152:155], v[188:191], v[60:63]
	v_mfma_f32_16x16x32_bf16 v[56:59], v[160:163], v[188:191], v[56:59]
	v_mfma_f32_16x16x32_bf16 v[44:47], v[152:155], v[196:199], v[44:47]
	v_mfma_f32_16x16x32_bf16 v[40:43], v[160:163], v[196:199], v[40:43]
	v_mfma_f32_16x16x32_bf16 v[28:31], v[152:155], v[204:207], v[28:31]
	v_mfma_f32_16x16x32_bf16 v[24:27], v[160:163], v[204:207], v[24:27]
	v_mfma_f32_16x16x32_bf16 v[12:15], v[152:155], v[212:215], v[12:15]
	v_mfma_f32_16x16x32_bf16 v[8:11], v[160:163], v[212:215], v[8:11]
	s_setprio 0
	s_setprio 1
	v_mfma_f32_16x16x32_bf16 v[52:55], v[164:167], v[180:183], v[52:55]
	v_mfma_f32_16x16x32_bf16 v[48:51], v[172:175], v[180:183], v[48:51]
	v_mfma_f32_16x16x32_bf16 v[36:39], v[164:167], v[192:195], v[36:39]
	v_mfma_f32_16x16x32_bf16 v[32:35], v[172:175], v[192:195], v[32:35]
	v_mfma_f32_16x16x32_bf16 v[20:23], v[164:167], v[200:203], v[20:23]
	v_mfma_f32_16x16x32_bf16 v[16:19], v[172:175], v[200:203], v[16:19]
	v_mfma_f32_16x16x32_bf16 v[4:7], v[164:167], v[208:211], v[4:7]
	v_mfma_f32_16x16x32_bf16 v[0:3], v[172:175], v[208:211], v[0:3]
	v_mfma_f32_16x16x32_bf16 v[52:55], v[168:171], v[188:191], v[52:55]
	v_mfma_f32_16x16x32_bf16 v[48:51], v[176:179], v[188:191], v[48:51]
	v_mfma_f32_16x16x32_bf16 v[36:39], v[168:171], v[196:199], v[36:39]
	v_mfma_f32_16x16x32_bf16 v[32:35], v[176:179], v[196:199], v[32:35]
	v_mfma_f32_16x16x32_bf16 v[20:23], v[168:171], v[204:207], v[20:23]
	v_mfma_f32_16x16x32_bf16 v[16:19], v[176:179], v[204:207], v[16:19]
	v_mfma_f32_16x16x32_bf16 v[4:7], v[168:171], v[212:215], v[4:7]
	v_mfma_f32_16x16x32_bf16 v[0:3], v[176:179], v[212:215], v[0:3]
	s_setprio 0
	s_barrier
	s_add_i32 s59, 0, 0x18000
	v_add_u32_e32 v147, s59, v145
	s_add_i32 s60, 0, 0x1c000
	ds_read_b128 v[148:151], v147
	ds_read_b128 v[152:155], v147 offset:1024
	ds_read_b128 v[156:159], v147 offset:2048
	ds_read_b128 v[160:163], v147 offset:3072
	v_add_u32_e32 v147, s60, v145
	ds_read_b128 v[164:167], v147
	ds_read_b128 v[168:171], v147 offset:1024
	ds_read_b128 v[172:175], v147 offset:2048
	ds_read_b128 v[176:179], v147 offset:3072
	s_add_u32 s28, s28, 0x40000
	s_addc_u32 s29, s29, 0
	s_mov_b32 m0, s43
	v_lshl_add_u64 v[224:225], s[28:29], 0, v[128:129]
	ds_read_b128 v[180:183], v146 offset:32768
	ds_read_b128 v[188:191], v146 offset:33792
	ds_read_b128 v[192:195], v146 offset:34816
	ds_read_b128 v[196:199], v146 offset:35840
	ds_read_b128 v[200:203], v146 offset:36864
	ds_read_b128 v[204:207], v146 offset:37888
	ds_read_b128 v[208:211], v146 offset:38912
	ds_read_b128 v[212:215], v146 offset:39936
	global_load_lds_dwordx4 v[224:225], off
	v_lshl_add_u64 v[224:225], s[28:29], 0, v[130:131]
	s_mov_b32 m0, s44
	s_nop 0
	global_load_lds_dwordx4 v[224:225], off
	s_waitcnt vmcnt(8)
	s_waitcnt lgkmcnt(0)
	s_barrier
	s_setprio 1
	s_waitcnt lgkmcnt(0)
	v_mfma_f32_16x16x32_bf16 v[124:127], v[148:151], v[180:183], v[124:127]
	v_mfma_f32_16x16x32_bf16 v[120:123], v[156:159], v[180:183], v[120:123]
	v_mfma_f32_16x16x32_bf16 v[108:111], v[148:151], v[192:195], v[108:111]
	v_mfma_f32_16x16x32_bf16 v[104:107], v[156:159], v[192:195], v[104:107]
	v_mfma_f32_16x16x32_bf16 v[92:95], v[148:151], v[200:203], v[92:95]
	v_mfma_f32_16x16x32_bf16 v[88:91], v[156:159], v[200:203], v[88:91]
	v_mfma_f32_16x16x32_bf16 v[76:79], v[148:151], v[208:211], v[76:79]
	v_mfma_f32_16x16x32_bf16 v[72:75], v[156:159], v[208:211], v[72:75]
	v_mfma_f32_16x16x32_bf16 v[124:127], v[152:155], v[188:191], v[124:127]
	v_mfma_f32_16x16x32_bf16 v[120:123], v[160:163], v[188:191], v[120:123]
	v_mfma_f32_16x16x32_bf16 v[108:111], v[152:155], v[196:199], v[108:111]
	v_mfma_f32_16x16x32_bf16 v[104:107], v[160:163], v[196:199], v[104:107]
	v_mfma_f32_16x16x32_bf16 v[92:95], v[152:155], v[204:207], v[92:95]
	v_mfma_f32_16x16x32_bf16 v[88:91], v[160:163], v[204:207], v[88:91]
	v_mfma_f32_16x16x32_bf16 v[76:79], v[152:155], v[212:215], v[76:79]
	v_mfma_f32_16x16x32_bf16 v[72:75], v[160:163], v[212:215], v[72:75]
	s_setprio 0
	s_setprio 1
	v_mfma_f32_16x16x32_bf16 v[116:119], v[164:167], v[180:183], v[116:119]
	v_mfma_f32_16x16x32_bf16 v[112:115], v[172:175], v[180:183], v[112:115]
	v_mfma_f32_16x16x32_bf16 v[100:103], v[164:167], v[192:195], v[100:103]
	v_mfma_f32_16x16x32_bf16 v[96:99], v[172:175], v[192:195], v[96:99]
	v_mfma_f32_16x16x32_bf16 v[84:87], v[164:167], v[200:203], v[84:87]
	v_mfma_f32_16x16x32_bf16 v[80:83], v[172:175], v[200:203], v[80:83]
	v_mfma_f32_16x16x32_bf16 v[68:71], v[164:167], v[208:211], v[68:71]
	v_mfma_f32_16x16x32_bf16 v[64:67], v[172:175], v[208:211], v[64:67]
	v_mfma_f32_16x16x32_bf16 v[116:119], v[168:171], v[188:191], v[116:119]
	v_mfma_f32_16x16x32_bf16 v[112:115], v[176:179], v[188:191], v[112:115]
	v_mfma_f32_16x16x32_bf16 v[100:103], v[168:171], v[196:199], v[100:103]
	v_mfma_f32_16x16x32_bf16 v[96:99], v[176:179], v[196:199], v[96:99]
	v_mfma_f32_16x16x32_bf16 v[84:87], v[168:171], v[204:207], v[84:87]
	v_mfma_f32_16x16x32_bf16 v[80:83], v[176:179], v[204:207], v[80:83]
	v_mfma_f32_16x16x32_bf16 v[68:71], v[168:171], v[212:215], v[68:71]
	v_mfma_f32_16x16x32_bf16 v[64:67], v[176:179], v[212:215], v[64:67]
	s_setprio 0
	s_barrier
; #define PG8_STAGE(bufoff, gbase, voff) do { _Pragma("unroll") for (int _i = 0; _i < 2; ++_i) \
;         __builtin_amdgcn_global_load_lds((const unsigned*)((const char*)(gbase) + (voff)[_i]), (PG8_LAS unsigned*)(lds + (bufoff) + ldsw + _i * 8192), 16, 0, 0); } while (0)
; #define PG8_LDA(dst, b, h) do { _Pragma("unroll") for (int m = 0; m < 4; ++m) _Pragma("unroll") for (int k = 0; k < 2; ++k) dst[m][k] = *(const PG8_LAS bf16x8*)(lds + PG8_SA(b, h) + aoff + m * 2048 + k * 1024); } while (0)
; #define PG8_MMA(ai, bj, At, Bt) do { __builtin_amdgcn_s_setprio(1); _Pragma("unroll") for (int m = 0; m < 4; ++m) _Pragma("unroll") for (int n = 0; n < 2; ++n) _Pragma("unroll") for (int k = 0; k < 2; ++k) \
;         acc[ai][bj][m][n] = __builtin_amdgcn_mfma_f32_16x16x32_bf16(Bt[n][k], At[m][k], acc[ai][bj][m][n], 0, 0, 0); __builtin_amdgcn_s_setprio(0); } while (0)
; #define PG8_WAIT_V(n) asm volatile("s_waitcnt vmcnt(" #n ")" ::: "memory")
; #define PG8_WAIT_L(n) asm volatile("s_waitcnt lgkmcnt(" #n ")" ::: "memory")
; #define PG8_BAR __builtin_amdgcn_s_barrier()
; #define PG8_SCHED __builtin_amdgcn_sched_barrier(0)
; template <class Epi, class Sched, bool ALIGN_EPI = false, bool SP2 = false>
; __device__ __forceinline__ void gemm_phase(PG8_LAS unsigned char* lds, const Gemm g, const Sched& S, const Epi& E) {
;     ...
;             PG8_LDA(At, 1, 1); PG8_STAGE(PG8_SB(1, 0), b3, voffB); PG8_STAGE(PG8_SB(1, 1), b3 + hstep, voffB); PG8_STAGE(PG8_SA(1, 0), a3, voffA);
;             PG8_WAIT_V(8); PG8_WAIT_L(0); PG8_BAR; PG8_MMA(1, 0, At, B0); PG8_MMA(1, 1, At, B1); PG8_BAR; PG8_SCHED;
;     ...
;         if (!has_next) break;
; #pragma unroll
;         for (int a = 0; a < 2; ++a)
; #pragma unroll
;             for (int b = 0; b < 2; ++b)
; #pragma unroll
;                 for (int m = 0; m < 4; ++m)
; #pragma unroll
;                     for (int n = 0; n < 2; ++n) acc[a][b][m][n] = (f32x4){0.f, 0.f, 0.f, 0.f};
;         cur = nxt; cA = nA; cB = nB; ++ui;
	s_add_i32 s28, s59, s38
	v_lshl_add_u64 v[184:185], v[184:185], 0, s[12:13]
	s_mov_b32 m0, s28
	ds_read_b128 v[180:183], v146 offset:49152
	ds_read_b128 v[188:191], v146 offset:50176
	ds_read_b128 v[192:195], v146 offset:51200
	ds_read_b128 v[196:199], v146 offset:52224
	ds_read_b128 v[200:203], v146 offset:53248
	ds_read_b128 v[204:207], v146 offset:54272
	ds_read_b128 v[208:211], v146 offset:55296
	ds_read_b128 v[212:215], v146 offset:56320
	global_load_lds_dwordx4 v[184:185], off
	s_add_i32 m0, s28, 0x2000
	s_add_u32 s26, s26, 0x40080
	v_lshl_add_u64 v[184:185], v[218:219], 0, s[12:13]
	s_addc_u32 s27, s27, 0
	s_add_i32 s28, s60, s38
	global_load_lds_dwordx4 v[184:185], off
	v_lshl_add_u64 v[184:185], s[26:27], 0, v[128:129]
	s_mov_b32 m0, s28
	s_nop 0
	global_load_lds_dwordx4 v[184:185], off
	v_lshl_add_u64 v[184:185], s[26:27], 0, v[130:131]
	s_add_i32 m0, s28, 0x2000
	s_nop 0
	global_load_lds_dwordx4 v[184:185], off
	v_lshl_add_u64 v[184:185], v[220:221], 0, s[12:13]
	s_mov_b32 m0, s46
	s_nop 0
	global_load_lds_dwordx4 v[184:185], off
	v_lshl_add_u64 v[184:185], v[222:223], 0, s[12:13]
	s_mov_b32 m0, s47
	s_nop 0
	global_load_lds_dwordx4 v[184:185], off
	s_waitcnt vmcnt(8)
	s_waitcnt lgkmcnt(0)
	s_barrier
	s_setprio 1
	s_waitcnt lgkmcnt(0)
	v_mfma_f32_16x16x32_bf16 v[60:63], v[148:151], v[180:183], v[60:63]
	v_mfma_f32_16x16x32_bf16 v[56:59], v[156:159], v[180:183], v[56:59]
	v_mfma_f32_16x16x32_bf16 v[44:47], v[148:151], v[192:195], v[44:47]
	v_mfma_f32_16x16x32_bf16 v[40:43], v[156:159], v[192:195], v[40:43]
	v_mfma_f32_16x16x32_bf16 v[28:31], v[148:151], v[200:203], v[28:31]
	v_mfma_f32_16x16x32_bf16 v[24:27], v[156:159], v[200:203], v[24:27]
	v_mfma_f32_16x16x32_bf16 v[12:15], v[148:151], v[208:211], v[12:15]
	v_mfma_f32_16x16x32_bf16 v[8:11], v[156:159], v[208:211], v[8:11]
	v_mfma_f32_16x16x32_bf16 v[60:63], v[152:155], v[188:191], v[60:63]
	v_mfma_f32_16x16x32_bf16 v[56:59], v[160:163], v[188:191], v[56:59]
	v_mfma_f32_16x16x32_bf16 v[44:47], v[152:155], v[196:199], v[44:47]
	v_mfma_f32_16x16x32_bf16 v[40:43], v[160:163], v[196:199], v[40:43]
	v_mfma_f32_16x16x32_bf16 v[28:31], v[152:155], v[204:207], v[28:31]
	v_mfma_f32_16x16x32_bf16 v[24:27], v[160:163], v[204:207], v[24:27]
	v_mfma_f32_16x16x32_bf16 v[12:15], v[152:155], v[212:215], v[12:15]
	v_mfma_f32_16x16x32_bf16 v[8:11], v[160:163], v[212:215], v[8:11]
	s_setprio 0
	s_setprio 1
	v_mfma_f32_16x16x32_bf16 v[52:55], v[164:167], v[180:183], v[52:55]
	v_mfma_f32_16x16x32_bf16 v[48:51], v[172:175], v[180:183], v[48:51]
	v_mfma_f32_16x16x32_bf16 v[36:39], v[164:167], v[192:195], v[36:39]
	v_mfma_f32_16x16x32_bf16 v[32:35], v[172:175], v[192:195], v[32:35]
	v_mfma_f32_16x16x32_bf16 v[20:23], v[164:167], v[200:203], v[20:23]
	v_mfma_f32_16x16x32_bf16 v[16:19], v[172:175], v[200:203], v[16:19]
	v_mfma_f32_16x16x32_bf16 v[4:7], v[164:167], v[208:211], v[4:7]
	v_mfma_f32_16x16x32_bf16 v[0:3], v[172:175], v[208:211], v[0:3]
	v_mfma_f32_16x16x32_bf16 v[52:55], v[168:171], v[188:191], v[52:55]
	v_mfma_f32_16x16x32_bf16 v[48:51], v[176:179], v[188:191], v[48:51]
	v_mfma_f32_16x16x32_bf16 v[36:39], v[168:171], v[196:199], v[36:39]
	v_mfma_f32_16x16x32_bf16 v[32:35], v[176:179], v[196:199], v[32:35]
	v_mfma_f32_16x16x32_bf16 v[20:23], v[168:171], v[204:207], v[20:23]
	v_mfma_f32_16x16x32_bf16 v[16:19], v[176:179], v[204:207], v[16:19]
	v_mfma_f32_16x16x32_bf16 v[4:7], v[168:171], v[212:215], v[4:7]
	v_mfma_f32_16x16x32_bf16 v[0:3], v[176:179], v[212:215], v[0:3]
	s_setprio 0
	s_add_i32 s58, s58, 2
	s_add_u32 s24, s24, 0x100
	s_addc_u32 s25, s25, 0
	s_cmp_gt_u32 s58, 13
	s_barrier
	s_cbranch_scc0 .LBB0_809
	s_add_u32 s24, s21, 0xffffff00
	s_addc_u32 s25, s51, -1
	s_andn2_b64 vcc, exec, s[2:3]
	s_cbranch_vccnz .LBB0_812
	v_mov_b32_e32 v0, 0
	s_mov_b32 s4, s14
	s_mov_b32 s8, s16
	s_mov_b64 s[10:11], s[22:23]
	s_mov_b32 s48, s20
	v_mov_b32_e32 v1, v0
	v_mov_b32_e32 v2, v0
	v_mov_b32_e32 v3, v0
	v_mov_b32_e32 v4, v0
	v_mov_b32_e32 v5, v0
	v_mov_b32_e32 v6, v0
	v_mov_b32_e32 v7, v0
	v_mov_b32_e32 v16, v0
	v_mov_b32_e32 v17, v0
	v_mov_b32_e32 v18, v0
	v_mov_b32_e32 v19, v0
	v_mov_b32_e32 v20, v0
	v_mov_b32_e32 v21, v0
	v_mov_b32_e32 v22, v0
	v_mov_b32_e32 v23, v0
	v_mov_b32_e32 v32, v0
	v_mov_b32_e32 v33, v0
	v_mov_b32_e32 v34, v0
	v_mov_b32_e32 v35, v0
	v_mov_b32_e32 v36, v0
	v_mov_b32_e32 v37, v0
	v_mov_b32_e32 v38, v0
	v_mov_b32_e32 v39, v0
	v_mov_b32_e32 v48, v0
	v_mov_b32_e32 v49, v0
	v_mov_b32_e32 v50, v0
	v_mov_b32_e32 v51, v0
	v_mov_b32_e32 v52, v0
	v_mov_b32_e32 v53, v0
	v_mov_b32_e32 v54, v0
	v_mov_b32_e32 v55, v0
	v_mov_b32_e32 v8, v0
	v_mov_b32_e32 v9, v0
	v_mov_b32_e32 v10, v0
	v_mov_b32_e32 v11, v0
	v_mov_b32_e32 v12, v0
	v_mov_b32_e32 v13, v0
	v_mov_b32_e32 v14, v0
	v_mov_b32_e32 v15, v0
	v_mov_b32_e32 v24, v0
	v_mov_b32_e32 v25, v0
	v_mov_b32_e32 v26, v0
	v_mov_b32_e32 v27, v0
	v_mov_b32_e32 v28, v0
	v_mov_b32_e32 v29, v0
	v_mov_b32_e32 v30, v0
	v_mov_b32_e32 v31, v0
	v_mov_b32_e32 v40, v0
	v_mov_b32_e32 v41, v0
	v_mov_b32_e32 v42, v0
	v_mov_b32_e32 v43, v0
	v_mov_b32_e32 v44, v0
	v_mov_b32_e32 v45, v0
	v_mov_b32_e32 v46, v0
	v_mov_b32_e32 v47, v0
	v_mov_b32_e32 v56, v0
	v_mov_b32_e32 v57, v0
	v_mov_b32_e32 v58, v0
	v_mov_b32_e32 v59, v0
	v_mov_b32_e32 v60, v0
	v_mov_b32_e32 v61, v0
	v_mov_b32_e32 v62, v0
	v_mov_b32_e32 v63, v0
	v_mov_b32_e32 v64, v0
	v_mov_b32_e32 v65, v0
	v_mov_b32_e32 v66, v0
	v_mov_b32_e32 v67, v0
	v_mov_b32_e32 v68, v0
	v_mov_b32_e32 v69, v0
	v_mov_b32_e32 v70, v0
	v_mov_b32_e32 v71, v0
	v_mov_b32_e32 v80, v0
	v_mov_b32_e32 v81, v0
	v_mov_b32_e32 v82, v0
	v_mov_b32_e32 v83, v0
	v_mov_b32_e32 v84, v0
	v_mov_b32_e32 v85, v0
	v_mov_b32_e32 v86, v0
	v_mov_b32_e32 v87, v0
	v_mov_b32_e32 v96, v0
	v_mov_b32_e32 v97, v0
	v_mov_b32_e32 v98, v0
	v_mov_b32_e32 v99, v0
	v_mov_b32_e32 v100, v0
	v_mov_b32_e32 v101, v0
	v_mov_b32_e32 v102, v0
	v_mov_b32_e32 v103, v0
	v_mov_b32_e32 v112, v0
	v_mov_b32_e32 v113, v0
	v_mov_b32_e32 v114, v0
	v_mov_b32_e32 v115, v0
	v_mov_b32_e32 v116, v0
	v_mov_b32_e32 v117, v0
	v_mov_b32_e32 v118, v0
	v_mov_b32_e32 v119, v0
	v_mov_b32_e32 v72, v0
	v_mov_b32_e32 v73, v0
	v_mov_b32_e32 v74, v0
	v_mov_b32_e32 v75, v0
	v_mov_b32_e32 v76, v0
	v_mov_b32_e32 v77, v0
	v_mov_b32_e32 v78, v0
	v_mov_b32_e32 v79, v0
	v_mov_b32_e32 v88, v0
	v_mov_b32_e32 v89, v0
	v_mov_b32_e32 v90, v0
	v_mov_b32_e32 v91, v0
	v_mov_b32_e32 v92, v0
	v_mov_b32_e32 v93, v0
	v_mov_b32_e32 v94, v0
	v_mov_b32_e32 v95, v0
	v_mov_b32_e32 v104, v0
	v_mov_b32_e32 v105, v0
	v_mov_b32_e32 v106, v0
	v_mov_b32_e32 v107, v0
	v_mov_b32_e32 v108, v0
	v_mov_b32_e32 v109, v0
	v_mov_b32_e32 v110, v0
	v_mov_b32_e32 v111, v0
	v_mov_b32_e32 v120, v0
	v_mov_b32_e32 v121, v0
	v_mov_b32_e32 v122, v0
	v_mov_b32_e32 v123, v0
	v_mov_b32_e32 v124, v0
	v_mov_b32_e32 v125, v0
	v_mov_b32_e32 v126, v0
	v_mov_b32_e32 v127, v0
	s_andn2_b64 vcc, exec, s[0:1]
	s_cbranch_vccnz .LBB0_813
	s_branch .LBB0_814
